# all s_setprio removed (GEMM phase priority flips and the attention-A static priority)
# speedup vs baseline: 1.0057x; 1.0057x over previous
; #define PG8_STAGE(bufoff, gbase, voff) do { _Pragma("unroll") for (int _i = 0; _i < 2; ++_i) \
;         __builtin_amdgcn_global_load_lds((const unsigned*)((const char*)(gbase) + (voff)[_i]), (PG8_LAS unsigned*)(lds + (bufoff) + ldsw + _i * 8192), 16, 0, 0); } while (0)
; #define PG8_LDA(dst, b, h) do { _Pragma("unroll") for (int m = 0; m < 4; ++m) _Pragma("unroll") for (int k = 0; k < 2; ++k) dst[m][k] = *(const PG8_LAS bf16x8*)(lds + PG8_SA(b, h) + aoff + m * 2048 + k * 1024); } while (0)
; #define PG8_LDB(dst, b, h) do { _Pragma("unroll") for (int n = 0; n < 2; ++n) _Pragma("unroll") for (int k = 0; k < 2; ++k) dst[n][k] = *(const PG8_LAS bf16x8*)(lds + PG8_SB(b, h) + boff + n * 2048 + k * 1024); } while (0)
; #define PG8_WAIT_V(n) asm volatile("s_waitcnt vmcnt(" #n ")" ::: "memory")
; #define PG8_WAIT_L(n) asm volatile("s_waitcnt lgkmcnt(" #n ")" ::: "memory")
; #define PG8_BAR __builtin_amdgcn_s_barrier()
; #define PG8_SCHED __builtin_amdgcn_sched_barrier(0)
; template <class Epi, class Sched, bool ALIGN_EPI = false, bool SP2 = false>
; __device__ __forceinline__ void gemm_phase(PG8_LAS unsigned char* lds, const Gemm g, const Sched& S, const Epi& E) {
;     ...
;         const char* nA = has_next ? (const char*)g.A + (size_t)nxt.pm * tstepA : cA; const char* nB = has_next ? (const char*)g.Bt + (size_t)nxt.pn * tstepB : cB;
;         for (int t = 0; t < nt; t += 2) {
;             const bool last = (t == nt - 2);
;             const char* a1 = cA + (size_t)(t + 1) * kstep;
;             const char* a2 = last ? nA : cA + (size_t)(t + 2) * kstep; const char* b2 = last ? nB : cB + (size_t)(t + 2) * kstep;
;             const char* a3 = a2 + kstep; const char* b3 = b2 + kstep;
;             if (last && has_next) S.a_ready(nxt);
;             if constexpr (SP2) {
;             PG8_LDB(B0, 0, 0); PG8_LDB(B1, 0, 1); PG8_SCHED; PG8_LDA(At, 0, 0); PG8_STAGE(PG8_SA(1, 1), a1 + hstepA, voffA);
;             PG8_WAIT_V(8); PG8_WAIT_L(0); PG8_BAR; PG8_MMA(0, 0, At, B0); PG8_MMA(0, 1, At, B1); PG8_BAR; PG8_SCHED;
;             PG8_LDA(At, 0, 1); PG8_STAGE(PG8_SB(0, 0), b2, voffB); PG8_STAGE(PG8_SB(0, 1), b2 + hstepB, voffB); PG8_STAGE(PG8_SA(0, 0), a2, voffA);
;             PG8_WAIT_V(8); PG8_WAIT_L(0); PG8_BAR; PG8_MMA(1, 0, At, B0); PG8_MMA(1, 1, At, B1); PG8_BAR; PG8_SCHED;
.LBB0_135:
	s_add_u32 s22, s20, 0xfffc0080
	s_addc_u32 s23, s21, -1
	s_add_i32 s28, 0, 0x10000
	s_cmp_eq_u32 s53, 12
	s_cselect_b32 s25, s12, s23
	s_cselect_b32 s24, s14, s22
	v_add_u32_e32 v138, s28, v141
	s_cselect_b32 s23, s15, s45
	s_cselect_b32 s22, s38, s43
	s_add_i32 s29, 0, 0x14000
	ds_read_b128 v[144:147], v138
	ds_read_b128 v[148:151], v138 offset:1024
	ds_read_b128 v[152:155], v138 offset:2048
	ds_read_b128 v[156:159], v138 offset:3072
	v_add_u32_e32 v138, s29, v141
	ds_read_b128 v[160:163], v138
	ds_read_b128 v[164:167], v138 offset:1024
	ds_read_b128 v[168:171], v138 offset:2048
	ds_read_b128 v[172:175], v138 offset:3072
	v_lshl_add_u64 v[138:139], s[20:21], 0, v[134:135]
	s_add_i32 m0, s26, 0xc000
	ds_read_b128 v[176:179], v143
	ds_read_b128 v[180:183], v143 offset:1024
	ds_read_b128 v[184:187], v143 offset:2048
	ds_read_b128 v[188:191], v143 offset:3072
	ds_read_b128 v[192:195], v143 offset:4096
	ds_read_b128 v[196:199], v143 offset:5120
	ds_read_b128 v[200:203], v143 offset:6144
	ds_read_b128 v[204:207], v143 offset:7168
	global_load_lds_dwordx4 v[138:139], off
	v_lshl_add_u64 v[138:139], s[20:21], 0, v[136:137]
	s_add_i32 m0, s26, 0xe000
	s_nop 0
	global_load_lds_dwordx4 v[138:139], off
	s_waitcnt vmcnt(8)
	s_waitcnt lgkmcnt(0)
	s_barrier
	s_waitcnt lgkmcnt(0)
	v_mfma_f32_16x16x32_bf16 v[124:127], v[144:147], v[176:179], v[124:127]
	v_mfma_f32_16x16x32_bf16 v[120:123], v[152:155], v[176:179], v[120:123]
	v_mfma_f32_16x16x32_bf16 v[108:111], v[144:147], v[184:187], v[108:111]
	v_mfma_f32_16x16x32_bf16 v[104:107], v[152:155], v[184:187], v[104:107]
	v_mfma_f32_16x16x32_bf16 v[92:95], v[144:147], v[192:195], v[92:95]
	v_mfma_f32_16x16x32_bf16 v[88:91], v[152:155], v[192:195], v[88:91]
	v_mfma_f32_16x16x32_bf16 v[76:79], v[144:147], v[200:203], v[76:79]
	v_mfma_f32_16x16x32_bf16 v[72:75], v[152:155], v[200:203], v[72:75]
	v_mfma_f32_16x16x32_bf16 v[124:127], v[148:151], v[180:183], v[124:127]
	v_mfma_f32_16x16x32_bf16 v[120:123], v[156:159], v[180:183], v[120:123]
	v_mfma_f32_16x16x32_bf16 v[108:111], v[148:151], v[188:191], v[108:111]
	v_mfma_f32_16x16x32_bf16 v[104:107], v[156:159], v[188:191], v[104:107]
	v_mfma_f32_16x16x32_bf16 v[92:95], v[148:151], v[196:199], v[92:95]
	v_mfma_f32_16x16x32_bf16 v[88:91], v[156:159], v[196:199], v[88:91]
	v_mfma_f32_16x16x32_bf16 v[76:79], v[148:151], v[204:207], v[76:79]
	v_mfma_f32_16x16x32_bf16 v[72:75], v[156:159], v[204:207], v[72:75]
	v_mfma_f32_16x16x32_bf16 v[116:119], v[160:163], v[176:179], v[116:119]
	v_mfma_f32_16x16x32_bf16 v[112:115], v[168:171], v[176:179], v[112:115]
	v_mfma_f32_16x16x32_bf16 v[100:103], v[160:163], v[184:187], v[100:103]
	v_mfma_f32_16x16x32_bf16 v[96:99], v[168:171], v[184:187], v[96:99]
	v_mfma_f32_16x16x32_bf16 v[84:87], v[160:163], v[192:195], v[84:87]
	v_mfma_f32_16x16x32_bf16 v[80:83], v[168:171], v[192:195], v[80:83]
	v_mfma_f32_16x16x32_bf16 v[68:71], v[160:163], v[200:203], v[68:71]
	v_mfma_f32_16x16x32_bf16 v[64:67], v[168:171], v[200:203], v[64:67]
	v_mfma_f32_16x16x32_bf16 v[116:119], v[164:167], v[180:183], v[116:119]
	v_mfma_f32_16x16x32_bf16 v[112:115], v[172:175], v[180:183], v[112:115]
	v_mfma_f32_16x16x32_bf16 v[100:103], v[164:167], v[188:191], v[100:103]
	v_mfma_f32_16x16x32_bf16 v[96:99], v[172:175], v[188:191], v[96:99]
	v_mfma_f32_16x16x32_bf16 v[84:87], v[164:167], v[196:199], v[84:87]
	v_mfma_f32_16x16x32_bf16 v[80:83], v[172:175], v[196:199], v[80:83]
	v_mfma_f32_16x16x32_bf16 v[68:71], v[164:167], v[204:207], v[68:71]
	v_mfma_f32_16x16x32_bf16 v[64:67], v[172:175], v[204:207], v[64:67]
	s_barrier
	s_add_i32 s28, s28, s18
	v_lshl_add_u64 v[138:139], s[22:23], 0, v[208:209]
	s_mov_b32 m0, s28
	ds_read_b128 v[176:179], v143 offset:16384
	ds_read_b128 v[180:183], v143 offset:17408
	ds_read_b128 v[184:187], v143 offset:18432
	ds_read_b128 v[188:191], v143 offset:19456
	ds_read_b128 v[192:195], v143 offset:20480
	ds_read_b128 v[196:199], v143 offset:21504
	ds_read_b128 v[200:203], v143 offset:22528
	ds_read_b128 v[204:207], v143 offset:23552
	global_load_lds_dwordx4 v[138:139], off
	s_add_i32 m0, s28, 0x2000
	s_add_u32 s54, s22, 0x40000
	v_lshl_add_u64 v[210:211], s[22:23], 0, v[128:129]
	s_addc_u32 s55, s23, 0
	s_add_i32 s28, s29, s18
	global_load_lds_dwordx4 v[210:211], off
	v_lshl_add_u64 v[212:213], s[54:55], 0, v[208:209]
	s_mov_b32 m0, s28
	v_lshl_add_u64 v[222:223], s[24:25], 0, v[130:131]
	global_load_lds_dwordx4 v[212:213], off
	v_lshl_add_u64 v[212:213], s[54:55], 0, v[128:129]
	s_add_i32 m0, s28, 0x2000
	s_nop 0
	global_load_lds_dwordx4 v[212:213], off
	v_lshl_add_u64 v[212:213], s[24:25], 0, v[132:133]
	s_mov_b32 m0, s26
	s_nop 0
	global_load_lds_dwordx4 v[212:213], off
	s_mov_b32 m0, s34
	s_nop 0
	global_load_lds_dwordx4 v[222:223], off
	s_waitcnt vmcnt(8)
	s_waitcnt lgkmcnt(0)
	s_barrier
; #define PG8_STAGE(bufoff, gbase, voff) do { _Pragma("unroll") for (int _i = 0; _i < 2; ++_i) \
;         __builtin_amdgcn_global_load_lds((const unsigned*)((const char*)(gbase) + (voff)[_i]), (PG8_LAS unsigned*)(lds + (bufoff) + ldsw + _i * 8192), 16, 0, 0); } while (0)
; #define PG8_LDA(dst, b, h) do { _Pragma("unroll") for (int m = 0; m < 4; ++m) _Pragma("unroll") for (int k = 0; k < 2; ++k) dst[m][k] = *(const PG8_LAS bf16x8*)(lds + PG8_SA(b, h) + aoff + m * 2048 + k * 1024); } while (0)
; #define PG8_LDB(dst, b, h) do { _Pragma("unroll") for (int n = 0; n < 2; ++n) _Pragma("unroll") for (int k = 0; k < 2; ++k) dst[n][k] = *(const PG8_LAS bf16x8*)(lds + PG8_SB(b, h) + boff + n * 2048 + k * 1024); } while (0)
; #define PG8_MMA(ai, bj, At, Bt) do { __builtin_amdgcn_s_setprio(1); _Pragma("unroll") for (int m = 0; m < 4; ++m) _Pragma("unroll") for (int n = 0; n < 2; ++n) _Pragma("unroll") for (int k = 0; k < 2; ++k) \
;         acc[ai][bj][m][n] = __builtin_amdgcn_mfma_f32_16x16x32_bf16(Bt[n][k], At[m][k], acc[ai][bj][m][n], 0, 0, 0); __builtin_amdgcn_s_setprio(0); } while (0)
; #define PG8_WAIT_V(n) asm volatile("s_waitcnt vmcnt(" #n ")" ::: "memory")
; #define PG8_WAIT_L(n) asm volatile("s_waitcnt lgkmcnt(" #n ")" ::: "memory")
; #define PG8_BAR __builtin_amdgcn_s_barrier()
; #define PG8_SCHED __builtin_amdgcn_sched_barrier(0)
; template <class Epi, class Sched, bool ALIGN_EPI = false, bool SP2 = false>
; __device__ __forceinline__ void gemm_phase(PG8_LAS unsigned char* lds, const Gemm g, const Sched& S, const Epi& E) {
;     ...
;             PG8_WAIT_V(8); PG8_WAIT_L(0); PG8_BAR; PG8_MMA(1, 0, At, B0); PG8_MMA(1, 1, At, B1); PG8_BAR; PG8_SCHED;
;             PG8_LDB(B0, 1, 0); PG8_LDB(B1, 1, 1); PG8_SCHED; PG8_LDA(At, 1, 0); PG8_STAGE(PG8_SA(0, 1), a2 + hstepA, voffA);
;             PG8_WAIT_V(8); PG8_WAIT_L(0); PG8_BAR; PG8_MMA(0, 0, At, B0); PG8_MMA(0, 1, At, B1); PG8_BAR; PG8_SCHED;
	s_waitcnt lgkmcnt(0)
	v_mfma_f32_16x16x32_bf16 v[60:63], v[144:147], v[176:179], v[60:63]
	v_mfma_f32_16x16x32_bf16 v[56:59], v[152:155], v[176:179], v[56:59]
	v_mfma_f32_16x16x32_bf16 v[44:47], v[144:147], v[184:187], v[44:47]
	v_mfma_f32_16x16x32_bf16 v[40:43], v[152:155], v[184:187], v[40:43]
	v_mfma_f32_16x16x32_bf16 v[28:31], v[144:147], v[192:195], v[28:31]
	v_mfma_f32_16x16x32_bf16 v[24:27], v[152:155], v[192:195], v[24:27]
	v_mfma_f32_16x16x32_bf16 v[12:15], v[144:147], v[200:203], v[12:15]
	v_mfma_f32_16x16x32_bf16 v[8:11], v[152:155], v[200:203], v[8:11]
	v_mfma_f32_16x16x32_bf16 v[60:63], v[148:151], v[180:183], v[60:63]
	v_mfma_f32_16x16x32_bf16 v[56:59], v[156:159], v[180:183], v[56:59]
	v_mfma_f32_16x16x32_bf16 v[44:47], v[148:151], v[188:191], v[44:47]
	v_mfma_f32_16x16x32_bf16 v[40:43], v[156:159], v[188:191], v[40:43]
	v_mfma_f32_16x16x32_bf16 v[28:31], v[148:151], v[196:199], v[28:31]
	v_mfma_f32_16x16x32_bf16 v[24:27], v[156:159], v[196:199], v[24:27]
	v_mfma_f32_16x16x32_bf16 v[12:15], v[148:151], v[204:207], v[12:15]
	v_mfma_f32_16x16x32_bf16 v[8:11], v[156:159], v[204:207], v[8:11]
	v_mfma_f32_16x16x32_bf16 v[52:55], v[160:163], v[176:179], v[52:55]
	v_mfma_f32_16x16x32_bf16 v[48:51], v[168:171], v[176:179], v[48:51]
	v_mfma_f32_16x16x32_bf16 v[36:39], v[160:163], v[184:187], v[36:39]
	v_mfma_f32_16x16x32_bf16 v[32:35], v[168:171], v[184:187], v[32:35]
	v_mfma_f32_16x16x32_bf16 v[20:23], v[160:163], v[192:195], v[20:23]
	v_mfma_f32_16x16x32_bf16 v[16:19], v[168:171], v[192:195], v[16:19]
	v_mfma_f32_16x16x32_bf16 v[4:7], v[160:163], v[200:203], v[4:7]
	v_mfma_f32_16x16x32_bf16 v[0:3], v[168:171], v[200:203], v[0:3]
	v_mfma_f32_16x16x32_bf16 v[52:55], v[164:167], v[180:183], v[52:55]
	v_mfma_f32_16x16x32_bf16 v[48:51], v[172:175], v[180:183], v[48:51]
	v_mfma_f32_16x16x32_bf16 v[36:39], v[164:167], v[188:191], v[36:39]
	v_mfma_f32_16x16x32_bf16 v[32:35], v[172:175], v[188:191], v[32:35]
	v_mfma_f32_16x16x32_bf16 v[20:23], v[164:167], v[196:199], v[20:23]
	v_mfma_f32_16x16x32_bf16 v[16:19], v[172:175], v[196:199], v[16:19]
	v_mfma_f32_16x16x32_bf16 v[4:7], v[164:167], v[204:207], v[4:7]
	v_mfma_f32_16x16x32_bf16 v[0:3], v[172:175], v[204:207], v[0:3]
	s_barrier
	s_add_i32 s28, 0, 0x18000
	s_add_i32 s29, 0, 0x1c000
	v_add_u32_e32 v156, s28, v141
	v_add_u32_e32 v172, s29, v141
	ds_read_b128 v[144:147], v156
	ds_read_b128 v[148:151], v156 offset:1024
	ds_read_b128 v[152:155], v156 offset:2048
	ds_read_b128 v[156:159], v156 offset:3072
	ds_read_b128 v[160:163], v172
	ds_read_b128 v[164:167], v172 offset:1024
	ds_read_b128 v[168:171], v172 offset:2048
	ds_read_b128 v[172:175], v172 offset:3072
	s_add_u32 s24, s24, 0x40000
	s_addc_u32 s25, s25, 0
	s_mov_b32 m0, s35
	v_lshl_add_u64 v[224:225], s[24:25], 0, v[132:133]
	ds_read_b128 v[176:179], v143 offset:32768
	ds_read_b128 v[180:183], v143 offset:33792
	ds_read_b128 v[184:187], v143 offset:34816
	ds_read_b128 v[188:191], v143 offset:35840
	ds_read_b128 v[192:195], v143 offset:36864
	ds_read_b128 v[196:199], v143 offset:37888
	ds_read_b128 v[200:203], v143 offset:38912
	ds_read_b128 v[204:207], v143 offset:39936
	global_load_lds_dwordx4 v[224:225], off
	v_lshl_add_u64 v[224:225], s[24:25], 0, v[130:131]
	s_mov_b32 m0, s39
	s_nop 0
	global_load_lds_dwordx4 v[224:225], off
	s_waitcnt vmcnt(8)
	s_waitcnt lgkmcnt(0)
	s_barrier
	s_waitcnt lgkmcnt(0)
	v_mfma_f32_16x16x32_bf16 v[124:127], v[144:147], v[176:179], v[124:127]
	v_mfma_f32_16x16x32_bf16 v[120:123], v[152:155], v[176:179], v[120:123]
	v_mfma_f32_16x16x32_bf16 v[108:111], v[144:147], v[184:187], v[108:111]
	v_mfma_f32_16x16x32_bf16 v[104:107], v[152:155], v[184:187], v[104:107]
	v_mfma_f32_16x16x32_bf16 v[92:95], v[144:147], v[192:195], v[92:95]
	v_mfma_f32_16x16x32_bf16 v[88:91], v[152:155], v[192:195], v[88:91]
	v_mfma_f32_16x16x32_bf16 v[76:79], v[144:147], v[200:203], v[76:79]
	v_mfma_f32_16x16x32_bf16 v[72:75], v[152:155], v[200:203], v[72:75]
	v_mfma_f32_16x16x32_bf16 v[124:127], v[148:151], v[180:183], v[124:127]
	v_mfma_f32_16x16x32_bf16 v[120:123], v[156:159], v[180:183], v[120:123]
	v_mfma_f32_16x16x32_bf16 v[108:111], v[148:151], v[188:191], v[108:111]
	v_mfma_f32_16x16x32_bf16 v[104:107], v[156:159], v[188:191], v[104:107]
	v_mfma_f32_16x16x32_bf16 v[92:95], v[148:151], v[196:199], v[92:95]
	v_mfma_f32_16x16x32_bf16 v[88:91], v[156:159], v[196:199], v[88:91]
	v_mfma_f32_16x16x32_bf16 v[76:79], v[148:151], v[204:207], v[76:79]
	v_mfma_f32_16x16x32_bf16 v[72:75], v[156:159], v[204:207], v[72:75]
	v_mfma_f32_16x16x32_bf16 v[116:119], v[160:163], v[176:179], v[116:119]
	v_mfma_f32_16x16x32_bf16 v[112:115], v[168:171], v[176:179], v[112:115]
	v_mfma_f32_16x16x32_bf16 v[100:103], v[160:163], v[184:187], v[100:103]
	v_mfma_f32_16x16x32_bf16 v[96:99], v[168:171], v[184:187], v[96:99]
	v_mfma_f32_16x16x32_bf16 v[84:87], v[160:163], v[192:195], v[84:87]
	v_mfma_f32_16x16x32_bf16 v[80:83], v[168:171], v[192:195], v[80:83]
	v_mfma_f32_16x16x32_bf16 v[68:71], v[160:163], v[200:203], v[68:71]
	v_mfma_f32_16x16x32_bf16 v[64:67], v[168:171], v[200:203], v[64:67]
	v_mfma_f32_16x16x32_bf16 v[116:119], v[164:167], v[180:183], v[116:119]
	v_mfma_f32_16x16x32_bf16 v[112:115], v[172:175], v[180:183], v[112:115]
	v_mfma_f32_16x16x32_bf16 v[100:103], v[164:167], v[188:191], v[100:103]
	v_mfma_f32_16x16x32_bf16 v[96:99], v[172:175], v[188:191], v[96:99]
	v_mfma_f32_16x16x32_bf16 v[84:87], v[164:167], v[196:199], v[84:87]
	v_mfma_f32_16x16x32_bf16 v[80:83], v[172:175], v[196:199], v[80:83]
	v_mfma_f32_16x16x32_bf16 v[68:71], v[164:167], v[204:207], v[68:71]
	v_mfma_f32_16x16x32_bf16 v[64:67], v[172:175], v[204:207], v[64:67]
	s_barrier
; #define PG8_STAGE(bufoff, gbase, voff) do { _Pragma("unroll") for (int _i = 0; _i < 2; ++_i) \
;         __builtin_amdgcn_global_load_lds((const unsigned*)((const char*)(gbase) + (voff)[_i]), (PG8_LAS unsigned*)(lds + (bufoff) + ldsw + _i * 8192), 16, 0, 0); } while (0)
; #define PG8_LDA(dst, b, h) do { _Pragma("unroll") for (int m = 0; m < 4; ++m) _Pragma("unroll") for (int k = 0; k < 2; ++k) dst[m][k] = *(const PG8_LAS bf16x8*)(lds + PG8_SA(b, h) + aoff + m * 2048 + k * 1024); } while (0)
; #define PG8_MMA(ai, bj, At, Bt) do { __builtin_amdgcn_s_setprio(1); _Pragma("unroll") for (int m = 0; m < 4; ++m) _Pragma("unroll") for (int n = 0; n < 2; ++n) _Pragma("unroll") for (int k = 0; k < 2; ++k) \
;         acc[ai][bj][m][n] = __builtin_amdgcn_mfma_f32_16x16x32_bf16(Bt[n][k], At[m][k], acc[ai][bj][m][n], 0, 0, 0); __builtin_amdgcn_s_setprio(0); } while (0)
; #define PG8_WAIT_V(n) asm volatile("s_waitcnt vmcnt(" #n ")" ::: "memory")
; #define PG8_WAIT_L(n) asm volatile("s_waitcnt lgkmcnt(" #n ")" ::: "memory")
; #define PG8_BAR __builtin_amdgcn_s_barrier()
; #define PG8_SCHED __builtin_amdgcn_sched_barrier(0)
; template <class Epi, class Sched, bool ALIGN_EPI = false, bool SP2 = false>
; __device__ __forceinline__ void gemm_phase(PG8_LAS unsigned char* lds, const Gemm g, const Sched& S, const Epi& E) {
;     ...
;         for (int t = 0; t < nt; t += 2) {
;             const bool last = (t == nt - 2);
;     ...
;             PG8_LDA(At, 1, 1); PG8_STAGE(PG8_SB(1, 0), b3, voffB); PG8_STAGE(PG8_SB(1, 1), b3 + hstepB, voffB); PG8_STAGE(PG8_SA(1, 0), a3, voffA);
;             PG8_WAIT_V(8); PG8_WAIT_L(0); PG8_BAR; PG8_MMA(1, 0, At, B0); PG8_MMA(1, 1, At, B1); PG8_BAR; PG8_SCHED;
	s_add_i32 s24, s28, s18
	v_lshl_add_u64 v[138:139], v[138:139], 0, s[10:11]
	s_mov_b32 m0, s24
	ds_read_b128 v[176:179], v143 offset:49152
	ds_read_b128 v[180:183], v143 offset:50176
	ds_read_b128 v[184:187], v143 offset:51200
	ds_read_b128 v[188:191], v143 offset:52224
	ds_read_b128 v[192:195], v143 offset:53248
	ds_read_b128 v[196:199], v143 offset:54272
	ds_read_b128 v[200:203], v143 offset:55296
	ds_read_b128 v[204:207], v143 offset:56320
	global_load_lds_dwordx4 v[138:139], off
	s_add_i32 m0, s24, 0x2000
	s_add_u32 s22, s22, 0x40080
	v_lshl_add_u64 v[138:139], v[210:211], 0, s[10:11]
	s_addc_u32 s23, s23, 0
	s_add_i32 s24, s29, s18
	global_load_lds_dwordx4 v[138:139], off
	v_lshl_add_u64 v[138:139], s[22:23], 0, v[208:209]
	s_mov_b32 m0, s24
	s_nop 0
	global_load_lds_dwordx4 v[138:139], off
	v_lshl_add_u64 v[138:139], s[22:23], 0, v[128:129]
	s_add_i32 m0, s24, 0x2000
	s_nop 0
	global_load_lds_dwordx4 v[138:139], off
	v_lshl_add_u64 v[138:139], v[212:213], 0, s[10:11]
	s_mov_b32 m0, s50
	s_nop 0
	global_load_lds_dwordx4 v[138:139], off
	v_lshl_add_u64 v[138:139], v[222:223], 0, s[10:11]
	s_mov_b32 m0, s51
	s_nop 0
	global_load_lds_dwordx4 v[138:139], off
	s_waitcnt vmcnt(8)
	s_waitcnt lgkmcnt(0)
	s_barrier
	s_waitcnt lgkmcnt(0)
	v_mfma_f32_16x16x32_bf16 v[60:63], v[144:147], v[176:179], v[60:63]
	v_mfma_f32_16x16x32_bf16 v[56:59], v[152:155], v[176:179], v[56:59]
	v_mfma_f32_16x16x32_bf16 v[44:47], v[144:147], v[184:187], v[44:47]
	v_mfma_f32_16x16x32_bf16 v[40:43], v[152:155], v[184:187], v[40:43]
	v_mfma_f32_16x16x32_bf16 v[28:31], v[144:147], v[192:195], v[28:31]
	v_mfma_f32_16x16x32_bf16 v[24:27], v[152:155], v[192:195], v[24:27]
	v_mfma_f32_16x16x32_bf16 v[12:15], v[144:147], v[200:203], v[12:15]
	v_mfma_f32_16x16x32_bf16 v[8:11], v[152:155], v[200:203], v[8:11]
	v_mfma_f32_16x16x32_bf16 v[60:63], v[148:151], v[180:183], v[60:63]
	v_mfma_f32_16x16x32_bf16 v[56:59], v[156:159], v[180:183], v[56:59]
	v_mfma_f32_16x16x32_bf16 v[44:47], v[148:151], v[188:191], v[44:47]
	v_mfma_f32_16x16x32_bf16 v[40:43], v[156:159], v[188:191], v[40:43]
	v_mfma_f32_16x16x32_bf16 v[28:31], v[148:151], v[196:199], v[28:31]
	v_mfma_f32_16x16x32_bf16 v[24:27], v[156:159], v[196:199], v[24:27]
	v_mfma_f32_16x16x32_bf16 v[12:15], v[148:151], v[204:207], v[12:15]
	v_mfma_f32_16x16x32_bf16 v[8:11], v[156:159], v[204:207], v[8:11]
	v_mfma_f32_16x16x32_bf16 v[52:55], v[160:163], v[176:179], v[52:55]
	v_mfma_f32_16x16x32_bf16 v[48:51], v[168:171], v[176:179], v[48:51]
	v_mfma_f32_16x16x32_bf16 v[36:39], v[160:163], v[184:187], v[36:39]
	v_mfma_f32_16x16x32_bf16 v[32:35], v[168:171], v[184:187], v[32:35]
	v_mfma_f32_16x16x32_bf16 v[20:23], v[160:163], v[192:195], v[20:23]
	v_mfma_f32_16x16x32_bf16 v[16:19], v[168:171], v[192:195], v[16:19]
	v_mfma_f32_16x16x32_bf16 v[4:7], v[160:163], v[200:203], v[4:7]
	v_mfma_f32_16x16x32_bf16 v[0:3], v[168:171], v[200:203], v[0:3]
	v_mfma_f32_16x16x32_bf16 v[52:55], v[164:167], v[180:183], v[52:55]
	v_mfma_f32_16x16x32_bf16 v[48:51], v[172:175], v[180:183], v[48:51]
	v_mfma_f32_16x16x32_bf16 v[36:39], v[164:167], v[188:191], v[36:39]
	v_mfma_f32_16x16x32_bf16 v[32:35], v[172:175], v[188:191], v[32:35]
	v_mfma_f32_16x16x32_bf16 v[20:23], v[164:167], v[196:199], v[20:23]
	v_mfma_f32_16x16x32_bf16 v[16:19], v[172:175], v[196:199], v[16:19]
	v_mfma_f32_16x16x32_bf16 v[4:7], v[164:167], v[204:207], v[4:7]
	v_mfma_f32_16x16x32_bf16 v[0:3], v[172:175], v[204:207], v[0:3]
	s_barrier
	s_add_i32 s53, s53, 2
	s_add_u32 s20, s20, 0x100
	s_addc_u32 s21, s21, 0
	s_add_u32 s43, s43, 0x100
	s_addc_u32 s45, s45, 0
	s_cmp_gt_u32 s53, 13
	s_cbranch_scc0 .LBB0_135
	s_and_b64 vcc, exec, s[6:7]
	s_cbranch_vccz .LBB0_138
	s_barrier

; #define PG8_STAGE(bufoff, gbase, voff) do { _Pragma("unroll") for (int _i = 0; _i < 2; ++_i) \
;         __builtin_amdgcn_global_load_lds((const unsigned*)((const char*)(gbase) + (voff)[_i]), (PG8_LAS unsigned*)(lds + (bufoff) + ldsw + _i * 8192), 16, 0, 0); } while (0)
; #define PG8_LDA(dst, b, h) do { _Pragma("unroll") for (int m = 0; m < 4; ++m) _Pragma("unroll") for (int k = 0; k < 2; ++k) dst[m][k] = *(const PG8_LAS bf16x8*)(lds + PG8_SA(b, h) + aoff + m * 2048 + k * 1024); } while (0)
; #define PG8_LDB(dst, b, h) do { _Pragma("unroll") for (int n = 0; n < 2; ++n) _Pragma("unroll") for (int k = 0; k < 2; ++k) dst[n][k] = *(const PG8_LAS bf16x8*)(lds + PG8_SB(b, h) + boff + n * 2048 + k * 1024); } while (0)
; #define PG8_WAIT_V(n) asm volatile("s_waitcnt vmcnt(" #n ")" ::: "memory")
; #define PG8_WAIT_L(n) asm volatile("s_waitcnt lgkmcnt(" #n ")" ::: "memory")
; #define PG8_BAR __builtin_amdgcn_s_barrier()
; #define PG8_SCHED __builtin_amdgcn_sched_barrier(0)
; template <class Epi, class Sched, bool ALIGN_EPI = false, bool SP2 = false>
; __device__ __forceinline__ void gemm_phase(PG8_LAS unsigned char* lds, const Gemm g, const Sched& S, const Epi& E) {
;     ...
;         const char* nA = has_next ? (const char*)g.A + (size_t)nxt.pm * tstepA : cA; const char* nB = has_next ? (const char*)g.Bt + (size_t)nxt.pn * tstepB : cB;
;         for (int t = 0; t < nt; t += 2) {
;             const bool last = (t == nt - 2);
;             const char* a1 = cA + (size_t)(t + 1) * kstep;
;             const char* a2 = last ? nA : cA + (size_t)(t + 2) * kstep; const char* b2 = last ? nB : cB + (size_t)(t + 2) * kstep;
;             const char* a3 = a2 + kstep; const char* b3 = b2 + kstep;
;             if (last && has_next) S.a_ready(nxt);
;             if constexpr (SP2) {
;             PG8_LDB(B0, 0, 0); PG8_LDB(B1, 0, 1); PG8_SCHED; PG8_LDA(At, 0, 0); PG8_STAGE(PG8_SA(1, 1), a1 + hstepA, voffA);
;             PG8_WAIT_V(8); PG8_WAIT_L(0); PG8_BAR; PG8_MMA(0, 0, At, B0); PG8_MMA(0, 1, At, B1); PG8_BAR; PG8_SCHED;
;             PG8_LDA(At, 0, 1); PG8_STAGE(PG8_SB(0, 0), b2, voffB); PG8_STAGE(PG8_SB(0, 1), b2 + hstepB, voffB); PG8_STAGE(PG8_SA(0, 0), a2, voffA);
;             PG8_WAIT_V(8); PG8_WAIT_L(0); PG8_BAR; PG8_MMA(1, 0, At, B0); PG8_MMA(1, 1, At, B1); PG8_BAR; PG8_SCHED;
.LBB0_215:
	s_add_u32 s20, s0, 0x100
	s_addc_u32 s21, s1, 0
	s_add_i32 s28, 0, 0x10000
	s_cmp_eq_u32 s51, 40
	s_cselect_b32 s25, s5, s21
	s_cselect_b32 s24, s4, s20
	v_add_u32_e32 v138, s28, v141
	s_cselect_b32 s23, s45, s15
	s_cselect_b32 s22, s44, s14
	s_add_i32 s29, 0, 0x14000
	ds_read_b128 v[134:137], v138
	ds_read_b128 v[144:147], v138 offset:1024
	ds_read_b128 v[148:151], v138 offset:2048
	ds_read_b128 v[152:155], v138 offset:3072
	v_add_u32_e32 v138, s29, v141
	ds_read_b128 v[156:159], v138
	ds_read_b128 v[160:163], v138 offset:1024
	ds_read_b128 v[164:167], v138 offset:2048
	ds_read_b128 v[168:171], v138 offset:3072
	v_lshl_add_u64 v[138:139], s[0:1], 0, v[130:131]
	s_add_i32 m0, s26, 0xc000
	ds_read_b128 v[172:175], v143
	ds_read_b128 v[176:179], v143 offset:1024
	ds_read_b128 v[180:183], v143 offset:2048
	ds_read_b128 v[184:187], v143 offset:3072
	ds_read_b128 v[188:191], v143 offset:4096
	ds_read_b128 v[192:195], v143 offset:5120
	ds_read_b128 v[196:199], v143 offset:6144
	ds_read_b128 v[200:203], v143 offset:7168
	global_load_lds_dwordx4 v[138:139], off
	v_lshl_add_u64 v[138:139], s[0:1], 0, v[132:133]
	s_add_i32 m0, s26, 0xe000
	s_nop 0
	global_load_lds_dwordx4 v[138:139], off
	s_waitcnt vmcnt(8)
	s_waitcnt lgkmcnt(0)
	s_barrier
	s_waitcnt lgkmcnt(0)
	v_mfma_f32_16x16x32_bf16 v[124:127], v[134:137], v[172:175], v[124:127]
	v_mfma_f32_16x16x32_bf16 v[120:123], v[148:151], v[172:175], v[120:123]
	v_mfma_f32_16x16x32_bf16 v[116:119], v[134:137], v[180:183], v[116:119]
	v_mfma_f32_16x16x32_bf16 v[112:115], v[148:151], v[180:183], v[112:115]
	v_mfma_f32_16x16x32_bf16 v[108:111], v[134:137], v[188:191], v[108:111]
	v_mfma_f32_16x16x32_bf16 v[100:103], v[148:151], v[188:191], v[100:103]
	v_mfma_f32_16x16x32_bf16 v[92:95], v[134:137], v[196:199], v[92:95]
	v_mfma_f32_16x16x32_bf16 v[80:83], v[148:151], v[196:199], v[80:83]
	v_mfma_f32_16x16x32_bf16 v[124:127], v[144:147], v[176:179], v[124:127]
	v_mfma_f32_16x16x32_bf16 v[120:123], v[152:155], v[176:179], v[120:123]
	v_mfma_f32_16x16x32_bf16 v[116:119], v[144:147], v[184:187], v[116:119]
	v_mfma_f32_16x16x32_bf16 v[112:115], v[152:155], v[184:187], v[112:115]
	v_mfma_f32_16x16x32_bf16 v[108:111], v[144:147], v[192:195], v[108:111]
	v_mfma_f32_16x16x32_bf16 v[100:103], v[152:155], v[192:195], v[100:103]
	v_mfma_f32_16x16x32_bf16 v[92:95], v[144:147], v[200:203], v[92:95]
	v_mfma_f32_16x16x32_bf16 v[80:83], v[152:155], v[200:203], v[80:83]
	v_mfma_f32_16x16x32_bf16 v[104:107], v[156:159], v[172:175], v[104:107]
	v_mfma_f32_16x16x32_bf16 v[96:99], v[164:167], v[172:175], v[96:99]
	v_mfma_f32_16x16x32_bf16 v[88:91], v[156:159], v[180:183], v[88:91]
	v_mfma_f32_16x16x32_bf16 v[84:87], v[164:167], v[180:183], v[84:87]
	v_mfma_f32_16x16x32_bf16 v[76:79], v[156:159], v[188:191], v[76:79]
	v_mfma_f32_16x16x32_bf16 v[72:75], v[164:167], v[188:191], v[72:75]
	v_mfma_f32_16x16x32_bf16 v[68:71], v[156:159], v[196:199], v[68:71]
	v_mfma_f32_16x16x32_bf16 v[64:67], v[164:167], v[196:199], v[64:67]
	v_mfma_f32_16x16x32_bf16 v[104:107], v[160:163], v[176:179], v[104:107]
	v_mfma_f32_16x16x32_bf16 v[96:99], v[168:171], v[176:179], v[96:99]
	v_mfma_f32_16x16x32_bf16 v[88:91], v[160:163], v[184:187], v[88:91]
	v_mfma_f32_16x16x32_bf16 v[84:87], v[168:171], v[184:187], v[84:87]
	v_mfma_f32_16x16x32_bf16 v[76:79], v[160:163], v[192:195], v[76:79]
	v_mfma_f32_16x16x32_bf16 v[72:75], v[168:171], v[192:195], v[72:75]
	v_mfma_f32_16x16x32_bf16 v[68:71], v[160:163], v[200:203], v[68:71]
	v_mfma_f32_16x16x32_bf16 v[64:67], v[168:171], v[200:203], v[64:67]
	s_barrier
	s_add_i32 s0, s28, s19
	v_lshl_add_u64 v[138:139], s[22:23], 0, v[208:209]
	s_mov_b32 m0, s0
	ds_read_b128 v[172:175], v143 offset:16384
	ds_read_b128 v[176:179], v143 offset:17408
	ds_read_b128 v[180:183], v143 offset:18432
	ds_read_b128 v[184:187], v143 offset:19456
	ds_read_b128 v[188:191], v143 offset:20480
	ds_read_b128 v[192:195], v143 offset:21504
	ds_read_b128 v[196:199], v143 offset:22528
	ds_read_b128 v[200:203], v143 offset:23552
	global_load_lds_dwordx4 v[138:139], off
	s_add_i32 m0, s0, 0x2000
	s_add_u32 s0, s22, 0xb0000
	v_lshl_add_u64 v[204:205], s[22:23], 0, v[128:129]
	s_addc_u32 s1, s23, 0
	s_add_i32 s28, s29, s19
	global_load_lds_dwordx4 v[204:205], off
	v_lshl_add_u64 v[206:207], s[0:1], 0, v[208:209]
	s_mov_b32 m0, s28
	v_lshl_add_u64 v[210:211], s[24:25], 0, v[128:129]
	global_load_lds_dwordx4 v[206:207], off
	v_lshl_add_u64 v[206:207], s[0:1], 0, v[128:129]
	s_add_i32 m0, s28, 0x2000
	s_nop 0
	global_load_lds_dwordx4 v[206:207], off
	v_lshl_add_u64 v[206:207], s[24:25], 0, v[208:209]
	s_mov_b32 m0, s26
	s_nop 0
	global_load_lds_dwordx4 v[206:207], off
	s_mov_b32 m0, s34
	s_nop 0
	global_load_lds_dwordx4 v[210:211], off
	s_waitcnt vmcnt(8)
	s_waitcnt lgkmcnt(0)
	s_barrier
; #define PG8_STAGE(bufoff, gbase, voff) do { _Pragma("unroll") for (int _i = 0; _i < 2; ++_i) \
;         __builtin_amdgcn_global_load_lds((const unsigned*)((const char*)(gbase) + (voff)[_i]), (PG8_LAS unsigned*)(lds + (bufoff) + ldsw + _i * 8192), 16, 0, 0); } while (0)
; #define PG8_LDA(dst, b, h) do { _Pragma("unroll") for (int m = 0; m < 4; ++m) _Pragma("unroll") for (int k = 0; k < 2; ++k) dst[m][k] = *(const PG8_LAS bf16x8*)(lds + PG8_SA(b, h) + aoff + m * 2048 + k * 1024); } while (0)
; #define PG8_LDB(dst, b, h) do { _Pragma("unroll") for (int n = 0; n < 2; ++n) _Pragma("unroll") for (int k = 0; k < 2; ++k) dst[n][k] = *(const PG8_LAS bf16x8*)(lds + PG8_SB(b, h) + boff + n * 2048 + k * 1024); } while (0)
; #define PG8_MMA(ai, bj, At, Bt) do { __builtin_amdgcn_s_setprio(1); _Pragma("unroll") for (int m = 0; m < 4; ++m) _Pragma("unroll") for (int n = 0; n < 2; ++n) _Pragma("unroll") for (int k = 0; k < 2; ++k) \
;         acc[ai][bj][m][n] = __builtin_amdgcn_mfma_f32_16x16x32_bf16(Bt[n][k], At[m][k], acc[ai][bj][m][n], 0, 0, 0); __builtin_amdgcn_s_setprio(0); } while (0)
; #define PG8_WAIT_V(n) asm volatile("s_waitcnt vmcnt(" #n ")" ::: "memory")
; #define PG8_WAIT_L(n) asm volatile("s_waitcnt lgkmcnt(" #n ")" ::: "memory")
; #define PG8_BAR __builtin_amdgcn_s_barrier()
; #define PG8_SCHED __builtin_amdgcn_sched_barrier(0)
; template <class Epi, class Sched, bool ALIGN_EPI = false, bool SP2 = false>
; __device__ __forceinline__ void gemm_phase(PG8_LAS unsigned char* lds, const Gemm g, const Sched& S, const Epi& E) {
;     ...
;             PG8_WAIT_V(8); PG8_WAIT_L(0); PG8_BAR; PG8_MMA(1, 0, At, B0); PG8_MMA(1, 1, At, B1); PG8_BAR; PG8_SCHED;
;             PG8_LDB(B0, 1, 0); PG8_LDB(B1, 1, 1); PG8_SCHED; PG8_LDA(At, 1, 0); PG8_STAGE(PG8_SA(0, 1), a2 + hstepA, voffA);
;             PG8_WAIT_V(8); PG8_WAIT_L(0); PG8_BAR; PG8_MMA(0, 0, At, B0); PG8_MMA(0, 1, At, B1); PG8_BAR; PG8_SCHED;
	s_waitcnt lgkmcnt(0)
	v_mfma_f32_16x16x32_bf16 v[60:63], v[134:137], v[172:175], v[60:63]
	v_mfma_f32_16x16x32_bf16 v[56:59], v[148:151], v[172:175], v[56:59]
	v_mfma_f32_16x16x32_bf16 v[52:55], v[134:137], v[180:183], v[52:55]
	v_mfma_f32_16x16x32_bf16 v[48:51], v[148:151], v[180:183], v[48:51]
	v_mfma_f32_16x16x32_bf16 v[44:47], v[134:137], v[188:191], v[44:47]
	v_mfma_f32_16x16x32_bf16 v[32:35], v[148:151], v[188:191], v[32:35]
	v_mfma_f32_16x16x32_bf16 v[16:19], v[134:137], v[196:199], v[16:19]
	v_mfma_f32_16x16x32_bf16 v[8:11], v[148:151], v[196:199], v[8:11]
	v_mfma_f32_16x16x32_bf16 v[60:63], v[144:147], v[176:179], v[60:63]
	v_mfma_f32_16x16x32_bf16 v[56:59], v[152:155], v[176:179], v[56:59]
	v_mfma_f32_16x16x32_bf16 v[52:55], v[144:147], v[184:187], v[52:55]
	v_mfma_f32_16x16x32_bf16 v[48:51], v[152:155], v[184:187], v[48:51]
	v_mfma_f32_16x16x32_bf16 v[44:47], v[144:147], v[192:195], v[44:47]
	v_mfma_f32_16x16x32_bf16 v[32:35], v[152:155], v[192:195], v[32:35]
	v_mfma_f32_16x16x32_bf16 v[16:19], v[144:147], v[200:203], v[16:19]
	v_mfma_f32_16x16x32_bf16 v[8:11], v[152:155], v[200:203], v[8:11]
	v_mfma_f32_16x16x32_bf16 v[40:43], v[156:159], v[172:175], v[40:43]
	v_mfma_f32_16x16x32_bf16 v[36:39], v[164:167], v[172:175], v[36:39]
	v_mfma_f32_16x16x32_bf16 v[28:31], v[156:159], v[180:183], v[28:31]
	v_mfma_f32_16x16x32_bf16 v[24:27], v[164:167], v[180:183], v[24:27]
	v_mfma_f32_16x16x32_bf16 v[20:23], v[156:159], v[188:191], v[20:23]
	v_mfma_f32_16x16x32_bf16 v[12:15], v[164:167], v[188:191], v[12:15]
	v_mfma_f32_16x16x32_bf16 v[4:7], v[156:159], v[196:199], v[4:7]
	v_mfma_f32_16x16x32_bf16 v[0:3], v[164:167], v[196:199], v[0:3]
	v_mfma_f32_16x16x32_bf16 v[40:43], v[160:163], v[176:179], v[40:43]
	v_mfma_f32_16x16x32_bf16 v[36:39], v[168:171], v[176:179], v[36:39]
	v_mfma_f32_16x16x32_bf16 v[28:31], v[160:163], v[184:187], v[28:31]
	v_mfma_f32_16x16x32_bf16 v[24:27], v[168:171], v[184:187], v[24:27]
	v_mfma_f32_16x16x32_bf16 v[20:23], v[160:163], v[192:195], v[20:23]
	v_mfma_f32_16x16x32_bf16 v[12:15], v[168:171], v[192:195], v[12:15]
	v_mfma_f32_16x16x32_bf16 v[4:7], v[160:163], v[200:203], v[4:7]
	v_mfma_f32_16x16x32_bf16 v[0:3], v[168:171], v[200:203], v[0:3]
	s_barrier
	s_add_i32 s28, 0, 0x18000
	s_add_i32 s29, 0, 0x1c000
	v_add_u32_e32 v152, s28, v141
	v_add_u32_e32 v168, s29, v141
	ds_read_b128 v[134:137], v152
	ds_read_b128 v[144:147], v152 offset:1024
	ds_read_b128 v[148:151], v152 offset:2048
	ds_read_b128 v[152:155], v152 offset:3072
	ds_read_b128 v[156:159], v168
	ds_read_b128 v[160:163], v168 offset:1024
	ds_read_b128 v[164:167], v168 offset:2048
	ds_read_b128 v[168:171], v168 offset:3072
	s_add_u32 s0, s24, 0xb0000
	s_addc_u32 s1, s25, 0
	s_mov_b32 m0, s35
	v_lshl_add_u64 v[212:213], s[0:1], 0, v[208:209]
	ds_read_b128 v[172:175], v143 offset:32768
	ds_read_b128 v[176:179], v143 offset:33792
	ds_read_b128 v[180:183], v143 offset:34816
	ds_read_b128 v[184:187], v143 offset:35840
	ds_read_b128 v[188:191], v143 offset:36864
	ds_read_b128 v[192:195], v143 offset:37888
	ds_read_b128 v[196:199], v143 offset:38912
	ds_read_b128 v[200:203], v143 offset:39936
	global_load_lds_dwordx4 v[212:213], off
	v_lshl_add_u64 v[212:213], s[0:1], 0, v[128:129]
	s_mov_b32 m0, s39
	s_nop 0
	global_load_lds_dwordx4 v[212:213], off
	s_waitcnt vmcnt(8)
	s_waitcnt lgkmcnt(0)
	s_barrier
	s_waitcnt lgkmcnt(0)
	v_mfma_f32_16x16x32_bf16 v[124:127], v[134:137], v[172:175], v[124:127]
	v_mfma_f32_16x16x32_bf16 v[120:123], v[148:151], v[172:175], v[120:123]
	v_mfma_f32_16x16x32_bf16 v[116:119], v[134:137], v[180:183], v[116:119]
	v_mfma_f32_16x16x32_bf16 v[112:115], v[148:151], v[180:183], v[112:115]
	v_mfma_f32_16x16x32_bf16 v[108:111], v[134:137], v[188:191], v[108:111]
	v_mfma_f32_16x16x32_bf16 v[100:103], v[148:151], v[188:191], v[100:103]
	v_mfma_f32_16x16x32_bf16 v[92:95], v[134:137], v[196:199], v[92:95]
	v_mfma_f32_16x16x32_bf16 v[80:83], v[148:151], v[196:199], v[80:83]
	v_mfma_f32_16x16x32_bf16 v[124:127], v[144:147], v[176:179], v[124:127]
	v_mfma_f32_16x16x32_bf16 v[120:123], v[152:155], v[176:179], v[120:123]
	v_mfma_f32_16x16x32_bf16 v[116:119], v[144:147], v[184:187], v[116:119]
	v_mfma_f32_16x16x32_bf16 v[112:115], v[152:155], v[184:187], v[112:115]
	v_mfma_f32_16x16x32_bf16 v[108:111], v[144:147], v[192:195], v[108:111]
	v_mfma_f32_16x16x32_bf16 v[100:103], v[152:155], v[192:195], v[100:103]
	v_mfma_f32_16x16x32_bf16 v[92:95], v[144:147], v[200:203], v[92:95]
	v_mfma_f32_16x16x32_bf16 v[80:83], v[152:155], v[200:203], v[80:83]
	v_mfma_f32_16x16x32_bf16 v[104:107], v[156:159], v[172:175], v[104:107]
	v_mfma_f32_16x16x32_bf16 v[96:99], v[164:167], v[172:175], v[96:99]
	v_mfma_f32_16x16x32_bf16 v[88:91], v[156:159], v[180:183], v[88:91]
	v_mfma_f32_16x16x32_bf16 v[84:87], v[164:167], v[180:183], v[84:87]
	v_mfma_f32_16x16x32_bf16 v[76:79], v[156:159], v[188:191], v[76:79]
	v_mfma_f32_16x16x32_bf16 v[72:75], v[164:167], v[188:191], v[72:75]
	v_mfma_f32_16x16x32_bf16 v[68:71], v[156:159], v[196:199], v[68:71]
	v_mfma_f32_16x16x32_bf16 v[64:67], v[164:167], v[196:199], v[64:67]
	v_mfma_f32_16x16x32_bf16 v[104:107], v[160:163], v[176:179], v[104:107]
	v_mfma_f32_16x16x32_bf16 v[96:99], v[168:171], v[176:179], v[96:99]
	v_mfma_f32_16x16x32_bf16 v[88:91], v[160:163], v[184:187], v[88:91]
	v_mfma_f32_16x16x32_bf16 v[84:87], v[168:171], v[184:187], v[84:87]
	v_mfma_f32_16x16x32_bf16 v[76:79], v[160:163], v[192:195], v[76:79]
	v_mfma_f32_16x16x32_bf16 v[72:75], v[168:171], v[192:195], v[72:75]
	v_mfma_f32_16x16x32_bf16 v[68:71], v[160:163], v[200:203], v[68:71]
	v_mfma_f32_16x16x32_bf16 v[64:67], v[168:171], v[200:203], v[64:67]
	s_barrier
; #define PG8_STAGE(bufoff, gbase, voff) do { _Pragma("unroll") for (int _i = 0; _i < 2; ++_i) \
;         __builtin_amdgcn_global_load_lds((const unsigned*)((const char*)(gbase) + (voff)[_i]), (PG8_LAS unsigned*)(lds + (bufoff) + ldsw + _i * 8192), 16, 0, 0); } while (0)
; #define PG8_LDA(dst, b, h) do { _Pragma("unroll") for (int m = 0; m < 4; ++m) _Pragma("unroll") for (int k = 0; k < 2; ++k) dst[m][k] = *(const PG8_LAS bf16x8*)(lds + PG8_SA(b, h) + aoff + m * 2048 + k * 1024); } while (0)
; #define PG8_MMA(ai, bj, At, Bt) do { __builtin_amdgcn_s_setprio(1); _Pragma("unroll") for (int m = 0; m < 4; ++m) _Pragma("unroll") for (int n = 0; n < 2; ++n) _Pragma("unroll") for (int k = 0; k < 2; ++k) \
;         acc[ai][bj][m][n] = __builtin_amdgcn_mfma_f32_16x16x32_bf16(Bt[n][k], At[m][k], acc[ai][bj][m][n], 0, 0, 0); __builtin_amdgcn_s_setprio(0); } while (0)
; #define PG8_WAIT_V(n) asm volatile("s_waitcnt vmcnt(" #n ")" ::: "memory")
; #define PG8_WAIT_L(n) asm volatile("s_waitcnt lgkmcnt(" #n ")" ::: "memory")
; #define PG8_BAR __builtin_amdgcn_s_barrier()
; #define PG8_SCHED __builtin_amdgcn_sched_barrier(0)
; template <class Epi, class Sched, bool ALIGN_EPI = false, bool SP2 = false>
; __device__ __forceinline__ void gemm_phase(PG8_LAS unsigned char* lds, const Gemm g, const Sched& S, const Epi& E) {
;     ...
;         for (int t = 0; t < nt; t += 2) {
;             const bool last = (t == nt - 2);
;     ...
;             PG8_LDA(At, 1, 1); PG8_STAGE(PG8_SB(1, 0), b3, voffB); PG8_STAGE(PG8_SB(1, 1), b3 + hstepB, voffB); PG8_STAGE(PG8_SA(1, 0), a3, voffA);
;             PG8_WAIT_V(8); PG8_WAIT_L(0); PG8_BAR; PG8_MMA(1, 0, At, B0); PG8_MMA(1, 1, At, B1); PG8_BAR; PG8_SCHED;
	s_add_i32 s0, s28, s19
	v_lshl_add_u64 v[138:139], v[138:139], 0, s[10:11]
	s_mov_b32 m0, s0
	ds_read_b128 v[172:175], v143 offset:49152
	ds_read_b128 v[176:179], v143 offset:50176
	ds_read_b128 v[180:183], v143 offset:51200
	ds_read_b128 v[184:187], v143 offset:52224
	ds_read_b128 v[188:191], v143 offset:53248
	ds_read_b128 v[192:195], v143 offset:54272
	ds_read_b128 v[196:199], v143 offset:55296
	ds_read_b128 v[200:203], v143 offset:56320
	global_load_lds_dwordx4 v[138:139], off
	s_add_i32 m0, s0, 0x2000
	s_add_u32 s0, s22, 0xb0080
	v_lshl_add_u64 v[138:139], v[204:205], 0, s[10:11]
	s_addc_u32 s1, s23, 0
	s_add_i32 s22, s29, s19
	global_load_lds_dwordx4 v[138:139], off
	v_lshl_add_u64 v[138:139], s[0:1], 0, v[208:209]
	s_mov_b32 m0, s22
	s_nop 0
	global_load_lds_dwordx4 v[138:139], off
	v_lshl_add_u64 v[138:139], s[0:1], 0, v[128:129]
	s_add_i32 m0, s22, 0x2000
	s_nop 0
	global_load_lds_dwordx4 v[138:139], off
	v_lshl_add_u64 v[138:139], v[206:207], 0, s[10:11]
	s_mov_b32 m0, s46
	s_nop 0
	global_load_lds_dwordx4 v[138:139], off
	v_lshl_add_u64 v[138:139], v[210:211], 0, s[10:11]
	s_mov_b32 m0, s47
	s_nop 0
	global_load_lds_dwordx4 v[138:139], off
	s_waitcnt vmcnt(8)
	s_waitcnt lgkmcnt(0)
	s_barrier
	s_waitcnt lgkmcnt(0)
	v_mfma_f32_16x16x32_bf16 v[60:63], v[134:137], v[172:175], v[60:63]
	v_mfma_f32_16x16x32_bf16 v[56:59], v[148:151], v[172:175], v[56:59]
	v_mfma_f32_16x16x32_bf16 v[52:55], v[134:137], v[180:183], v[52:55]
	v_mfma_f32_16x16x32_bf16 v[48:51], v[148:151], v[180:183], v[48:51]
	v_mfma_f32_16x16x32_bf16 v[44:47], v[134:137], v[188:191], v[44:47]
	v_mfma_f32_16x16x32_bf16 v[32:35], v[148:151], v[188:191], v[32:35]
	v_mfma_f32_16x16x32_bf16 v[16:19], v[134:137], v[196:199], v[16:19]
	v_mfma_f32_16x16x32_bf16 v[8:11], v[148:151], v[196:199], v[8:11]
	v_mfma_f32_16x16x32_bf16 v[60:63], v[144:147], v[176:179], v[60:63]
	v_mfma_f32_16x16x32_bf16 v[56:59], v[152:155], v[176:179], v[56:59]
	v_mfma_f32_16x16x32_bf16 v[52:55], v[144:147], v[184:187], v[52:55]
	v_mfma_f32_16x16x32_bf16 v[48:51], v[152:155], v[184:187], v[48:51]
	v_mfma_f32_16x16x32_bf16 v[44:47], v[144:147], v[192:195], v[44:47]
	v_mfma_f32_16x16x32_bf16 v[32:35], v[152:155], v[192:195], v[32:35]
	v_mfma_f32_16x16x32_bf16 v[16:19], v[144:147], v[200:203], v[16:19]
	v_mfma_f32_16x16x32_bf16 v[8:11], v[152:155], v[200:203], v[8:11]
	v_mfma_f32_16x16x32_bf16 v[40:43], v[156:159], v[172:175], v[40:43]
	v_mfma_f32_16x16x32_bf16 v[36:39], v[164:167], v[172:175], v[36:39]
	v_mfma_f32_16x16x32_bf16 v[28:31], v[156:159], v[180:183], v[28:31]
	v_mfma_f32_16x16x32_bf16 v[24:27], v[164:167], v[180:183], v[24:27]
	v_mfma_f32_16x16x32_bf16 v[20:23], v[156:159], v[188:191], v[20:23]
	v_mfma_f32_16x16x32_bf16 v[12:15], v[164:167], v[188:191], v[12:15]
	v_mfma_f32_16x16x32_bf16 v[4:7], v[156:159], v[196:199], v[4:7]
	v_mfma_f32_16x16x32_bf16 v[0:3], v[164:167], v[196:199], v[0:3]
	v_mfma_f32_16x16x32_bf16 v[40:43], v[160:163], v[176:179], v[40:43]
	v_mfma_f32_16x16x32_bf16 v[36:39], v[168:171], v[176:179], v[36:39]
	v_mfma_f32_16x16x32_bf16 v[28:31], v[160:163], v[184:187], v[28:31]
	v_mfma_f32_16x16x32_bf16 v[24:27], v[168:171], v[184:187], v[24:27]
	v_mfma_f32_16x16x32_bf16 v[20:23], v[160:163], v[192:195], v[20:23]
	v_mfma_f32_16x16x32_bf16 v[12:15], v[168:171], v[192:195], v[12:15]
	v_mfma_f32_16x16x32_bf16 v[4:7], v[160:163], v[200:203], v[4:7]
	v_mfma_f32_16x16x32_bf16 v[0:3], v[168:171], v[200:203], v[0:3]
	s_barrier
	s_add_i32 s51, s51, 2
	s_add_u32 s14, s14, 0x100
	s_addc_u32 s15, s15, 0
	s_cmp_gt_u32 s51, 41
	s_mov_b64 s[0:1], s[20:21]
	s_cbranch_scc0 .LBB0_215
	s_and_b64 vcc, exec, s[42:43]
	s_cbranch_vccz .LBB0_218
	s_barrier

; #define PG8_STAGE(bufoff, gbase, voff) do { _Pragma("unroll") for (int _i = 0; _i < 2; ++_i) \
;         __builtin_amdgcn_global_load_lds((const unsigned*)((const char*)(gbase) + (voff)[_i]), (PG8_LAS unsigned*)(lds + (bufoff) + ldsw + _i * 8192), 16, 0, 0); } while (0)
; #define PG8_LDA(dst, b, h) do { _Pragma("unroll") for (int m = 0; m < 4; ++m) _Pragma("unroll") for (int k = 0; k < 2; ++k) dst[m][k] = *(const PG8_LAS bf16x8*)(lds + PG8_SA(b, h) + aoff + m * 2048 + k * 1024); } while (0)
; #define PG8_LDB(dst, b, h) do { _Pragma("unroll") for (int n = 0; n < 2; ++n) _Pragma("unroll") for (int k = 0; k < 2; ++k) dst[n][k] = *(const PG8_LAS bf16x8*)(lds + PG8_SB(b, h) + boff + n * 2048 + k * 1024); } while (0)
; #define PG8_WAIT_V(n) asm volatile("s_waitcnt vmcnt(" #n ")" ::: "memory")
; #define PG8_WAIT_L(n) asm volatile("s_waitcnt lgkmcnt(" #n ")" ::: "memory")
; #define PG8_BAR __builtin_amdgcn_s_barrier()
; #define PG8_SCHED __builtin_amdgcn_sched_barrier(0)
; template <class Epi, class Sched, bool ALIGN_EPI = false, bool SP2 = false>
; __device__ __forceinline__ void gemm_phase(PG8_LAS unsigned char* lds, const Gemm g, const Sched& S, const Epi& E) {
;     ...
;         const char* nA = has_next ? (const char*)g.A + (size_t)nxt.pm * tstepA : cA; const char* nB = has_next ? (const char*)g.Bt + (size_t)nxt.pn * tstepB : cB;
;         for (int t = 0; t < nt; t += 2) {
;             const bool last = (t == nt - 2);
;             const char* a1 = cA + (size_t)(t + 1) * kstep;
;             const char* a2 = last ? nA : cA + (size_t)(t + 2) * kstep; const char* b2 = last ? nB : cB + (size_t)(t + 2) * kstep;
;             const char* a3 = a2 + kstep; const char* b3 = b2 + kstep;
;             if (last && has_next) S.a_ready(nxt);
;             if constexpr (SP2) {
;             PG8_LDB(B0, 0, 0); PG8_LDB(B1, 0, 1); PG8_SCHED; PG8_LDA(At, 0, 0); PG8_STAGE(PG8_SA(1, 1), a1 + hstepA, voffA);
;             PG8_WAIT_V(8); PG8_WAIT_L(0); PG8_BAR; PG8_MMA(0, 0, At, B0); PG8_MMA(0, 1, At, B1); PG8_BAR; PG8_SCHED;
;             PG8_LDA(At, 0, 1); PG8_STAGE(PG8_SB(0, 0), b2, voffB); PG8_STAGE(PG8_SB(0, 1), b2 + hstepB, voffB); PG8_STAGE(PG8_SA(0, 0), a2, voffA);
;             PG8_WAIT_V(8); PG8_WAIT_L(0); PG8_BAR; PG8_MMA(1, 0, At, B0); PG8_MMA(1, 1, At, B1); PG8_BAR; PG8_SCHED;
.LBB0_338:
	s_add_u32 s22, s0, 0xfffc0080
	s_addc_u32 s23, s1, -1
	s_add_i32 s28, 0, 0x10000
	s_cmp_eq_u32 s51, 12
	s_cselect_b32 s25, s14, s23
	s_cselect_b32 s24, s15, s22
	v_add_u32_e32 v138, s28, v142
	s_cselect_b32 s23, s21, s50
	s_cselect_b32 s22, s41, s49
	s_add_i32 s29, 0, 0x14000
	ds_read_b128 v[146:149], v138
	ds_read_b128 v[150:153], v138 offset:1024
	ds_read_b128 v[154:157], v138 offset:2048
	ds_read_b128 v[158:161], v138 offset:3072
	v_add_u32_e32 v138, s29, v142
	ds_read_b128 v[162:165], v138
	ds_read_b128 v[166:169], v138 offset:1024
	ds_read_b128 v[170:173], v138 offset:2048
	ds_read_b128 v[174:177], v138 offset:3072
	v_lshl_add_u64 v[140:141], s[0:1], 0, v[134:135]
	s_add_i32 m0, s26, 0xc000
	ds_read_b128 v[178:181], v144
	ds_read_b128 v[182:185], v144 offset:1024
	ds_read_b128 v[186:189], v144 offset:2048
	ds_read_b128 v[190:193], v144 offset:3072
	ds_read_b128 v[194:197], v144 offset:4096
	ds_read_b128 v[198:201], v144 offset:5120
	ds_read_b128 v[202:205], v144 offset:6144
	ds_read_b128 v[210:213], v144 offset:7168
	global_load_lds_dwordx4 v[140:141], off
	v_lshl_add_u64 v[140:141], s[0:1], 0, v[136:137]
	s_add_i32 m0, s26, 0xe000
	s_nop 0
	global_load_lds_dwordx4 v[140:141], off
	s_waitcnt vmcnt(8)
	s_waitcnt lgkmcnt(0)
	s_barrier
	s_waitcnt lgkmcnt(0)
	v_mfma_f32_16x16x32_bf16 v[124:127], v[146:149], v[178:181], v[124:127]
	v_mfma_f32_16x16x32_bf16 v[120:123], v[154:157], v[178:181], v[120:123]
	v_mfma_f32_16x16x32_bf16 v[116:119], v[146:149], v[186:189], v[116:119]
	v_mfma_f32_16x16x32_bf16 v[108:111], v[154:157], v[186:189], v[108:111]
	v_mfma_f32_16x16x32_bf16 v[100:103], v[146:149], v[194:197], v[100:103]
	v_mfma_f32_16x16x32_bf16 v[92:95], v[154:157], v[194:197], v[92:95]
	v_mfma_f32_16x16x32_bf16 v[84:87], v[146:149], v[202:205], v[84:87]
	v_mfma_f32_16x16x32_bf16 v[76:79], v[154:157], v[202:205], v[76:79]
	v_mfma_f32_16x16x32_bf16 v[124:127], v[150:153], v[182:185], v[124:127]
	v_mfma_f32_16x16x32_bf16 v[120:123], v[158:161], v[182:185], v[120:123]
	v_mfma_f32_16x16x32_bf16 v[116:119], v[150:153], v[190:193], v[116:119]
	v_mfma_f32_16x16x32_bf16 v[108:111], v[158:161], v[190:193], v[108:111]
	v_mfma_f32_16x16x32_bf16 v[100:103], v[150:153], v[198:201], v[100:103]
	v_mfma_f32_16x16x32_bf16 v[92:95], v[158:161], v[198:201], v[92:95]
	v_mfma_f32_16x16x32_bf16 v[84:87], v[150:153], v[210:213], v[84:87]
	v_mfma_f32_16x16x32_bf16 v[76:79], v[158:161], v[210:213], v[76:79]
	v_mfma_f32_16x16x32_bf16 v[112:115], v[162:165], v[178:181], v[112:115]
	v_mfma_f32_16x16x32_bf16 v[104:107], v[170:173], v[178:181], v[104:107]
	v_mfma_f32_16x16x32_bf16 v[96:99], v[162:165], v[186:189], v[96:99]
	v_mfma_f32_16x16x32_bf16 v[88:91], v[170:173], v[186:189], v[88:91]
	v_mfma_f32_16x16x32_bf16 v[80:83], v[162:165], v[194:197], v[80:83]
	v_mfma_f32_16x16x32_bf16 v[72:75], v[170:173], v[194:197], v[72:75]
	v_mfma_f32_16x16x32_bf16 v[68:71], v[162:165], v[202:205], v[68:71]
	v_mfma_f32_16x16x32_bf16 v[64:67], v[170:173], v[202:205], v[64:67]
	v_mfma_f32_16x16x32_bf16 v[112:115], v[166:169], v[182:185], v[112:115]
	v_mfma_f32_16x16x32_bf16 v[104:107], v[174:177], v[182:185], v[104:107]
	v_mfma_f32_16x16x32_bf16 v[96:99], v[166:169], v[190:193], v[96:99]
	v_mfma_f32_16x16x32_bf16 v[88:91], v[174:177], v[190:193], v[88:91]
	v_mfma_f32_16x16x32_bf16 v[80:83], v[166:169], v[198:201], v[80:83]
	v_mfma_f32_16x16x32_bf16 v[72:75], v[174:177], v[198:201], v[72:75]
	v_mfma_f32_16x16x32_bf16 v[68:71], v[166:169], v[210:213], v[68:71]
	v_mfma_f32_16x16x32_bf16 v[64:67], v[174:177], v[210:213], v[64:67]
	s_barrier
	s_add_i32 s28, s28, s18
	v_lshl_add_u64 v[140:141], s[22:23], 0, v[208:209]
	s_mov_b32 m0, s28
	ds_read_b128 v[178:181], v144 offset:16384
	ds_read_b128 v[182:185], v144 offset:17408
	ds_read_b128 v[186:189], v144 offset:18432
	ds_read_b128 v[190:193], v144 offset:19456
	ds_read_b128 v[194:197], v144 offset:20480
	ds_read_b128 v[198:201], v144 offset:21504
	ds_read_b128 v[202:205], v144 offset:22528
	ds_read_b128 v[210:213], v144 offset:23552
	global_load_lds_dwordx4 v[140:141], off
	s_add_i32 m0, s28, 0x2000
	s_add_u32 s52, s22, 0x40000
	v_lshl_add_u64 v[206:207], s[22:23], 0, v[128:129]
	s_addc_u32 s53, s23, 0
	s_add_i32 s28, s29, s18
	global_load_lds_dwordx4 v[206:207], off
	v_lshl_add_u64 v[222:223], s[52:53], 0, v[208:209]
	s_mov_b32 m0, s28
	v_lshl_add_u64 v[224:225], s[24:25], 0, v[130:131]
	global_load_lds_dwordx4 v[222:223], off
	v_lshl_add_u64 v[222:223], s[52:53], 0, v[128:129]
	s_add_i32 m0, s28, 0x2000
	s_nop 0
	global_load_lds_dwordx4 v[222:223], off
	v_lshl_add_u64 v[222:223], s[24:25], 0, v[132:133]
	s_mov_b32 m0, s26
	s_nop 0
	global_load_lds_dwordx4 v[222:223], off
	s_mov_b32 m0, s34
	s_nop 0
	global_load_lds_dwordx4 v[224:225], off
	s_waitcnt vmcnt(8)
	s_waitcnt lgkmcnt(0)
	s_barrier
; #define PG8_STAGE(bufoff, gbase, voff) do { _Pragma("unroll") for (int _i = 0; _i < 2; ++_i) \
;         __builtin_amdgcn_global_load_lds((const unsigned*)((const char*)(gbase) + (voff)[_i]), (PG8_LAS unsigned*)(lds + (bufoff) + ldsw + _i * 8192), 16, 0, 0); } while (0)
; #define PG8_LDA(dst, b, h) do { _Pragma("unroll") for (int m = 0; m < 4; ++m) _Pragma("unroll") for (int k = 0; k < 2; ++k) dst[m][k] = *(const PG8_LAS bf16x8*)(lds + PG8_SA(b, h) + aoff + m * 2048 + k * 1024); } while (0)
; #define PG8_LDB(dst, b, h) do { _Pragma("unroll") for (int n = 0; n < 2; ++n) _Pragma("unroll") for (int k = 0; k < 2; ++k) dst[n][k] = *(const PG8_LAS bf16x8*)(lds + PG8_SB(b, h) + boff + n * 2048 + k * 1024); } while (0)
; #define PG8_MMA(ai, bj, At, Bt) do { __builtin_amdgcn_s_setprio(1); _Pragma("unroll") for (int m = 0; m < 4; ++m) _Pragma("unroll") for (int n = 0; n < 2; ++n) _Pragma("unroll") for (int k = 0; k < 2; ++k) \
;         acc[ai][bj][m][n] = __builtin_amdgcn_mfma_f32_16x16x32_bf16(Bt[n][k], At[m][k], acc[ai][bj][m][n], 0, 0, 0); __builtin_amdgcn_s_setprio(0); } while (0)
; #define PG8_WAIT_V(n) asm volatile("s_waitcnt vmcnt(" #n ")" ::: "memory")
; #define PG8_WAIT_L(n) asm volatile("s_waitcnt lgkmcnt(" #n ")" ::: "memory")
; #define PG8_BAR __builtin_amdgcn_s_barrier()
; #define PG8_SCHED __builtin_amdgcn_sched_barrier(0)
; template <class Epi, class Sched, bool ALIGN_EPI = false, bool SP2 = false>
; __device__ __forceinline__ void gemm_phase(PG8_LAS unsigned char* lds, const Gemm g, const Sched& S, const Epi& E) {
;     ...
;             PG8_WAIT_V(8); PG8_WAIT_L(0); PG8_BAR; PG8_MMA(1, 0, At, B0); PG8_MMA(1, 1, At, B1); PG8_BAR; PG8_SCHED;
;             PG8_LDB(B0, 1, 0); PG8_LDB(B1, 1, 1); PG8_SCHED; PG8_LDA(At, 1, 0); PG8_STAGE(PG8_SA(0, 1), a2 + hstepA, voffA);
;             PG8_WAIT_V(8); PG8_WAIT_L(0); PG8_BAR; PG8_MMA(0, 0, At, B0); PG8_MMA(0, 1, At, B1); PG8_BAR; PG8_SCHED;
	s_waitcnt lgkmcnt(0)
	v_mfma_f32_16x16x32_bf16 v[60:63], v[146:149], v[178:181], v[60:63]
	v_mfma_f32_16x16x32_bf16 v[56:59], v[154:157], v[178:181], v[56:59]
	v_mfma_f32_16x16x32_bf16 v[52:55], v[146:149], v[186:189], v[52:55]
	v_mfma_f32_16x16x32_bf16 v[44:47], v[154:157], v[186:189], v[44:47]
	v_mfma_f32_16x16x32_bf16 v[36:39], v[146:149], v[194:197], v[36:39]
	v_mfma_f32_16x16x32_bf16 v[28:31], v[154:157], v[194:197], v[28:31]
	v_mfma_f32_16x16x32_bf16 v[20:23], v[146:149], v[202:205], v[20:23]
	v_mfma_f32_16x16x32_bf16 v[12:15], v[154:157], v[202:205], v[12:15]
	v_mfma_f32_16x16x32_bf16 v[60:63], v[150:153], v[182:185], v[60:63]
	v_mfma_f32_16x16x32_bf16 v[56:59], v[158:161], v[182:185], v[56:59]
	v_mfma_f32_16x16x32_bf16 v[52:55], v[150:153], v[190:193], v[52:55]
	v_mfma_f32_16x16x32_bf16 v[44:47], v[158:161], v[190:193], v[44:47]
	v_mfma_f32_16x16x32_bf16 v[36:39], v[150:153], v[198:201], v[36:39]
	v_mfma_f32_16x16x32_bf16 v[28:31], v[158:161], v[198:201], v[28:31]
	v_mfma_f32_16x16x32_bf16 v[20:23], v[150:153], v[210:213], v[20:23]
	v_mfma_f32_16x16x32_bf16 v[12:15], v[158:161], v[210:213], v[12:15]
	v_mfma_f32_16x16x32_bf16 v[48:51], v[162:165], v[178:181], v[48:51]
	v_mfma_f32_16x16x32_bf16 v[40:43], v[170:173], v[178:181], v[40:43]
	v_mfma_f32_16x16x32_bf16 v[32:35], v[162:165], v[186:189], v[32:35]
	v_mfma_f32_16x16x32_bf16 v[24:27], v[170:173], v[186:189], v[24:27]
	v_mfma_f32_16x16x32_bf16 v[16:19], v[162:165], v[194:197], v[16:19]
	v_mfma_f32_16x16x32_bf16 v[8:11], v[170:173], v[194:197], v[8:11]
	v_mfma_f32_16x16x32_bf16 v[4:7], v[162:165], v[202:205], v[4:7]
	v_mfma_f32_16x16x32_bf16 v[0:3], v[170:173], v[202:205], v[0:3]
	v_mfma_f32_16x16x32_bf16 v[48:51], v[166:169], v[182:185], v[48:51]
	v_mfma_f32_16x16x32_bf16 v[40:43], v[174:177], v[182:185], v[40:43]
	v_mfma_f32_16x16x32_bf16 v[32:35], v[166:169], v[190:193], v[32:35]
	v_mfma_f32_16x16x32_bf16 v[24:27], v[174:177], v[190:193], v[24:27]
	v_mfma_f32_16x16x32_bf16 v[16:19], v[166:169], v[198:201], v[16:19]
	v_mfma_f32_16x16x32_bf16 v[8:11], v[174:177], v[198:201], v[8:11]
	v_mfma_f32_16x16x32_bf16 v[4:7], v[166:169], v[210:213], v[4:7]
	v_mfma_f32_16x16x32_bf16 v[0:3], v[174:177], v[210:213], v[0:3]
	s_barrier
	s_add_i32 s28, 0, 0x18000
	v_add_u32_e32 v138, s28, v142
	s_add_i32 s29, 0, 0x1c000
	ds_read_b128 v[146:149], v138
	ds_read_b128 v[150:153], v138 offset:1024
	ds_read_b128 v[154:157], v138 offset:2048
	ds_read_b128 v[158:161], v138 offset:3072
	v_add_u32_e32 v138, s29, v142
	ds_read_b128 v[162:165], v138
	ds_read_b128 v[166:169], v138 offset:1024
	ds_read_b128 v[170:173], v138 offset:2048
	ds_read_b128 v[174:177], v138 offset:3072
	s_add_u32 s24, s24, 0x40000
	s_addc_u32 s25, s25, 0
	s_mov_b32 m0, s35
	v_lshl_add_u64 v[226:227], s[24:25], 0, v[132:133]
	ds_read_b128 v[178:181], v144 offset:32768
	ds_read_b128 v[182:185], v144 offset:33792
	ds_read_b128 v[186:189], v144 offset:34816
	ds_read_b128 v[190:193], v144 offset:35840
	ds_read_b128 v[194:197], v144 offset:36864
	ds_read_b128 v[198:201], v144 offset:37888
	ds_read_b128 v[202:205], v144 offset:38912
	ds_read_b128 v[210:213], v144 offset:39936
	global_load_lds_dwordx4 v[226:227], off
	v_lshl_add_u64 v[226:227], s[24:25], 0, v[130:131]
	s_mov_b32 m0, s39
	s_nop 0
	global_load_lds_dwordx4 v[226:227], off
	s_waitcnt vmcnt(8)
	s_waitcnt lgkmcnt(0)
	s_barrier
	s_waitcnt lgkmcnt(0)
	v_mfma_f32_16x16x32_bf16 v[124:127], v[146:149], v[178:181], v[124:127]
	v_mfma_f32_16x16x32_bf16 v[120:123], v[154:157], v[178:181], v[120:123]
	v_mfma_f32_16x16x32_bf16 v[116:119], v[146:149], v[186:189], v[116:119]
	v_mfma_f32_16x16x32_bf16 v[108:111], v[154:157], v[186:189], v[108:111]
	v_mfma_f32_16x16x32_bf16 v[100:103], v[146:149], v[194:197], v[100:103]
	v_mfma_f32_16x16x32_bf16 v[92:95], v[154:157], v[194:197], v[92:95]
	v_mfma_f32_16x16x32_bf16 v[84:87], v[146:149], v[202:205], v[84:87]
	v_mfma_f32_16x16x32_bf16 v[76:79], v[154:157], v[202:205], v[76:79]
	v_mfma_f32_16x16x32_bf16 v[124:127], v[150:153], v[182:185], v[124:127]
	v_mfma_f32_16x16x32_bf16 v[120:123], v[158:161], v[182:185], v[120:123]
	v_mfma_f32_16x16x32_bf16 v[116:119], v[150:153], v[190:193], v[116:119]
	v_mfma_f32_16x16x32_bf16 v[108:111], v[158:161], v[190:193], v[108:111]
	v_mfma_f32_16x16x32_bf16 v[100:103], v[150:153], v[198:201], v[100:103]
	v_mfma_f32_16x16x32_bf16 v[92:95], v[158:161], v[198:201], v[92:95]
	v_mfma_f32_16x16x32_bf16 v[84:87], v[150:153], v[210:213], v[84:87]
	v_mfma_f32_16x16x32_bf16 v[76:79], v[158:161], v[210:213], v[76:79]
	v_mfma_f32_16x16x32_bf16 v[112:115], v[162:165], v[178:181], v[112:115]
	v_mfma_f32_16x16x32_bf16 v[104:107], v[170:173], v[178:181], v[104:107]
	v_mfma_f32_16x16x32_bf16 v[96:99], v[162:165], v[186:189], v[96:99]
	v_mfma_f32_16x16x32_bf16 v[88:91], v[170:173], v[186:189], v[88:91]
	v_mfma_f32_16x16x32_bf16 v[80:83], v[162:165], v[194:197], v[80:83]
	v_mfma_f32_16x16x32_bf16 v[72:75], v[170:173], v[194:197], v[72:75]
	v_mfma_f32_16x16x32_bf16 v[68:71], v[162:165], v[202:205], v[68:71]
	v_mfma_f32_16x16x32_bf16 v[64:67], v[170:173], v[202:205], v[64:67]
	v_mfma_f32_16x16x32_bf16 v[112:115], v[166:169], v[182:185], v[112:115]
	v_mfma_f32_16x16x32_bf16 v[104:107], v[174:177], v[182:185], v[104:107]
	v_mfma_f32_16x16x32_bf16 v[96:99], v[166:169], v[190:193], v[96:99]
	v_mfma_f32_16x16x32_bf16 v[88:91], v[174:177], v[190:193], v[88:91]
	v_mfma_f32_16x16x32_bf16 v[80:83], v[166:169], v[198:201], v[80:83]
	v_mfma_f32_16x16x32_bf16 v[72:75], v[174:177], v[198:201], v[72:75]
	v_mfma_f32_16x16x32_bf16 v[68:71], v[166:169], v[210:213], v[68:71]
	v_mfma_f32_16x16x32_bf16 v[64:67], v[174:177], v[210:213], v[64:67]
	s_barrier
; #define PG8_STAGE(bufoff, gbase, voff) do { _Pragma("unroll") for (int _i = 0; _i < 2; ++_i) \
;         __builtin_amdgcn_global_load_lds((const unsigned*)((const char*)(gbase) + (voff)[_i]), (PG8_LAS unsigned*)(lds + (bufoff) + ldsw + _i * 8192), 16, 0, 0); } while (0)
; #define PG8_LDA(dst, b, h) do { _Pragma("unroll") for (int m = 0; m < 4; ++m) _Pragma("unroll") for (int k = 0; k < 2; ++k) dst[m][k] = *(const PG8_LAS bf16x8*)(lds + PG8_SA(b, h) + aoff + m * 2048 + k * 1024); } while (0)
; #define PG8_MMA(ai, bj, At, Bt) do { __builtin_amdgcn_s_setprio(1); _Pragma("unroll") for (int m = 0; m < 4; ++m) _Pragma("unroll") for (int n = 0; n < 2; ++n) _Pragma("unroll") for (int k = 0; k < 2; ++k) \
;         acc[ai][bj][m][n] = __builtin_amdgcn_mfma_f32_16x16x32_bf16(Bt[n][k], At[m][k], acc[ai][bj][m][n], 0, 0, 0); __builtin_amdgcn_s_setprio(0); } while (0)
; #define PG8_WAIT_V(n) asm volatile("s_waitcnt vmcnt(" #n ")" ::: "memory")
; #define PG8_WAIT_L(n) asm volatile("s_waitcnt lgkmcnt(" #n ")" ::: "memory")
; #define PG8_BAR __builtin_amdgcn_s_barrier()
; #define PG8_SCHED __builtin_amdgcn_sched_barrier(0)
; template <class Epi, class Sched, bool ALIGN_EPI = false, bool SP2 = false>
; __device__ __forceinline__ void gemm_phase(PG8_LAS unsigned char* lds, const Gemm g, const Sched& S, const Epi& E) {
;     ...
;         for (int t = 0; t < nt; t += 2) {
;             const bool last = (t == nt - 2);
;     ...
;             PG8_LDA(At, 1, 1); PG8_STAGE(PG8_SB(1, 0), b3, voffB); PG8_STAGE(PG8_SB(1, 1), b3 + hstepB, voffB); PG8_STAGE(PG8_SA(1, 0), a3, voffA);
;             PG8_WAIT_V(8); PG8_WAIT_L(0); PG8_BAR; PG8_MMA(1, 0, At, B0); PG8_MMA(1, 1, At, B1); PG8_BAR; PG8_SCHED;
	s_add_i32 s24, s28, s18
	v_lshl_add_u64 v[140:141], v[140:141], 0, s[10:11]
	s_mov_b32 m0, s24
	ds_read_b128 v[178:181], v144 offset:49152
	ds_read_b128 v[182:185], v144 offset:50176
	ds_read_b128 v[186:189], v144 offset:51200
	ds_read_b128 v[190:193], v144 offset:52224
	ds_read_b128 v[194:197], v144 offset:53248
	ds_read_b128 v[198:201], v144 offset:54272
	ds_read_b128 v[202:205], v144 offset:55296
	ds_read_b128 v[210:213], v144 offset:56320
	global_load_lds_dwordx4 v[140:141], off
	s_add_i32 m0, s24, 0x2000
	s_add_u32 s22, s22, 0x40080
	v_lshl_add_u64 v[140:141], v[206:207], 0, s[10:11]
	s_addc_u32 s23, s23, 0
	s_add_i32 s24, s29, s18
	global_load_lds_dwordx4 v[140:141], off
	v_lshl_add_u64 v[140:141], s[22:23], 0, v[208:209]
	s_mov_b32 m0, s24
	s_nop 0
	global_load_lds_dwordx4 v[140:141], off
	v_lshl_add_u64 v[140:141], s[22:23], 0, v[128:129]
	s_add_i32 m0, s24, 0x2000
	s_nop 0
	global_load_lds_dwordx4 v[140:141], off
	v_lshl_add_u64 v[140:141], v[222:223], 0, s[10:11]
	s_mov_b32 m0, s12
	s_nop 0
	global_load_lds_dwordx4 v[140:141], off
	v_lshl_add_u64 v[140:141], v[224:225], 0, s[10:11]
	s_mov_b32 m0, s43
	s_nop 0
	global_load_lds_dwordx4 v[140:141], off
	s_waitcnt vmcnt(8)
	s_waitcnt lgkmcnt(0)
	s_barrier
	s_waitcnt lgkmcnt(0)
	v_mfma_f32_16x16x32_bf16 v[60:63], v[146:149], v[178:181], v[60:63]
	v_mfma_f32_16x16x32_bf16 v[56:59], v[154:157], v[178:181], v[56:59]
	v_mfma_f32_16x16x32_bf16 v[52:55], v[146:149], v[186:189], v[52:55]
	v_mfma_f32_16x16x32_bf16 v[44:47], v[154:157], v[186:189], v[44:47]
	v_mfma_f32_16x16x32_bf16 v[36:39], v[146:149], v[194:197], v[36:39]
	v_mfma_f32_16x16x32_bf16 v[28:31], v[154:157], v[194:197], v[28:31]
	v_mfma_f32_16x16x32_bf16 v[20:23], v[146:149], v[202:205], v[20:23]
	v_mfma_f32_16x16x32_bf16 v[12:15], v[154:157], v[202:205], v[12:15]
	v_mfma_f32_16x16x32_bf16 v[60:63], v[150:153], v[182:185], v[60:63]
	v_mfma_f32_16x16x32_bf16 v[56:59], v[158:161], v[182:185], v[56:59]
	v_mfma_f32_16x16x32_bf16 v[52:55], v[150:153], v[190:193], v[52:55]
	v_mfma_f32_16x16x32_bf16 v[44:47], v[158:161], v[190:193], v[44:47]
	v_mfma_f32_16x16x32_bf16 v[36:39], v[150:153], v[198:201], v[36:39]
	v_mfma_f32_16x16x32_bf16 v[28:31], v[158:161], v[198:201], v[28:31]
	v_mfma_f32_16x16x32_bf16 v[20:23], v[150:153], v[210:213], v[20:23]
	v_mfma_f32_16x16x32_bf16 v[12:15], v[158:161], v[210:213], v[12:15]
	v_mfma_f32_16x16x32_bf16 v[48:51], v[162:165], v[178:181], v[48:51]
	v_mfma_f32_16x16x32_bf16 v[40:43], v[170:173], v[178:181], v[40:43]
	v_mfma_f32_16x16x32_bf16 v[32:35], v[162:165], v[186:189], v[32:35]
	v_mfma_f32_16x16x32_bf16 v[24:27], v[170:173], v[186:189], v[24:27]
	v_mfma_f32_16x16x32_bf16 v[16:19], v[162:165], v[194:197], v[16:19]
	v_mfma_f32_16x16x32_bf16 v[8:11], v[170:173], v[194:197], v[8:11]
	v_mfma_f32_16x16x32_bf16 v[4:7], v[162:165], v[202:205], v[4:7]
	v_mfma_f32_16x16x32_bf16 v[0:3], v[170:173], v[202:205], v[0:3]
	v_mfma_f32_16x16x32_bf16 v[48:51], v[166:169], v[182:185], v[48:51]
	v_mfma_f32_16x16x32_bf16 v[40:43], v[174:177], v[182:185], v[40:43]
	v_mfma_f32_16x16x32_bf16 v[32:35], v[166:169], v[190:193], v[32:35]
	v_mfma_f32_16x16x32_bf16 v[24:27], v[174:177], v[190:193], v[24:27]
	v_mfma_f32_16x16x32_bf16 v[16:19], v[166:169], v[198:201], v[16:19]
	v_mfma_f32_16x16x32_bf16 v[8:11], v[174:177], v[198:201], v[8:11]
	v_mfma_f32_16x16x32_bf16 v[4:7], v[166:169], v[210:213], v[4:7]
	v_mfma_f32_16x16x32_bf16 v[0:3], v[174:177], v[210:213], v[0:3]
	s_barrier
	s_add_i32 s51, s51, 2
	s_add_u32 s0, s0, 0x100
	s_addc_u32 s1, s1, 0
	s_add_u32 s49, s49, 0x100
	s_addc_u32 s50, s50, 0
	s_cmp_gt_u32 s51, 13
	s_cbranch_scc0 .LBB0_338
	s_and_b64 vcc, exec, s[8:9]
	s_cbranch_vccz .LBB0_341
	s_barrier

; #define PG8_STAGE(bufoff, gbase, voff) do { _Pragma("unroll") for (int _i = 0; _i < 2; ++_i) \
;         __builtin_amdgcn_global_load_lds((const unsigned*)((const char*)(gbase) + (voff)[_i]), (PG8_LAS unsigned*)(lds + (bufoff) + ldsw + _i * 8192), 16, 0, 0); } while (0)
; #define PG8_LDA(dst, b, h) do { _Pragma("unroll") for (int m = 0; m < 4; ++m) _Pragma("unroll") for (int k = 0; k < 2; ++k) dst[m][k] = *(const PG8_LAS bf16x8*)(lds + PG8_SA(b, h) + aoff + m * 2048 + k * 1024); } while (0)
; #define PG8_LDB(dst, b, h) do { _Pragma("unroll") for (int n = 0; n < 2; ++n) _Pragma("unroll") for (int k = 0; k < 2; ++k) dst[n][k] = *(const PG8_LAS bf16x8*)(lds + PG8_SB(b, h) + boff + n * 2048 + k * 1024); } while (0)
; #define PG8_WAIT_V(n) asm volatile("s_waitcnt vmcnt(" #n ")" ::: "memory")
; #define PG8_WAIT_L(n) asm volatile("s_waitcnt lgkmcnt(" #n ")" ::: "memory")
; #define PG8_BAR __builtin_amdgcn_s_barrier()
; #define PG8_SCHED __builtin_amdgcn_sched_barrier(0)
; template <class Epi, class Sched, bool ALIGN_EPI = false, bool SP2 = false>
; __device__ __forceinline__ void gemm_phase(PG8_LAS unsigned char* lds, const Gemm g, const Sched& S, const Epi& E) {
;     ...
;         const char* nA = has_next ? (const char*)g.A + (size_t)nxt.pm * tstepA : cA; const char* nB = has_next ? (const char*)g.Bt + (size_t)nxt.pn * tstepB : cB;
;         for (int t = 0; t < nt; t += 2) {
;             const bool last = (t == nt - 2);
;             const char* a1 = cA + (size_t)(t + 1) * kstep;
;             const char* a2 = last ? nA : cA + (size_t)(t + 2) * kstep; const char* b2 = last ? nB : cB + (size_t)(t + 2) * kstep;
;             const char* a3 = a2 + kstep; const char* b3 = b2 + kstep;
;             if (last && has_next) S.a_ready(nxt);
;             if constexpr (SP2) {
;             PG8_LDB(B0, 0, 0); PG8_LDB(B1, 0, 1); PG8_SCHED; PG8_LDA(At, 0, 0); PG8_STAGE(PG8_SA(1, 1), a1 + hstepA, voffA);
;             PG8_WAIT_V(8); PG8_WAIT_L(0); PG8_BAR; PG8_MMA(0, 0, At, B0); PG8_MMA(0, 1, At, B1); PG8_BAR; PG8_SCHED;
;             PG8_LDA(At, 0, 1); PG8_STAGE(PG8_SB(0, 0), b2, voffB); PG8_STAGE(PG8_SB(0, 1), b2 + hstepB, voffB); PG8_STAGE(PG8_SA(0, 0), a2, voffA);
;             PG8_WAIT_V(8); PG8_WAIT_L(0); PG8_BAR; PG8_MMA(1, 0, At, B0); PG8_MMA(1, 1, At, B1); PG8_BAR; PG8_SCHED;
.LBB0_354:
	s_add_u32 s22, s44, 0xfffc0080
	s_addc_u32 s23, s45, -1
	s_add_i32 s28, 0, 0x10000
	s_cmp_eq_u32 s51, 12
	s_cselect_b32 s47, s14, s23
	s_cselect_b32 s46, s15, s22
	s_cselect_b32 s23, s1, s50
	s_cselect_b32 s22, s41, s49
	s_add_i32 s29, 0, 0x14000
	v_add_u32_e32 v154, s28, v139
	v_add_u32_e32 v170, s29, v139
	ds_read_b128 v[142:145], v154
	ds_read_b128 v[146:149], v154 offset:1024
	ds_read_b128 v[150:153], v154 offset:2048
	ds_read_b128 v[154:157], v154 offset:3072
	ds_read_b128 v[158:161], v170
	ds_read_b128 v[162:165], v170 offset:1024
	ds_read_b128 v[166:169], v170 offset:2048
	ds_read_b128 v[170:173], v170 offset:3072
	v_lshl_add_u64 v[206:207], s[44:45], 0, v[134:135]
	s_add_i32 m0, s21, 0xc000
	ds_read_b128 v[174:177], v141
	ds_read_b128 v[178:181], v141 offset:1024
	ds_read_b128 v[182:185], v141 offset:2048
	ds_read_b128 v[186:189], v141 offset:3072
	ds_read_b128 v[190:193], v141 offset:4096
	ds_read_b128 v[194:197], v141 offset:5120
	ds_read_b128 v[198:201], v141 offset:6144
	ds_read_b128 v[202:205], v141 offset:7168
	global_load_lds_dwordx4 v[206:207], off
	v_lshl_add_u64 v[206:207], s[44:45], 0, v[136:137]
	s_add_i32 m0, s21, 0xe000
	s_nop 0
	global_load_lds_dwordx4 v[206:207], off
	s_waitcnt vmcnt(8)
	s_waitcnt lgkmcnt(0)
	s_barrier
	s_waitcnt lgkmcnt(0)
	v_mfma_f32_16x16x32_bf16 v[124:127], v[142:145], v[174:177], v[124:127]
	v_mfma_f32_16x16x32_bf16 v[120:123], v[150:153], v[174:177], v[120:123]
	v_mfma_f32_16x16x32_bf16 v[116:119], v[142:145], v[182:185], v[116:119]
	v_mfma_f32_16x16x32_bf16 v[112:115], v[150:153], v[182:185], v[112:115]
	v_mfma_f32_16x16x32_bf16 v[100:103], v[142:145], v[190:193], v[100:103]
	v_mfma_f32_16x16x32_bf16 v[96:99], v[150:153], v[190:193], v[96:99]
	v_mfma_f32_16x16x32_bf16 v[84:87], v[142:145], v[198:201], v[84:87]
	v_mfma_f32_16x16x32_bf16 v[80:83], v[150:153], v[198:201], v[80:83]
	v_mfma_f32_16x16x32_bf16 v[124:127], v[146:149], v[178:181], v[124:127]
	v_mfma_f32_16x16x32_bf16 v[120:123], v[154:157], v[178:181], v[120:123]
	v_mfma_f32_16x16x32_bf16 v[116:119], v[146:149], v[186:189], v[116:119]
	v_mfma_f32_16x16x32_bf16 v[112:115], v[154:157], v[186:189], v[112:115]
	v_mfma_f32_16x16x32_bf16 v[100:103], v[146:149], v[194:197], v[100:103]
	v_mfma_f32_16x16x32_bf16 v[96:99], v[154:157], v[194:197], v[96:99]
	v_mfma_f32_16x16x32_bf16 v[84:87], v[146:149], v[202:205], v[84:87]
	v_mfma_f32_16x16x32_bf16 v[80:83], v[154:157], v[202:205], v[80:83]
	v_mfma_f32_16x16x32_bf16 v[108:111], v[158:161], v[174:177], v[108:111]
	v_mfma_f32_16x16x32_bf16 v[104:107], v[166:169], v[174:177], v[104:107]
	v_mfma_f32_16x16x32_bf16 v[92:95], v[158:161], v[182:185], v[92:95]
	v_mfma_f32_16x16x32_bf16 v[88:91], v[166:169], v[182:185], v[88:91]
	v_mfma_f32_16x16x32_bf16 v[76:79], v[158:161], v[190:193], v[76:79]
	v_mfma_f32_16x16x32_bf16 v[72:75], v[166:169], v[190:193], v[72:75]
	v_mfma_f32_16x16x32_bf16 v[68:71], v[158:161], v[198:201], v[68:71]
	v_mfma_f32_16x16x32_bf16 v[64:67], v[166:169], v[198:201], v[64:67]
	v_mfma_f32_16x16x32_bf16 v[108:111], v[162:165], v[178:181], v[108:111]
	v_mfma_f32_16x16x32_bf16 v[104:107], v[170:173], v[178:181], v[104:107]
	v_mfma_f32_16x16x32_bf16 v[92:95], v[162:165], v[186:189], v[92:95]
	v_mfma_f32_16x16x32_bf16 v[88:91], v[170:173], v[186:189], v[88:91]
	v_mfma_f32_16x16x32_bf16 v[76:79], v[162:165], v[194:197], v[76:79]
	v_mfma_f32_16x16x32_bf16 v[72:75], v[170:173], v[194:197], v[72:75]
	v_mfma_f32_16x16x32_bf16 v[68:71], v[162:165], v[202:205], v[68:71]
	v_mfma_f32_16x16x32_bf16 v[64:67], v[170:173], v[202:205], v[64:67]
	s_barrier
	s_add_i32 s28, s28, s18
	v_lshl_add_u64 v[206:207], s[22:23], 0, v[208:209]
	s_mov_b32 m0, s28
	ds_read_b128 v[174:177], v141 offset:16384
	ds_read_b128 v[178:181], v141 offset:17408
	ds_read_b128 v[182:185], v141 offset:18432
	ds_read_b128 v[186:189], v141 offset:19456
	ds_read_b128 v[190:193], v141 offset:20480
	ds_read_b128 v[194:197], v141 offset:21504
	ds_read_b128 v[198:201], v141 offset:22528
	ds_read_b128 v[202:205], v141 offset:23552
	global_load_lds_dwordx4 v[206:207], off
	s_add_i32 m0, s28, 0x2000
	s_add_u32 s52, s22, 0x40000
	v_lshl_add_u64 v[210:211], s[22:23], 0, v[128:129]
	s_addc_u32 s53, s23, 0
	s_add_i32 s28, s29, s18
	global_load_lds_dwordx4 v[210:211], off
	v_lshl_add_u64 v[212:213], s[52:53], 0, v[208:209]
	s_mov_b32 m0, s28
	v_lshl_add_u64 v[222:223], s[46:47], 0, v[130:131]
	global_load_lds_dwordx4 v[212:213], off
	v_lshl_add_u64 v[212:213], s[52:53], 0, v[128:129]
	s_add_i32 m0, s28, 0x2000
	s_nop 0
	global_load_lds_dwordx4 v[212:213], off
	v_lshl_add_u64 v[212:213], s[46:47], 0, v[132:133]
	s_mov_b32 m0, s21
	s_nop 0
	global_load_lds_dwordx4 v[212:213], off
	s_mov_b32 m0, s12
	s_nop 0
	global_load_lds_dwordx4 v[222:223], off
	s_waitcnt vmcnt(8)
	s_waitcnt lgkmcnt(0)
	s_barrier
; #define PG8_STAGE(bufoff, gbase, voff) do { _Pragma("unroll") for (int _i = 0; _i < 2; ++_i) \
;         __builtin_amdgcn_global_load_lds((const unsigned*)((const char*)(gbase) + (voff)[_i]), (PG8_LAS unsigned*)(lds + (bufoff) + ldsw + _i * 8192), 16, 0, 0); } while (0)
; #define PG8_LDA(dst, b, h) do { _Pragma("unroll") for (int m = 0; m < 4; ++m) _Pragma("unroll") for (int k = 0; k < 2; ++k) dst[m][k] = *(const PG8_LAS bf16x8*)(lds + PG8_SA(b, h) + aoff + m * 2048 + k * 1024); } while (0)
; #define PG8_LDB(dst, b, h) do { _Pragma("unroll") for (int n = 0; n < 2; ++n) _Pragma("unroll") for (int k = 0; k < 2; ++k) dst[n][k] = *(const PG8_LAS bf16x8*)(lds + PG8_SB(b, h) + boff + n * 2048 + k * 1024); } while (0)
; #define PG8_MMA(ai, bj, At, Bt) do { __builtin_amdgcn_s_setprio(1); _Pragma("unroll") for (int m = 0; m < 4; ++m) _Pragma("unroll") for (int n = 0; n < 2; ++n) _Pragma("unroll") for (int k = 0; k < 2; ++k) \
;         acc[ai][bj][m][n] = __builtin_amdgcn_mfma_f32_16x16x32_bf16(Bt[n][k], At[m][k], acc[ai][bj][m][n], 0, 0, 0); __builtin_amdgcn_s_setprio(0); } while (0)
; #define PG8_WAIT_V(n) asm volatile("s_waitcnt vmcnt(" #n ")" ::: "memory")
; #define PG8_WAIT_L(n) asm volatile("s_waitcnt lgkmcnt(" #n ")" ::: "memory")
; #define PG8_BAR __builtin_amdgcn_s_barrier()
; #define PG8_SCHED __builtin_amdgcn_sched_barrier(0)
; template <class Epi, class Sched, bool ALIGN_EPI = false, bool SP2 = false>
; __device__ __forceinline__ void gemm_phase(PG8_LAS unsigned char* lds, const Gemm g, const Sched& S, const Epi& E) {
;     ...
;             PG8_WAIT_V(8); PG8_WAIT_L(0); PG8_BAR; PG8_MMA(1, 0, At, B0); PG8_MMA(1, 1, At, B1); PG8_BAR; PG8_SCHED;
;             PG8_LDB(B0, 1, 0); PG8_LDB(B1, 1, 1); PG8_SCHED; PG8_LDA(At, 1, 0); PG8_STAGE(PG8_SA(0, 1), a2 + hstepA, voffA);
;             PG8_WAIT_V(8); PG8_WAIT_L(0); PG8_BAR; PG8_MMA(0, 0, At, B0); PG8_MMA(0, 1, At, B1); PG8_BAR; PG8_SCHED;
	s_waitcnt lgkmcnt(0)
	v_mfma_f32_16x16x32_bf16 v[60:63], v[142:145], v[174:177], v[60:63]
	v_mfma_f32_16x16x32_bf16 v[56:59], v[150:153], v[174:177], v[56:59]
	v_mfma_f32_16x16x32_bf16 v[52:55], v[142:145], v[182:185], v[52:55]
	v_mfma_f32_16x16x32_bf16 v[48:51], v[150:153], v[182:185], v[48:51]
	v_mfma_f32_16x16x32_bf16 v[36:39], v[142:145], v[190:193], v[36:39]
	v_mfma_f32_16x16x32_bf16 v[32:35], v[150:153], v[190:193], v[32:35]
	v_mfma_f32_16x16x32_bf16 v[20:23], v[142:145], v[198:201], v[20:23]
	v_mfma_f32_16x16x32_bf16 v[16:19], v[150:153], v[198:201], v[16:19]
	v_mfma_f32_16x16x32_bf16 v[60:63], v[146:149], v[178:181], v[60:63]
	v_mfma_f32_16x16x32_bf16 v[56:59], v[154:157], v[178:181], v[56:59]
	v_mfma_f32_16x16x32_bf16 v[52:55], v[146:149], v[186:189], v[52:55]
	v_mfma_f32_16x16x32_bf16 v[48:51], v[154:157], v[186:189], v[48:51]
	v_mfma_f32_16x16x32_bf16 v[36:39], v[146:149], v[194:197], v[36:39]
	v_mfma_f32_16x16x32_bf16 v[32:35], v[154:157], v[194:197], v[32:35]
	v_mfma_f32_16x16x32_bf16 v[20:23], v[146:149], v[202:205], v[20:23]
	v_mfma_f32_16x16x32_bf16 v[16:19], v[154:157], v[202:205], v[16:19]
	v_mfma_f32_16x16x32_bf16 v[44:47], v[158:161], v[174:177], v[44:47]
	v_mfma_f32_16x16x32_bf16 v[40:43], v[166:169], v[174:177], v[40:43]
	v_mfma_f32_16x16x32_bf16 v[28:31], v[158:161], v[182:185], v[28:31]
	v_mfma_f32_16x16x32_bf16 v[24:27], v[166:169], v[182:185], v[24:27]
	v_mfma_f32_16x16x32_bf16 v[12:15], v[158:161], v[190:193], v[12:15]
	v_mfma_f32_16x16x32_bf16 v[8:11], v[166:169], v[190:193], v[8:11]
	v_mfma_f32_16x16x32_bf16 v[4:7], v[158:161], v[198:201], v[4:7]
	v_mfma_f32_16x16x32_bf16 v[0:3], v[166:169], v[198:201], v[0:3]
	v_mfma_f32_16x16x32_bf16 v[44:47], v[162:165], v[178:181], v[44:47]
	v_mfma_f32_16x16x32_bf16 v[40:43], v[170:173], v[178:181], v[40:43]
	v_mfma_f32_16x16x32_bf16 v[28:31], v[162:165], v[186:189], v[28:31]
	v_mfma_f32_16x16x32_bf16 v[24:27], v[170:173], v[186:189], v[24:27]
	v_mfma_f32_16x16x32_bf16 v[12:15], v[162:165], v[194:197], v[12:15]
	v_mfma_f32_16x16x32_bf16 v[8:11], v[170:173], v[194:197], v[8:11]
	v_mfma_f32_16x16x32_bf16 v[4:7], v[162:165], v[202:205], v[4:7]
	v_mfma_f32_16x16x32_bf16 v[0:3], v[170:173], v[202:205], v[0:3]
	s_barrier
	s_add_i32 s28, 0, 0x18000
	s_add_i32 s29, 0, 0x1c000
	v_add_u32_e32 v154, s28, v139
	v_add_u32_e32 v170, s29, v139
	ds_read_b128 v[142:145], v154
	ds_read_b128 v[146:149], v154 offset:1024
	ds_read_b128 v[150:153], v154 offset:2048
	ds_read_b128 v[154:157], v154 offset:3072
	ds_read_b128 v[158:161], v170
	ds_read_b128 v[162:165], v170 offset:1024
	ds_read_b128 v[166:169], v170 offset:2048
	ds_read_b128 v[170:173], v170 offset:3072
	s_add_u32 s46, s46, 0x40000
	s_addc_u32 s47, s47, 0
	s_mov_b32 m0, s26
	v_lshl_add_u64 v[224:225], s[46:47], 0, v[132:133]
	ds_read_b128 v[174:177], v141 offset:32768
	ds_read_b128 v[178:181], v141 offset:33792
	ds_read_b128 v[182:185], v141 offset:34816
	ds_read_b128 v[186:189], v141 offset:35840
	ds_read_b128 v[190:193], v141 offset:36864
	ds_read_b128 v[194:197], v141 offset:37888
	ds_read_b128 v[198:201], v141 offset:38912
	ds_read_b128 v[202:205], v141 offset:39936
	global_load_lds_dwordx4 v[224:225], off
	v_lshl_add_u64 v[224:225], s[46:47], 0, v[130:131]
	s_mov_b32 m0, s34
	s_nop 0
	global_load_lds_dwordx4 v[224:225], off
	s_waitcnt vmcnt(8)
	s_waitcnt lgkmcnt(0)
	s_barrier
	s_waitcnt lgkmcnt(0)
	v_mfma_f32_16x16x32_bf16 v[124:127], v[142:145], v[174:177], v[124:127]
	v_mfma_f32_16x16x32_bf16 v[120:123], v[150:153], v[174:177], v[120:123]
	v_mfma_f32_16x16x32_bf16 v[116:119], v[142:145], v[182:185], v[116:119]
	v_mfma_f32_16x16x32_bf16 v[112:115], v[150:153], v[182:185], v[112:115]
	v_mfma_f32_16x16x32_bf16 v[100:103], v[142:145], v[190:193], v[100:103]
	v_mfma_f32_16x16x32_bf16 v[96:99], v[150:153], v[190:193], v[96:99]
	v_mfma_f32_16x16x32_bf16 v[84:87], v[142:145], v[198:201], v[84:87]
	v_mfma_f32_16x16x32_bf16 v[80:83], v[150:153], v[198:201], v[80:83]
	v_mfma_f32_16x16x32_bf16 v[124:127], v[146:149], v[178:181], v[124:127]
	v_mfma_f32_16x16x32_bf16 v[120:123], v[154:157], v[178:181], v[120:123]
	v_mfma_f32_16x16x32_bf16 v[116:119], v[146:149], v[186:189], v[116:119]
	v_mfma_f32_16x16x32_bf16 v[112:115], v[154:157], v[186:189], v[112:115]
	v_mfma_f32_16x16x32_bf16 v[100:103], v[146:149], v[194:197], v[100:103]
	v_mfma_f32_16x16x32_bf16 v[96:99], v[154:157], v[194:197], v[96:99]
	v_mfma_f32_16x16x32_bf16 v[84:87], v[146:149], v[202:205], v[84:87]
	v_mfma_f32_16x16x32_bf16 v[80:83], v[154:157], v[202:205], v[80:83]
	v_mfma_f32_16x16x32_bf16 v[108:111], v[158:161], v[174:177], v[108:111]
	v_mfma_f32_16x16x32_bf16 v[104:107], v[166:169], v[174:177], v[104:107]
	v_mfma_f32_16x16x32_bf16 v[92:95], v[158:161], v[182:185], v[92:95]
	v_mfma_f32_16x16x32_bf16 v[88:91], v[166:169], v[182:185], v[88:91]
	v_mfma_f32_16x16x32_bf16 v[76:79], v[158:161], v[190:193], v[76:79]
	v_mfma_f32_16x16x32_bf16 v[72:75], v[166:169], v[190:193], v[72:75]
	v_mfma_f32_16x16x32_bf16 v[68:71], v[158:161], v[198:201], v[68:71]
	v_mfma_f32_16x16x32_bf16 v[64:67], v[166:169], v[198:201], v[64:67]
	v_mfma_f32_16x16x32_bf16 v[108:111], v[162:165], v[178:181], v[108:111]
	v_mfma_f32_16x16x32_bf16 v[104:107], v[170:173], v[178:181], v[104:107]
	v_mfma_f32_16x16x32_bf16 v[92:95], v[162:165], v[186:189], v[92:95]
	v_mfma_f32_16x16x32_bf16 v[88:91], v[170:173], v[186:189], v[88:91]
	v_mfma_f32_16x16x32_bf16 v[76:79], v[162:165], v[194:197], v[76:79]
	v_mfma_f32_16x16x32_bf16 v[72:75], v[170:173], v[194:197], v[72:75]
	v_mfma_f32_16x16x32_bf16 v[68:71], v[162:165], v[202:205], v[68:71]
	v_mfma_f32_16x16x32_bf16 v[64:67], v[170:173], v[202:205], v[64:67]
	s_barrier
; #define PG8_STAGE(bufoff, gbase, voff) do { _Pragma("unroll") for (int _i = 0; _i < 2; ++_i) \
;         __builtin_amdgcn_global_load_lds((const unsigned*)((const char*)(gbase) + (voff)[_i]), (PG8_LAS unsigned*)(lds + (bufoff) + ldsw + _i * 8192), 16, 0, 0); } while (0)
; #define PG8_LDA(dst, b, h) do { _Pragma("unroll") for (int m = 0; m < 4; ++m) _Pragma("unroll") for (int k = 0; k < 2; ++k) dst[m][k] = *(const PG8_LAS bf16x8*)(lds + PG8_SA(b, h) + aoff + m * 2048 + k * 1024); } while (0)
; #define PG8_MMA(ai, bj, At, Bt) do { __builtin_amdgcn_s_setprio(1); _Pragma("unroll") for (int m = 0; m < 4; ++m) _Pragma("unroll") for (int n = 0; n < 2; ++n) _Pragma("unroll") for (int k = 0; k < 2; ++k) \
;         acc[ai][bj][m][n] = __builtin_amdgcn_mfma_f32_16x16x32_bf16(Bt[n][k], At[m][k], acc[ai][bj][m][n], 0, 0, 0); __builtin_amdgcn_s_setprio(0); } while (0)
; #define PG8_WAIT_V(n) asm volatile("s_waitcnt vmcnt(" #n ")" ::: "memory")
; #define PG8_WAIT_L(n) asm volatile("s_waitcnt lgkmcnt(" #n ")" ::: "memory")
; #define PG8_BAR __builtin_amdgcn_s_barrier()
; #define PG8_SCHED __builtin_amdgcn_sched_barrier(0)
; template <class Epi, class Sched, bool ALIGN_EPI = false, bool SP2 = false>
; __device__ __forceinline__ void gemm_phase(PG8_LAS unsigned char* lds, const Gemm g, const Sched& S, const Epi& E) {
;     ...
;             PG8_LDA(At, 1, 1); PG8_STAGE(PG8_SB(1, 0), b3, voffB); PG8_STAGE(PG8_SB(1, 1), b3 + hstepB, voffB); PG8_STAGE(PG8_SA(1, 0), a3, voffA);
;             PG8_WAIT_V(8); PG8_WAIT_L(0); PG8_BAR; PG8_MMA(1, 0, At, B0); PG8_MMA(1, 1, At, B1); PG8_BAR; PG8_SCHED;
;     ...
;         }
;         if constexpr (ALIGN_EPI) { if (wr == 0) PG8_BAR; }
	s_add_i32 s28, s28, s18
	v_lshl_add_u64 v[206:207], v[206:207], 0, s[10:11]
	s_mov_b32 m0, s28
	ds_read_b128 v[174:177], v141 offset:49152
	ds_read_b128 v[178:181], v141 offset:50176
	ds_read_b128 v[182:185], v141 offset:51200
	ds_read_b128 v[186:189], v141 offset:52224
	ds_read_b128 v[190:193], v141 offset:53248
	ds_read_b128 v[194:197], v141 offset:54272
	ds_read_b128 v[198:201], v141 offset:55296
	ds_read_b128 v[202:205], v141 offset:56320
	global_load_lds_dwordx4 v[206:207], off
	s_add_i32 m0, s28, 0x2000
	s_add_u32 s22, s22, 0x40080
	v_lshl_add_u64 v[206:207], v[210:211], 0, s[10:11]
	s_addc_u32 s23, s23, 0
	s_add_i32 s28, s29, s18
	global_load_lds_dwordx4 v[206:207], off
	v_lshl_add_u64 v[206:207], s[22:23], 0, v[208:209]
	s_mov_b32 m0, s28
	s_nop 0
	global_load_lds_dwordx4 v[206:207], off
	v_lshl_add_u64 v[206:207], s[22:23], 0, v[128:129]
	s_add_i32 m0, s28, 0x2000
	s_nop 0
	global_load_lds_dwordx4 v[206:207], off
	v_lshl_add_u64 v[206:207], v[212:213], 0, s[10:11]
	s_mov_b32 m0, s35
	s_nop 0
	global_load_lds_dwordx4 v[206:207], off
	v_lshl_add_u64 v[206:207], v[222:223], 0, s[10:11]
	s_mov_b32 m0, s39
	s_nop 0
	global_load_lds_dwordx4 v[206:207], off
	s_waitcnt vmcnt(8)
	s_waitcnt lgkmcnt(0)
	s_barrier
	s_waitcnt lgkmcnt(0)
	v_mfma_f32_16x16x32_bf16 v[60:63], v[142:145], v[174:177], v[60:63]
	v_mfma_f32_16x16x32_bf16 v[56:59], v[150:153], v[174:177], v[56:59]
	v_mfma_f32_16x16x32_bf16 v[52:55], v[142:145], v[182:185], v[52:55]
	v_mfma_f32_16x16x32_bf16 v[48:51], v[150:153], v[182:185], v[48:51]
	v_mfma_f32_16x16x32_bf16 v[36:39], v[142:145], v[190:193], v[36:39]
	v_mfma_f32_16x16x32_bf16 v[32:35], v[150:153], v[190:193], v[32:35]
	v_mfma_f32_16x16x32_bf16 v[20:23], v[142:145], v[198:201], v[20:23]
	v_mfma_f32_16x16x32_bf16 v[16:19], v[150:153], v[198:201], v[16:19]
	v_mfma_f32_16x16x32_bf16 v[60:63], v[146:149], v[178:181], v[60:63]
	v_mfma_f32_16x16x32_bf16 v[56:59], v[154:157], v[178:181], v[56:59]
	v_mfma_f32_16x16x32_bf16 v[52:55], v[146:149], v[186:189], v[52:55]
	v_mfma_f32_16x16x32_bf16 v[48:51], v[154:157], v[186:189], v[48:51]
	v_mfma_f32_16x16x32_bf16 v[36:39], v[146:149], v[194:197], v[36:39]
	v_mfma_f32_16x16x32_bf16 v[32:35], v[154:157], v[194:197], v[32:35]
	v_mfma_f32_16x16x32_bf16 v[20:23], v[146:149], v[202:205], v[20:23]
	v_mfma_f32_16x16x32_bf16 v[16:19], v[154:157], v[202:205], v[16:19]
	v_mfma_f32_16x16x32_bf16 v[44:47], v[158:161], v[174:177], v[44:47]
	v_mfma_f32_16x16x32_bf16 v[40:43], v[166:169], v[174:177], v[40:43]
	v_mfma_f32_16x16x32_bf16 v[28:31], v[158:161], v[182:185], v[28:31]
	v_mfma_f32_16x16x32_bf16 v[24:27], v[166:169], v[182:185], v[24:27]
	v_mfma_f32_16x16x32_bf16 v[12:15], v[158:161], v[190:193], v[12:15]
	v_mfma_f32_16x16x32_bf16 v[8:11], v[166:169], v[190:193], v[8:11]
	v_mfma_f32_16x16x32_bf16 v[4:7], v[158:161], v[198:201], v[4:7]
	v_mfma_f32_16x16x32_bf16 v[0:3], v[166:169], v[198:201], v[0:3]
	v_mfma_f32_16x16x32_bf16 v[44:47], v[162:165], v[178:181], v[44:47]
	v_mfma_f32_16x16x32_bf16 v[40:43], v[170:173], v[178:181], v[40:43]
	v_mfma_f32_16x16x32_bf16 v[28:31], v[162:165], v[186:189], v[28:31]
	v_mfma_f32_16x16x32_bf16 v[24:27], v[170:173], v[186:189], v[24:27]
	v_mfma_f32_16x16x32_bf16 v[12:15], v[162:165], v[194:197], v[12:15]
	v_mfma_f32_16x16x32_bf16 v[8:11], v[170:173], v[194:197], v[8:11]
	v_mfma_f32_16x16x32_bf16 v[4:7], v[162:165], v[202:205], v[4:7]
	v_mfma_f32_16x16x32_bf16 v[0:3], v[170:173], v[202:205], v[0:3]
	s_barrier
	s_add_i32 s51, s51, 2
	s_add_u32 s44, s44, 0x100
	s_addc_u32 s45, s45, 0
	s_add_u32 s49, s49, 0x100
	s_addc_u32 s50, s50, 0
	s_cmp_gt_u32 s51, 13
	s_cbranch_scc0 .LBB0_354
	s_and_b64 vcc, exec, s[8:9]
	s_cbranch_vccz .LBB0_357
	s_barrier

; #define FLAS __attribute__((address_space(3)))
; __device__ __forceinline__ void attn_unit_a(FLAS unsigned char* lds, const Unit u) {
;     ...
;     const f32x16 z16 = {0.f,0.f,0.f,0.f,0.f,0.f,0.f,0.f,0.f,0.f,0.f,0.f,0.f,0.f,0.f,0.f};
;     f32x16 o[NDB];
; #pragma unroll
;     for (int i = 0; i < NDB; ++i) o[i] = z16;
;     float mrun = 0.f, lsum = 0.f, fpend = 1.f; bool first = true, pend = false;
;     ...
;     f32x16 pa0, pa1, pb0, pb1; float cbC = 0.f;
;     { bool zi; FA_BIAS(0, pa0, pa1, cbC, zi); if (zi) { pa0 = z16; pa1 = z16; }
;       const FLAS unsigned char* kb = lds + LA_K;
; #pragma unroll
;       for (int d0 = 0; d0 < 4; ++d0) { const int ko = (2 * d0 + hi) * 1024 + ((r32 ^ (2 * d0 + hi)) * 16); const bf16x8 a0 = *(const FLAS bf16x8*)(kb + ko), a1 = *(const FLAS bf16x8*)(kb + ko + 512);
;           pa0 = __builtin_amdgcn_mfma_f32_32x32x16_bf16(a0, qr[d0], pa0, 0, 0, 0); pa1 = __builtin_amdgcn_mfma_f32_32x32x16_bf16(a1, qr[d0], pa1, 0, 0, 0); } }
;     u32x4 pwa[4] = {{0u,0u,0u,0u},{0u,0u,0u,0u},{0u,0u,0u,0u},{0u,0u,0u,0u}}, pwb[4] = {{0u,0u,0u,0u},{0u,0u,0u,0u},{0u,0u,0u,0u},{0u,0u,0u,0u}};
.LBB0_432:
	v_xor_b32_e32 v1, v243, v5
	v_lshlrev_b32_e32 v1, 4, v1
	v_lshl_add_u32 v4, v243, 10, 0
	v_add_u32_e32 v247, v4, v1
	ds_read_b128 v[6:9], v247
	ds_read_b128 v[10:13], v247 offset:512
	v_or_b32_e32 v1, 2, v243
	v_bitop3_b32 v4, v243, v5, 2 bitop3:0x36
	v_lshlrev_b32_e32 v4, 4, v4
	v_lshl_add_u32 v1, v1, 10, 0
	v_add_u32_e32 v248, v1, v4
	s_waitcnt lgkmcnt(1)
	v_mfma_f32_32x32x16_bf16 v[128:143], v[6:9], v[160:163], v[128:143]
	ds_read_b128 v[6:9], v248
	v_or_b32_e32 v1, 4, v243
	v_bitop3_b32 v4, v243, v5, 4 bitop3:0x36
	v_lshlrev_b32_e32 v4, 4, v4
	v_lshl_add_u32 v1, v1, 10, 0
	v_add_u32_e32 v249, v1, v4
	s_lshr_b32 s0, s43, 8
	s_waitcnt lgkmcnt(1)
	v_mfma_f32_32x32x16_bf16 v[144:159], v[10:13], v[160:163], v[144:159]
	ds_read_b128 v[10:13], v248 offset:512
	s_lshl_b32 s15, s41, 1
	s_and_b32 s18, s40, 15
	s_and_b32 s0, s0, 1
	s_lshl_b32 s26, s42, 7
	s_bfe_u32 s1, s41, 0x2000d
	s_and_b32 s15, s15, 0xc000
	s_waitcnt lgkmcnt(1)
	v_mfma_f32_32x32x16_bf16 v[128:143], v[6:9], v[164:167], v[128:143]
	ds_read_b128 v[6:9], v249
	s_lshl_b32 s18, s18, 8
	s_lshl_b32 s20, s0, 7
	s_add_i32 s0, 0, 0x16000
	v_add_u32_e32 v240, s0, v224
	s_add_u32 s0, s70, s15
	s_mul_i32 s19, s1, 0x1800000
	s_waitcnt lgkmcnt(1)
	v_mfma_f32_32x32x16_bf16 v[144:159], v[10:13], v[164:167], v[144:159]
	ds_read_b128 v[10:13], v249 offset:512
	s_addc_u32 s1, s71, 0
	v_or_b32_e32 v1, 6, v243
	v_bitop3_b32 v4, v243, v5, 6 bitop3:0x36
	s_add_u32 s0, s0, s12
	v_lshlrev_b32_e32 v4, 4, v4
	v_lshl_add_u32 v1, v1, 10, 0
	s_waitcnt lgkmcnt(1)
	v_mfma_f32_32x32x16_bf16 v[128:143], v[6:9], v[168:171], v[128:143]
	s_addc_u32 s1, s1, 0
	v_add_u32_e32 v250, v1, v4
	v_lshl_add_u64 v[228:229], s[0:1], 0, v[2:3]
	s_lshl_b32 s0, s5, 8
	ds_read_b128 v[6:9], v250
	ds_read_b128 v[14:17], v250 offset:512
	s_and_b32 s0, s0, 0xfffff000
	s_or_b32 s0, s0, s18
	s_waitcnt lgkmcnt(2)
	v_mfma_f32_32x32x16_bf16 v[144:159], v[10:13], v[168:171], v[144:159]
	s_add_i32 s0, s0, s14
	s_sub_i32 s48, 64, s0
	v_add_lshl_u32 v1, s0, v5, 2
	s_add_u32 s0, s70, s20
	s_addc_u32 s1, s71, 0
	s_add_u32 s0, s0, s4
	s_addc_u32 s1, s1, 0
	s_waitcnt lgkmcnt(1)
	v_mfma_f32_32x32x16_bf16 v[128:143], v[6:9], v[172:175], v[128:143]
	s_add_u32 s0, s0, s19
	s_addc_u32 s1, s1, 0
	v_sub_u32_e32 v1, v224, v1
	v_mov_b64_e32 v[2:3], s[0:1]
	v_mul_u32_u24_e32 v246, 0x90, v5
	v_add_u32_e32 v210, 0, v1
	v_mad_i64_i32 v[230:231], s[0:1], v0, s65, v[2:3]
	s_waitcnt lgkmcnt(0)
	v_mfma_f32_32x32x16_bf16 v[144:159], v[14:17], v[172:175], v[144:159]
	v_mov_b32_e32 v14, v209
	v_mov_b32_e32 v15, v209
	v_mov_b32_e32 v0, v209
	v_mov_b32_e32 v1, v209
	v_mov_b32_e32 v2, v209
	v_mov_b32_e32 v3, v209
	v_mov_b32_e32 v4, v209
	v_mov_b32_e32 v5, v209
	v_mov_b32_e32 v6, v209
	v_mov_b32_e32 v7, v209
	v_mov_b32_e32 v8, v209
	v_mov_b32_e32 v9, v209
	v_mov_b32_e32 v10, v209
	v_mov_b32_e32 v11, v209
	v_mov_b32_e32 v12, v209
	v_mov_b32_e32 v13, v209
	v_mov_b32_e32 v188, 0
	v_mov_b64_e32 v[30:31], v[14:15]
	v_mov_b64_e32 v[46:47], v[14:15]
	v_mov_b64_e32 v[62:63], v[14:15]
	v_ashrrev_i32_e32 v223, 31, v222
	v_add3_u32 v251, 0, v246, v224
	s_mov_b32 s49, 0
	s_mov_b64 s[24:25], -1
	v_mov_b32_e32 v211, 0
	v_mov_b32_e32 v226, 1.0
	v_mov_b64_e32 v[28:29], v[12:13]
	v_mov_b64_e32 v[26:27], v[10:11]
	v_mov_b64_e32 v[24:25], v[8:9]
	v_mov_b64_e32 v[22:23], v[6:7]
	v_mov_b64_e32 v[20:21], v[4:5]
	v_mov_b64_e32 v[18:19], v[2:3]
	v_mov_b64_e32 v[16:17], v[0:1]
	v_mov_b64_e32 v[44:45], v[12:13]
	v_mov_b64_e32 v[42:43], v[10:11]
	v_mov_b64_e32 v[40:41], v[8:9]
	v_mov_b64_e32 v[38:39], v[6:7]
	v_mov_b64_e32 v[36:37], v[4:5]
	v_mov_b64_e32 v[34:35], v[2:3]
	v_mov_b64_e32 v[32:33], v[0:1]
	v_mov_b64_e32 v[60:61], v[12:13]
	v_mov_b64_e32 v[58:59], v[10:11]
	v_mov_b64_e32 v[56:57], v[8:9]
	v_mov_b64_e32 v[54:55], v[6:7]
	v_mov_b64_e32 v[52:53], v[4:5]
	v_mov_b64_e32 v[50:51], v[2:3]
	v_mov_b64_e32 v[48:49], v[0:1]
	s_mov_b32 s19, 0
	v_mov_b32_e32 v212, 0
	v_mov_b32_e32 v189, v188
	v_mov_b32_e32 v190, v188
	v_mov_b32_e32 v191, v188
	v_mov_b32_e32 v192, v188
	v_mov_b32_e32 v193, v188
	v_mov_b32_e32 v194, v188
	v_mov_b32_e32 v195, v188
	v_mov_b32_e32 v196, v188
	v_mov_b32_e32 v197, v188
	v_mov_b32_e32 v198, v188
	v_mov_b32_e32 v199, v188
	v_mov_b32_e32 v104, v188
	v_mov_b32_e32 v105, v188
	v_mov_b32_e32 v106, v188
	v_mov_b32_e32 v107, v188
	v_readfirstlane_b32 s100, v236
	s_nop 3
	s_cmp_lt_u32 s100, 0x100
	s_cbranch_scc1 .Lprio_skip
; #define FLAS __attribute__((address_space(3)))
; #define FA_SB() __builtin_amdgcn_sched_barrier(0)
; __device__ __forceinline__ float fadd_s(float a, float b) { float r; asm("v_add_f32_e32 %0, %1, %2" : "=v"(r) : "v"(a), "v"(b)); return r; }
; #define FA_PVM(G) do { o[(G) & 3] = __builtin_amdgcn_mfma_f32_32x32x16_bf16(__builtin_bit_cast(bf16x8, vr[(G) % 3]), __builtin_bit_cast(bf16x8, PWC[(G) >> 2]), o[(G) & 3], 0, 0, 0); if ((G) + 3 < 16) vr[(G) % 3] = FA_VFRAG((G) + 3); } while (0)
; __device__ __forceinline__ void attn_unit_a(FLAS unsigned char* lds, const Unit u) {
;     ...
;         const int vsp = (i == 0) ? 0 : ((i - 1) & 3);
;         const FLAS unsigned char* vb_ = lds + LA_V + vsp * VBUF + r32 * VPITCH + hi * 16;
;         const FLAS unsigned char* kb = lds + LA_K + ((i + 1) & 1) * KBUF;
;     ...
;         u32x4 vr[3];
; #pragma unroll
;         for (int m = 0; m < 3; ++m) vr[m] = FA_VFRAG(m);
;         const float off = cbC - mrun;
;         FA_SB();
;         float ra, rb, rm;
;         FA_PVM(0); pC0[0] = fadd_s(pC0[0], off); pC1[0] = fadd_s(pC1[0], off); pC0[1] = fadd_s(pC0[1], off); pC1[1] = fadd_s(pC1[1], off); pC0[2] = fadd_s(pC0[2], off); pC1[2] = fadd_s(pC1[2], off); FA_SB();
.Lprio_skip:
	s_waitcnt lgkmcnt(0)
	v_readlane_b32 s100, v254, 47
	v_mov_b32_e32 v92, s13
	s_nop 3
	v_mov_b32_e32 v93, s100
	ds_read_b32 v92, v92
	ds_read_b32 v93, v93
	v_sub_f32_e32 v94, v204, v211
	v_add_f32_e32 v96, v128, v94
	v_add_f32_e32 v112, v144, v94
	v_add_f32_e32 v97, v129, v94
	v_add_f32_e32 v113, v145, v94
	v_add_f32_e32 v98, v130, v94
	v_add_f32_e32 v114, v146, v94
	v_add_f32_e32 v99, v131, v94
	v_add_f32_e32 v115, v147, v94
	v_add_f32_e32 v100, v132, v94
	v_add_f32_e32 v116, v148, v94
	v_add_f32_e32 v101, v133, v94
	v_add_f32_e32 v117, v149, v94
	v_add_f32_e32 v102, v134, v94
	v_add_f32_e32 v118, v150, v94
	v_add_f32_e32 v103, v135, v94
	v_add_f32_e32 v119, v151, v94
	v_add_f32_e32 v104, v136, v94
	v_add_f32_e32 v120, v152, v94
	v_add_f32_e32 v105, v137, v94
	v_add_f32_e32 v121, v153, v94
	v_add_f32_e32 v106, v138, v94
	v_add_f32_e32 v122, v154, v94
	v_add_f32_e32 v107, v139, v94
	v_add_f32_e32 v123, v155, v94
	v_add_f32_e32 v108, v140, v94
	v_add_f32_e32 v124, v156, v94
	v_add_f32_e32 v109, v141, v94
	v_add_f32_e32 v125, v157, v94
	v_add_f32_e32 v110, v142, v94
	v_add_f32_e32 v126, v158, v94
	v_add_f32_e32 v111, v143, v94
	v_add_f32_e32 v127, v159, v94
	v_mov_b32_e32 v144, 0x7fc00000
	v_mov_b32_e32 v145, 0x7fc00000
	v_mov_b32_e32 v146, 0x7fc00000
	v_mov_b32_e32 v147, 0x7fc00000
	v_mov_b32_e32 v148, 0x7fc00000
	v_mov_b32_e32 v149, 0x7fc00000
	v_mov_b32_e32 v150, 0x7fc00000
	v_mov_b32_e32 v151, 0x7fc00000
	v_mov_b32_e32 v152, 0x7fc00000
	v_mov_b32_e32 v153, 0x7fc00000
	v_mov_b32_e32 v154, 0x7fc00000
	v_mov_b32_e32 v155, 0x7fc00000
	v_mov_b32_e32 v156, 0x7fc00000
	v_mov_b32_e32 v157, 0x7fc00000
	v_mov_b32_e32 v158, 0x7fc00000
	v_mov_b32_e32 v159, 0x7fc00000
	v_mov_b32_e32 v204, 0
	v_mov_b32_e32 v205, 0
	v_mov_b32_e32 v206, 0
	v_mov_b32_e32 v207, 0
	s_waitcnt lgkmcnt(0)
	v_readfirstlane_b32 s101, v92
	v_readfirstlane_b32 s100, v93
	v_mov_b32_e32 v72, 0
	v_mov_b32_e32 v73, 0
	v_mov_b32_e32 v74, 0
	v_mov_b32_e32 v75, 0
	v_mov_b32_e32 v76, 0
	v_mov_b32_e32 v77, 0
	v_mov_b32_e32 v78, 0
	v_mov_b32_e32 v79, 0
	v_mov_b32_e32 v80, 0
	v_mov_b32_e32 v81, 0
	v_mov_b32_e32 v82, 0
	v_mov_b32_e32 v83, 0
	v_mov_b32_e32 v84, 0
	v_mov_b32_e32 v85, 0
	v_mov_b32_e32 v86, 0
	v_mov_b32_e32 v87, 0
	v_mov_b32_e32 v88, 0
	v_mov_b32_e32 v89, 0
	v_mov_b32_e32 v90, 0
	v_mov_b32_e32 v91, 0
	v_mov_b32_e32 v92, 0
	v_mov_b32_e32 v93, 0
	v_mov_b32_e32 v94, 0
	v_mov_b32_e32 v95, 0
	s_mov_b32 s99, 0x7fc00000
	s_add_i32 s12, s19, -1
	s_and_b32 s18, s12, 3
	s_mulk_i32 s18, 0x4800
	s_cmp_lg_u32 s49, 0
	s_cselect_b32 s12, s18, 0
	v_add_u32_e32 v200, s12, v251
	ds_read_b128 v[128:131], v200 offset:16384
	ds_read_b128 v[132:135], v200 offset:20992
	ds_read_b128 v[136:139], v200 offset:25600
	s_cbranch_execnz .LBB0_435
	s_branch .LBB0_434

; __device__ __forceinline__ void attn_unit_a(FLAS unsigned char* lds, const Unit u) {
;     ...
;     if (pend) {
; #pragma unroll
;         for (int d = 0; d < NDB; ++d) o[d] = o[d] * fpend; }
.Lexit_a:
	s_andn2_b64 vcc, exec, s[0:1]
	s_cbranch_vccnz .LBB0_479
	v_pk_mul_f32 v[62:63], v[62:63], v[226:227] op_sel_hi:[1,0]
	v_pk_mul_f32 v[60:61], v[60:61], v[226:227] op_sel_hi:[1,0]
	v_pk_mul_f32 v[58:59], v[58:59], v[226:227] op_sel_hi:[1,0]
	v_pk_mul_f32 v[56:57], v[56:57], v[226:227] op_sel_hi:[1,0]
	v_pk_mul_f32 v[54:55], v[54:55], v[226:227] op_sel_hi:[1,0]
	v_pk_mul_f32 v[52:53], v[52:53], v[226:227] op_sel_hi:[1,0]
	v_pk_mul_f32 v[50:51], v[50:51], v[226:227] op_sel_hi:[1,0]
	v_pk_mul_f32 v[48:49], v[48:49], v[226:227] op_sel_hi:[1,0]
	v_pk_mul_f32 v[46:47], v[46:47], v[226:227] op_sel_hi:[1,0]
	v_pk_mul_f32 v[44:45], v[44:45], v[226:227] op_sel_hi:[1,0]
	v_pk_mul_f32 v[42:43], v[42:43], v[226:227] op_sel_hi:[1,0]
	v_pk_mul_f32 v[40:41], v[40:41], v[226:227] op_sel_hi:[1,0]
	v_pk_mul_f32 v[38:39], v[38:39], v[226:227] op_sel_hi:[1,0]
	v_pk_mul_f32 v[36:37], v[36:37], v[226:227] op_sel_hi:[1,0]
	v_pk_mul_f32 v[34:35], v[34:35], v[226:227] op_sel_hi:[1,0]
	v_pk_mul_f32 v[32:33], v[32:33], v[226:227] op_sel_hi:[1,0]
	v_pk_mul_f32 v[30:31], v[30:31], v[226:227] op_sel_hi:[1,0]
	v_pk_mul_f32 v[28:29], v[28:29], v[226:227] op_sel_hi:[1,0]
	v_pk_mul_f32 v[26:27], v[26:27], v[226:227] op_sel_hi:[1,0]
	v_pk_mul_f32 v[24:25], v[24:25], v[226:227] op_sel_hi:[1,0]
	v_pk_mul_f32 v[22:23], v[22:23], v[226:227] op_sel_hi:[1,0]
	v_pk_mul_f32 v[20:21], v[20:21], v[226:227] op_sel_hi:[1,0]
	v_pk_mul_f32 v[18:19], v[18:19], v[226:227] op_sel_hi:[1,0]
	v_pk_mul_f32 v[16:17], v[16:17], v[226:227] op_sel_hi:[1,0]
	v_pk_mul_f32 v[14:15], v[14:15], v[226:227] op_sel_hi:[1,0]
	v_pk_mul_f32 v[12:13], v[12:13], v[226:227] op_sel_hi:[1,0]
	v_pk_mul_f32 v[10:11], v[10:11], v[226:227] op_sel_hi:[1,0]
	v_pk_mul_f32 v[8:9], v[8:9], v[226:227] op_sel_hi:[1,0]
	v_pk_mul_f32 v[6:7], v[6:7], v[226:227] op_sel_hi:[1,0]
	v_pk_mul_f32 v[4:5], v[4:5], v[226:227] op_sel_hi:[1,0]
	v_pk_mul_f32 v[2:3], v[2:3], v[226:227] op_sel_hi:[1,0]
	v_pk_mul_f32 v[0:1], v[0:1], v[226:227] op_sel_hi:[1,0]

; #define PG8_STAGE(bufoff, gbase, voff) do { _Pragma("unroll") for (int _i = 0; _i < 2; ++_i) \
;         __builtin_amdgcn_global_load_lds((const unsigned*)((const char*)(gbase) + (voff)[_i]), (PG8_LAS unsigned*)(lds + (bufoff) + ldsw + _i * 8192), 16, 0, 0); } while (0)
; #define PG8_LDA(dst, b, h) do { _Pragma("unroll") for (int m = 0; m < 4; ++m) _Pragma("unroll") for (int k = 0; k < 2; ++k) dst[m][k] = *(const PG8_LAS bf16x8*)(lds + PG8_SA(b, h) + aoff + m * 2048 + k * 1024); } while (0)
; #define PG8_LDB(dst, b, h) do { _Pragma("unroll") for (int n = 0; n < 2; ++n) _Pragma("unroll") for (int k = 0; k < 2; ++k) dst[n][k] = *(const PG8_LAS bf16x8*)(lds + PG8_SB(b, h) + boff + n * 2048 + k * 1024); } while (0)
; #define PG8_MMA(ai, bj, At, Bt) do { __builtin_amdgcn_s_setprio(1); _Pragma("unroll") for (int m = 0; m < 4; ++m) _Pragma("unroll") for (int n = 0; n < 2; ++n) _Pragma("unroll") for (int k = 0; k < 2; ++k) \
;         acc[ai][bj][m][n] = __builtin_amdgcn_mfma_f32_16x16x32_bf16(Bt[n][k], At[m][k], acc[ai][bj][m][n], 0, 0, 0); __builtin_amdgcn_s_setprio(0); } while (0)
; #define PG8_WAIT_V(n) asm volatile("s_waitcnt vmcnt(" #n ")" ::: "memory")
; #define PG8_WAIT_L(n) asm volatile("s_waitcnt lgkmcnt(" #n ")" ::: "memory")
; #define PG8_BAR __builtin_amdgcn_s_barrier()
; #define PG8_SCHED __builtin_amdgcn_sched_barrier(0)
; template <class Epi, class Sched, bool ALIGN_EPI = false, bool SP2 = false>
; __device__ __forceinline__ void gemm_phase(PG8_LAS unsigned char* lds, const Gemm g, const Sched& S, const Epi& E) {
;     ...
;             const bool last = (t == nt - 2);
;             const char* a1 = cA + (size_t)(t + 1) * kstep;
;             const char* a2 = last ? nA : cA + (size_t)(t + 2) * kstep; const char* b2 = last ? nB : cB + (size_t)(t + 2) * kstep;
;             const char* a3 = a2 + kstep; const char* b3 = b2 + kstep;
;             if (last && has_next) S.a_ready(nxt);
;             if constexpr (SP2) {
;             PG8_LDB(B0, 0, 0); PG8_LDB(B1, 0, 1); PG8_SCHED; PG8_LDA(At, 0, 0); PG8_STAGE(PG8_SA(1, 1), a1 + hstepA, voffA);
;             PG8_WAIT_V(8); PG8_WAIT_L(0); PG8_BAR; PG8_MMA(0, 0, At, B0); PG8_MMA(0, 1, At, B1); PG8_BAR; PG8_SCHED;
;             PG8_LDA(At, 0, 1); PG8_STAGE(PG8_SB(0, 0), b2, voffB); PG8_STAGE(PG8_SB(0, 1), b2 + hstepB, voffB); PG8_STAGE(PG8_SA(0, 0), a2, voffA);
.LBB0_607:
	s_add_u32 s22, s0, 0xfffc0080
	s_addc_u32 s23, s1, -1
	s_add_i32 s28, 0, 0x10000
	s_cmp_eq_u32 s51, 12
	s_cselect_b32 s25, s14, s23
	s_cselect_b32 s24, s15, s22
	s_cselect_b32 s23, s9, s50
	s_cselect_b32 s22, s38, s43
	s_add_i32 s29, 0, 0x14000
	v_add_u32_e32 v154, s28, v143
	v_add_u32_e32 v170, s29, v143
	ds_read_b128 v[138:141], v154
	ds_read_b128 v[146:149], v154 offset:1024
	ds_read_b128 v[150:153], v154 offset:2048
	ds_read_b128 v[154:157], v154 offset:3072
	ds_read_b128 v[158:161], v170
	ds_read_b128 v[162:165], v170 offset:1024
	ds_read_b128 v[166:169], v170 offset:2048
	ds_read_b128 v[170:173], v170 offset:3072
	v_lshl_add_u64 v[206:207], s[0:1], 0, v[134:135]
	s_add_i32 m0, s21, 0xc000
	ds_read_b128 v[174:177], v145
	ds_read_b128 v[178:181], v145 offset:1024
	ds_read_b128 v[182:185], v145 offset:2048
	ds_read_b128 v[186:189], v145 offset:3072
	ds_read_b128 v[190:193], v145 offset:4096
	ds_read_b128 v[194:197], v145 offset:5120
	ds_read_b128 v[198:201], v145 offset:6144
	ds_read_b128 v[202:205], v145 offset:7168
	global_load_lds_dwordx4 v[206:207], off
	v_lshl_add_u64 v[206:207], s[0:1], 0, v[136:137]
	s_add_i32 m0, s21, 0xe000
	s_nop 0
	global_load_lds_dwordx4 v[206:207], off
	s_waitcnt vmcnt(8)
	s_waitcnt lgkmcnt(0)
	s_barrier
	s_waitcnt lgkmcnt(0)
	v_mfma_f32_16x16x32_bf16 v[124:127], v[138:141], v[174:177], v[124:127]
	v_mfma_f32_16x16x32_bf16 v[120:123], v[150:153], v[174:177], v[120:123]
	v_mfma_f32_16x16x32_bf16 v[108:111], v[138:141], v[182:185], v[108:111]
	v_mfma_f32_16x16x32_bf16 v[104:107], v[150:153], v[182:185], v[104:107]
	v_mfma_f32_16x16x32_bf16 v[92:95], v[138:141], v[190:193], v[92:95]
	v_mfma_f32_16x16x32_bf16 v[88:91], v[150:153], v[190:193], v[88:91]
	v_mfma_f32_16x16x32_bf16 v[76:79], v[138:141], v[198:201], v[76:79]
	v_mfma_f32_16x16x32_bf16 v[72:75], v[150:153], v[198:201], v[72:75]
	v_mfma_f32_16x16x32_bf16 v[124:127], v[146:149], v[178:181], v[124:127]
	v_mfma_f32_16x16x32_bf16 v[120:123], v[154:157], v[178:181], v[120:123]
	v_mfma_f32_16x16x32_bf16 v[108:111], v[146:149], v[186:189], v[108:111]
	v_mfma_f32_16x16x32_bf16 v[104:107], v[154:157], v[186:189], v[104:107]
	v_mfma_f32_16x16x32_bf16 v[92:95], v[146:149], v[194:197], v[92:95]
	v_mfma_f32_16x16x32_bf16 v[88:91], v[154:157], v[194:197], v[88:91]
	v_mfma_f32_16x16x32_bf16 v[76:79], v[146:149], v[202:205], v[76:79]
	v_mfma_f32_16x16x32_bf16 v[72:75], v[154:157], v[202:205], v[72:75]
	v_mfma_f32_16x16x32_bf16 v[116:119], v[158:161], v[174:177], v[116:119]
	v_mfma_f32_16x16x32_bf16 v[112:115], v[166:169], v[174:177], v[112:115]
	v_mfma_f32_16x16x32_bf16 v[100:103], v[158:161], v[182:185], v[100:103]
	v_mfma_f32_16x16x32_bf16 v[96:99], v[166:169], v[182:185], v[96:99]
	v_mfma_f32_16x16x32_bf16 v[84:87], v[158:161], v[190:193], v[84:87]
	v_mfma_f32_16x16x32_bf16 v[80:83], v[166:169], v[190:193], v[80:83]
	v_mfma_f32_16x16x32_bf16 v[68:71], v[158:161], v[198:201], v[68:71]
	v_mfma_f32_16x16x32_bf16 v[64:67], v[166:169], v[198:201], v[64:67]
	v_mfma_f32_16x16x32_bf16 v[116:119], v[162:165], v[178:181], v[116:119]
	v_mfma_f32_16x16x32_bf16 v[112:115], v[170:173], v[178:181], v[112:115]
	v_mfma_f32_16x16x32_bf16 v[100:103], v[162:165], v[186:189], v[100:103]
	v_mfma_f32_16x16x32_bf16 v[96:99], v[170:173], v[186:189], v[96:99]
	v_mfma_f32_16x16x32_bf16 v[84:87], v[162:165], v[194:197], v[84:87]
	v_mfma_f32_16x16x32_bf16 v[80:83], v[170:173], v[194:197], v[80:83]
	v_mfma_f32_16x16x32_bf16 v[68:71], v[162:165], v[202:205], v[68:71]
	v_mfma_f32_16x16x32_bf16 v[64:67], v[170:173], v[202:205], v[64:67]
	s_barrier
	s_add_i32 s28, s28, s26
	v_lshl_add_u64 v[206:207], s[22:23], 0, v[208:209]
	s_mov_b32 m0, s28
	ds_read_b128 v[174:177], v145 offset:16384
	ds_read_b128 v[178:181], v145 offset:17408
	ds_read_b128 v[182:185], v145 offset:18432
	ds_read_b128 v[186:189], v145 offset:19456
	ds_read_b128 v[190:193], v145 offset:20480
	ds_read_b128 v[194:197], v145 offset:21504
	ds_read_b128 v[198:201], v145 offset:22528
	ds_read_b128 v[202:205], v145 offset:23552
	global_load_lds_dwordx4 v[206:207], off
	s_add_i32 m0, s28, 0x2000
	s_add_u32 s52, s22, 0x40000
	v_lshl_add_u64 v[210:211], s[22:23], 0, v[128:129]
	s_addc_u32 s53, s23, 0
	s_add_i32 s28, s29, s26
	global_load_lds_dwordx4 v[210:211], off
	v_lshl_add_u64 v[212:213], s[52:53], 0, v[208:209]
	s_mov_b32 m0, s28
	v_lshl_add_u64 v[222:223], s[24:25], 0, v[130:131]
	global_load_lds_dwordx4 v[212:213], off
	v_lshl_add_u64 v[212:213], s[52:53], 0, v[128:129]
	s_add_i32 m0, s28, 0x2000
	s_nop 0
	global_load_lds_dwordx4 v[212:213], off
	v_lshl_add_u64 v[212:213], s[24:25], 0, v[132:133]
	s_mov_b32 m0, s21
	s_nop 0
	global_load_lds_dwordx4 v[212:213], off
	s_mov_b32 m0, s18
	s_nop 0
	global_load_lds_dwordx4 v[222:223], off
	s_waitcnt vmcnt(8)
	s_waitcnt lgkmcnt(0)
	s_barrier
; #define PG8_STAGE(bufoff, gbase, voff) do { _Pragma("unroll") for (int _i = 0; _i < 2; ++_i) \
;         __builtin_amdgcn_global_load_lds((const unsigned*)((const char*)(gbase) + (voff)[_i]), (PG8_LAS unsigned*)(lds + (bufoff) + ldsw + _i * 8192), 16, 0, 0); } while (0)
; #define PG8_LDA(dst, b, h) do { _Pragma("unroll") for (int m = 0; m < 4; ++m) _Pragma("unroll") for (int k = 0; k < 2; ++k) dst[m][k] = *(const PG8_LAS bf16x8*)(lds + PG8_SA(b, h) + aoff + m * 2048 + k * 1024); } while (0)
; #define PG8_LDB(dst, b, h) do { _Pragma("unroll") for (int n = 0; n < 2; ++n) _Pragma("unroll") for (int k = 0; k < 2; ++k) dst[n][k] = *(const PG8_LAS bf16x8*)(lds + PG8_SB(b, h) + boff + n * 2048 + k * 1024); } while (0)
; #define PG8_MMA(ai, bj, At, Bt) do { __builtin_amdgcn_s_setprio(1); _Pragma("unroll") for (int m = 0; m < 4; ++m) _Pragma("unroll") for (int n = 0; n < 2; ++n) _Pragma("unroll") for (int k = 0; k < 2; ++k) \
;         acc[ai][bj][m][n] = __builtin_amdgcn_mfma_f32_16x16x32_bf16(Bt[n][k], At[m][k], acc[ai][bj][m][n], 0, 0, 0); __builtin_amdgcn_s_setprio(0); } while (0)
; #define PG8_WAIT_V(n) asm volatile("s_waitcnt vmcnt(" #n ")" ::: "memory")
; #define PG8_WAIT_L(n) asm volatile("s_waitcnt lgkmcnt(" #n ")" ::: "memory")
; #define PG8_BAR __builtin_amdgcn_s_barrier()
; #define PG8_SCHED __builtin_amdgcn_sched_barrier(0)
; template <class Epi, class Sched, bool ALIGN_EPI = false, bool SP2 = false>
; __device__ __forceinline__ void gemm_phase(PG8_LAS unsigned char* lds, const Gemm g, const Sched& S, const Epi& E) {
;     ...
;             PG8_WAIT_V(8); PG8_WAIT_L(0); PG8_BAR; PG8_MMA(1, 0, At, B0); PG8_MMA(1, 1, At, B1); PG8_BAR; PG8_SCHED;
;             PG8_LDB(B0, 1, 0); PG8_LDB(B1, 1, 1); PG8_SCHED; PG8_LDA(At, 1, 0); PG8_STAGE(PG8_SA(0, 1), a2 + hstepA, voffA);
;             PG8_WAIT_V(8); PG8_WAIT_L(0); PG8_BAR; PG8_MMA(0, 0, At, B0); PG8_MMA(0, 1, At, B1); PG8_BAR; PG8_SCHED;
	s_waitcnt lgkmcnt(0)
	v_mfma_f32_16x16x32_bf16 v[60:63], v[138:141], v[174:177], v[60:63]
	v_mfma_f32_16x16x32_bf16 v[56:59], v[150:153], v[174:177], v[56:59]
	v_mfma_f32_16x16x32_bf16 v[44:47], v[138:141], v[182:185], v[44:47]
	v_mfma_f32_16x16x32_bf16 v[40:43], v[150:153], v[182:185], v[40:43]
	v_mfma_f32_16x16x32_bf16 v[28:31], v[138:141], v[190:193], v[28:31]
	v_mfma_f32_16x16x32_bf16 v[24:27], v[150:153], v[190:193], v[24:27]
	v_mfma_f32_16x16x32_bf16 v[12:15], v[138:141], v[198:201], v[12:15]
	v_mfma_f32_16x16x32_bf16 v[8:11], v[150:153], v[198:201], v[8:11]
	v_mfma_f32_16x16x32_bf16 v[60:63], v[146:149], v[178:181], v[60:63]
	v_mfma_f32_16x16x32_bf16 v[56:59], v[154:157], v[178:181], v[56:59]
	v_mfma_f32_16x16x32_bf16 v[44:47], v[146:149], v[186:189], v[44:47]
	v_mfma_f32_16x16x32_bf16 v[40:43], v[154:157], v[186:189], v[40:43]
	v_mfma_f32_16x16x32_bf16 v[28:31], v[146:149], v[194:197], v[28:31]
	v_mfma_f32_16x16x32_bf16 v[24:27], v[154:157], v[194:197], v[24:27]
	v_mfma_f32_16x16x32_bf16 v[12:15], v[146:149], v[202:205], v[12:15]
	v_mfma_f32_16x16x32_bf16 v[8:11], v[154:157], v[202:205], v[8:11]
	v_mfma_f32_16x16x32_bf16 v[52:55], v[158:161], v[174:177], v[52:55]
	v_mfma_f32_16x16x32_bf16 v[48:51], v[166:169], v[174:177], v[48:51]
	v_mfma_f32_16x16x32_bf16 v[36:39], v[158:161], v[182:185], v[36:39]
	v_mfma_f32_16x16x32_bf16 v[32:35], v[166:169], v[182:185], v[32:35]
	v_mfma_f32_16x16x32_bf16 v[20:23], v[158:161], v[190:193], v[20:23]
	v_mfma_f32_16x16x32_bf16 v[16:19], v[166:169], v[190:193], v[16:19]
	v_mfma_f32_16x16x32_bf16 v[4:7], v[158:161], v[198:201], v[4:7]
	v_mfma_f32_16x16x32_bf16 v[0:3], v[166:169], v[198:201], v[0:3]
	v_mfma_f32_16x16x32_bf16 v[52:55], v[162:165], v[178:181], v[52:55]
	v_mfma_f32_16x16x32_bf16 v[48:51], v[170:173], v[178:181], v[48:51]
	v_mfma_f32_16x16x32_bf16 v[36:39], v[162:165], v[186:189], v[36:39]
	v_mfma_f32_16x16x32_bf16 v[32:35], v[170:173], v[186:189], v[32:35]
	v_mfma_f32_16x16x32_bf16 v[20:23], v[162:165], v[194:197], v[20:23]
	v_mfma_f32_16x16x32_bf16 v[16:19], v[170:173], v[194:197], v[16:19]
	v_mfma_f32_16x16x32_bf16 v[4:7], v[162:165], v[202:205], v[4:7]
	v_mfma_f32_16x16x32_bf16 v[0:3], v[170:173], v[202:205], v[0:3]
	s_barrier
	s_add_i32 s28, 0, 0x18000
	s_add_i32 s29, 0, 0x1c000
	v_add_u32_e32 v154, s28, v143
	v_add_u32_e32 v170, s29, v143
	ds_read_b128 v[138:141], v154
	ds_read_b128 v[146:149], v154 offset:1024
	ds_read_b128 v[150:153], v154 offset:2048
	ds_read_b128 v[154:157], v154 offset:3072
	ds_read_b128 v[158:161], v170
	ds_read_b128 v[162:165], v170 offset:1024
	ds_read_b128 v[166:169], v170 offset:2048
	ds_read_b128 v[170:173], v170 offset:3072
	s_add_u32 s24, s24, 0x40000
	s_addc_u32 s25, s25, 0
	s_mov_b32 m0, s19
	v_lshl_add_u64 v[224:225], s[24:25], 0, v[132:133]
	ds_read_b128 v[174:177], v145 offset:32768
	ds_read_b128 v[178:181], v145 offset:33792
	ds_read_b128 v[182:185], v145 offset:34816
	ds_read_b128 v[186:189], v145 offset:35840
	ds_read_b128 v[190:193], v145 offset:36864
	ds_read_b128 v[194:197], v145 offset:37888
	ds_read_b128 v[198:201], v145 offset:38912
	ds_read_b128 v[202:205], v145 offset:39936
	global_load_lds_dwordx4 v[224:225], off
	v_lshl_add_u64 v[224:225], s[24:25], 0, v[130:131]
	s_mov_b32 m0, s34
	s_nop 0
	global_load_lds_dwordx4 v[224:225], off
	s_waitcnt vmcnt(8)
	s_waitcnt lgkmcnt(0)
	s_barrier
	s_waitcnt lgkmcnt(0)
	v_mfma_f32_16x16x32_bf16 v[124:127], v[138:141], v[174:177], v[124:127]
	v_mfma_f32_16x16x32_bf16 v[120:123], v[150:153], v[174:177], v[120:123]
	v_mfma_f32_16x16x32_bf16 v[108:111], v[138:141], v[182:185], v[108:111]
	v_mfma_f32_16x16x32_bf16 v[104:107], v[150:153], v[182:185], v[104:107]
	v_mfma_f32_16x16x32_bf16 v[92:95], v[138:141], v[190:193], v[92:95]
	v_mfma_f32_16x16x32_bf16 v[88:91], v[150:153], v[190:193], v[88:91]
	v_mfma_f32_16x16x32_bf16 v[76:79], v[138:141], v[198:201], v[76:79]
	v_mfma_f32_16x16x32_bf16 v[72:75], v[150:153], v[198:201], v[72:75]
	v_mfma_f32_16x16x32_bf16 v[124:127], v[146:149], v[178:181], v[124:127]
	v_mfma_f32_16x16x32_bf16 v[120:123], v[154:157], v[178:181], v[120:123]
	v_mfma_f32_16x16x32_bf16 v[108:111], v[146:149], v[186:189], v[108:111]
	v_mfma_f32_16x16x32_bf16 v[104:107], v[154:157], v[186:189], v[104:107]
	v_mfma_f32_16x16x32_bf16 v[92:95], v[146:149], v[194:197], v[92:95]
	v_mfma_f32_16x16x32_bf16 v[88:91], v[154:157], v[194:197], v[88:91]
	v_mfma_f32_16x16x32_bf16 v[76:79], v[146:149], v[202:205], v[76:79]
	v_mfma_f32_16x16x32_bf16 v[72:75], v[154:157], v[202:205], v[72:75]
	v_mfma_f32_16x16x32_bf16 v[116:119], v[158:161], v[174:177], v[116:119]
	v_mfma_f32_16x16x32_bf16 v[112:115], v[166:169], v[174:177], v[112:115]
	v_mfma_f32_16x16x32_bf16 v[100:103], v[158:161], v[182:185], v[100:103]
	v_mfma_f32_16x16x32_bf16 v[96:99], v[166:169], v[182:185], v[96:99]
	v_mfma_f32_16x16x32_bf16 v[84:87], v[158:161], v[190:193], v[84:87]
	v_mfma_f32_16x16x32_bf16 v[80:83], v[166:169], v[190:193], v[80:83]
	v_mfma_f32_16x16x32_bf16 v[68:71], v[158:161], v[198:201], v[68:71]
	v_mfma_f32_16x16x32_bf16 v[64:67], v[166:169], v[198:201], v[64:67]
	v_mfma_f32_16x16x32_bf16 v[116:119], v[162:165], v[178:181], v[116:119]
	v_mfma_f32_16x16x32_bf16 v[112:115], v[170:173], v[178:181], v[112:115]
	v_mfma_f32_16x16x32_bf16 v[100:103], v[162:165], v[186:189], v[100:103]
	v_mfma_f32_16x16x32_bf16 v[96:99], v[170:173], v[186:189], v[96:99]
	v_mfma_f32_16x16x32_bf16 v[84:87], v[162:165], v[194:197], v[84:87]
	v_mfma_f32_16x16x32_bf16 v[80:83], v[170:173], v[194:197], v[80:83]
	v_mfma_f32_16x16x32_bf16 v[68:71], v[162:165], v[202:205], v[68:71]
	v_mfma_f32_16x16x32_bf16 v[64:67], v[170:173], v[202:205], v[64:67]
	s_barrier
; #define PG8_STAGE(bufoff, gbase, voff) do { _Pragma("unroll") for (int _i = 0; _i < 2; ++_i) \
;         __builtin_amdgcn_global_load_lds((const unsigned*)((const char*)(gbase) + (voff)[_i]), (PG8_LAS unsigned*)(lds + (bufoff) + ldsw + _i * 8192), 16, 0, 0); } while (0)
; #define PG8_LDA(dst, b, h) do { _Pragma("unroll") for (int m = 0; m < 4; ++m) _Pragma("unroll") for (int k = 0; k < 2; ++k) dst[m][k] = *(const PG8_LAS bf16x8*)(lds + PG8_SA(b, h) + aoff + m * 2048 + k * 1024); } while (0)
; #define PG8_MMA(ai, bj, At, Bt) do { __builtin_amdgcn_s_setprio(1); _Pragma("unroll") for (int m = 0; m < 4; ++m) _Pragma("unroll") for (int n = 0; n < 2; ++n) _Pragma("unroll") for (int k = 0; k < 2; ++k) \
;         acc[ai][bj][m][n] = __builtin_amdgcn_mfma_f32_16x16x32_bf16(Bt[n][k], At[m][k], acc[ai][bj][m][n], 0, 0, 0); __builtin_amdgcn_s_setprio(0); } while (0)
; #define PG8_WAIT_V(n) asm volatile("s_waitcnt vmcnt(" #n ")" ::: "memory")
; #define PG8_WAIT_L(n) asm volatile("s_waitcnt lgkmcnt(" #n ")" ::: "memory")
; #define PG8_BAR __builtin_amdgcn_s_barrier()
; #define PG8_SCHED __builtin_amdgcn_sched_barrier(0)
; template <class Epi, class Sched, bool ALIGN_EPI = false, bool SP2 = false>
; __device__ __forceinline__ void gemm_phase(PG8_LAS unsigned char* lds, const Gemm g, const Sched& S, const Epi& E) {
;     ...
;             PG8_LDA(At, 1, 1); PG8_STAGE(PG8_SB(1, 0), b3, voffB); PG8_STAGE(PG8_SB(1, 1), b3 + hstepB, voffB); PG8_STAGE(PG8_SA(1, 0), a3, voffA);
;             PG8_WAIT_V(8); PG8_WAIT_L(0); PG8_BAR; PG8_MMA(1, 0, At, B0); PG8_MMA(1, 1, At, B1); PG8_BAR; PG8_SCHED;
;     ...
;         }
;         if constexpr (ALIGN_EPI) { if (wr == 0) PG8_BAR; }
	s_add_i32 s24, s28, s26
	v_lshl_add_u64 v[206:207], v[206:207], 0, s[10:11]
	s_mov_b32 m0, s24
	ds_read_b128 v[174:177], v145 offset:49152
	ds_read_b128 v[178:181], v145 offset:50176
	ds_read_b128 v[182:185], v145 offset:51200
	ds_read_b128 v[186:189], v145 offset:52224
	ds_read_b128 v[190:193], v145 offset:53248
	ds_read_b128 v[194:197], v145 offset:54272
	ds_read_b128 v[198:201], v145 offset:55296
	ds_read_b128 v[202:205], v145 offset:56320
	global_load_lds_dwordx4 v[206:207], off
	s_add_i32 m0, s24, 0x2000
	s_add_u32 s22, s22, 0x40080
	v_lshl_add_u64 v[206:207], v[210:211], 0, s[10:11]
	s_addc_u32 s23, s23, 0
	s_add_i32 s24, s29, s26
	global_load_lds_dwordx4 v[206:207], off
	v_lshl_add_u64 v[206:207], s[22:23], 0, v[208:209]
	s_mov_b32 m0, s24
	s_nop 0
	global_load_lds_dwordx4 v[206:207], off
	v_lshl_add_u64 v[206:207], s[22:23], 0, v[128:129]
	s_add_i32 m0, s24, 0x2000
	s_nop 0
	global_load_lds_dwordx4 v[206:207], off
	v_lshl_add_u64 v[206:207], v[212:213], 0, s[10:11]
	s_mov_b32 m0, s35
	s_nop 0
	global_load_lds_dwordx4 v[206:207], off
	v_lshl_add_u64 v[206:207], v[222:223], 0, s[10:11]
	s_mov_b32 m0, s39
	s_nop 0
	global_load_lds_dwordx4 v[206:207], off
	s_waitcnt vmcnt(8)
	s_waitcnt lgkmcnt(0)
	s_barrier
	s_waitcnt lgkmcnt(0)
	v_mfma_f32_16x16x32_bf16 v[60:63], v[138:141], v[174:177], v[60:63]
	v_mfma_f32_16x16x32_bf16 v[56:59], v[150:153], v[174:177], v[56:59]
	v_mfma_f32_16x16x32_bf16 v[44:47], v[138:141], v[182:185], v[44:47]
	v_mfma_f32_16x16x32_bf16 v[40:43], v[150:153], v[182:185], v[40:43]
	v_mfma_f32_16x16x32_bf16 v[28:31], v[138:141], v[190:193], v[28:31]
	v_mfma_f32_16x16x32_bf16 v[24:27], v[150:153], v[190:193], v[24:27]
	v_mfma_f32_16x16x32_bf16 v[12:15], v[138:141], v[198:201], v[12:15]
	v_mfma_f32_16x16x32_bf16 v[8:11], v[150:153], v[198:201], v[8:11]
	v_mfma_f32_16x16x32_bf16 v[60:63], v[146:149], v[178:181], v[60:63]
	v_mfma_f32_16x16x32_bf16 v[56:59], v[154:157], v[178:181], v[56:59]
	v_mfma_f32_16x16x32_bf16 v[44:47], v[146:149], v[186:189], v[44:47]
	v_mfma_f32_16x16x32_bf16 v[40:43], v[154:157], v[186:189], v[40:43]
	v_mfma_f32_16x16x32_bf16 v[28:31], v[146:149], v[194:197], v[28:31]
	v_mfma_f32_16x16x32_bf16 v[24:27], v[154:157], v[194:197], v[24:27]
	v_mfma_f32_16x16x32_bf16 v[12:15], v[146:149], v[202:205], v[12:15]
	v_mfma_f32_16x16x32_bf16 v[8:11], v[154:157], v[202:205], v[8:11]
	v_mfma_f32_16x16x32_bf16 v[52:55], v[158:161], v[174:177], v[52:55]
	v_mfma_f32_16x16x32_bf16 v[48:51], v[166:169], v[174:177], v[48:51]
	v_mfma_f32_16x16x32_bf16 v[36:39], v[158:161], v[182:185], v[36:39]
	v_mfma_f32_16x16x32_bf16 v[32:35], v[166:169], v[182:185], v[32:35]
	v_mfma_f32_16x16x32_bf16 v[20:23], v[158:161], v[190:193], v[20:23]
	v_mfma_f32_16x16x32_bf16 v[16:19], v[166:169], v[190:193], v[16:19]
	v_mfma_f32_16x16x32_bf16 v[4:7], v[158:161], v[198:201], v[4:7]
	v_mfma_f32_16x16x32_bf16 v[0:3], v[166:169], v[198:201], v[0:3]
	v_mfma_f32_16x16x32_bf16 v[52:55], v[162:165], v[178:181], v[52:55]
	v_mfma_f32_16x16x32_bf16 v[48:51], v[170:173], v[178:181], v[48:51]
	v_mfma_f32_16x16x32_bf16 v[36:39], v[162:165], v[186:189], v[36:39]
	v_mfma_f32_16x16x32_bf16 v[32:35], v[170:173], v[186:189], v[32:35]
	v_mfma_f32_16x16x32_bf16 v[20:23], v[162:165], v[194:197], v[20:23]
	v_mfma_f32_16x16x32_bf16 v[16:19], v[170:173], v[194:197], v[16:19]
	v_mfma_f32_16x16x32_bf16 v[4:7], v[162:165], v[202:205], v[4:7]
	v_mfma_f32_16x16x32_bf16 v[0:3], v[170:173], v[202:205], v[0:3]
	s_barrier
	s_add_i32 s51, s51, 2
	s_add_u32 s0, s0, 0x100
	s_addc_u32 s1, s1, 0
	s_add_u32 s43, s43, 0x100
	s_addc_u32 s50, s50, 0
	s_cmp_gt_u32 s51, 13
	s_cbranch_scc0 .LBB0_607
	s_and_b64 vcc, exec, s[6:7]
	s_cbranch_vccz .LBB0_610
	s_barrier

; #define PG8_STAGE(bufoff, gbase, voff) do { _Pragma("unroll") for (int _i = 0; _i < 2; ++_i) \
;         __builtin_amdgcn_global_load_lds((const unsigned*)((const char*)(gbase) + (voff)[_i]), (PG8_LAS unsigned*)(lds + (bufoff) + ldsw + _i * 8192), 16, 0, 0); } while (0)
; #define PG8_LDA(dst, b, h) do { _Pragma("unroll") for (int m = 0; m < 4; ++m) _Pragma("unroll") for (int k = 0; k < 2; ++k) dst[m][k] = *(const PG8_LAS bf16x8*)(lds + PG8_SA(b, h) + aoff + m * 2048 + k * 1024); } while (0)
; #define PG8_LDB(dst, b, h) do { _Pragma("unroll") for (int n = 0; n < 2; ++n) _Pragma("unroll") for (int k = 0; k < 2; ++k) dst[n][k] = *(const PG8_LAS bf16x8*)(lds + PG8_SB(b, h) + boff + n * 2048 + k * 1024); } while (0)
; #define PG8_MMA(ai, bj, At, Bt) do { __builtin_amdgcn_s_setprio(1); _Pragma("unroll") for (int m = 0; m < 4; ++m) _Pragma("unroll") for (int n = 0; n < 2; ++n) _Pragma("unroll") for (int k = 0; k < 2; ++k) \
;         acc[ai][bj][m][n] = __builtin_amdgcn_mfma_f32_16x16x32_bf16(Bt[n][k], At[m][k], acc[ai][bj][m][n], 0, 0, 0); __builtin_amdgcn_s_setprio(0); } while (0)
; #define PG8_WAIT_V(n) asm volatile("s_waitcnt vmcnt(" #n ")" ::: "memory")
; #define PG8_WAIT_L(n) asm volatile("s_waitcnt lgkmcnt(" #n ")" ::: "memory")
; #define PG8_BAR __builtin_amdgcn_s_barrier()
; #define PG8_SCHED __builtin_amdgcn_sched_barrier(0)
; template <class Epi, class Sched, bool ALIGN_EPI = false, bool SP2 = false>
; __device__ __forceinline__ void gemm_phase(PG8_LAS unsigned char* lds, const Gemm g, const Sched& S, const Epi& E) {
;     ...
;             const bool last = (t == nt - 2);
;             const char* a1 = cA + (size_t)(t + 1) * kstep;
;             const char* a2 = last ? nA : cA + (size_t)(t + 2) * kstep; const char* b2 = last ? nB : cB + (size_t)(t + 2) * kstep;
;             const char* a3 = a2 + kstep; const char* b3 = b2 + kstep;
;             if (last && has_next) S.a_ready(nxt);
;             if constexpr (SP2) {
;             PG8_LDB(B0, 0, 0); PG8_LDB(B1, 0, 1); PG8_SCHED; PG8_LDA(At, 0, 0); PG8_STAGE(PG8_SA(1, 1), a1 + hstepA, voffA);
;             PG8_WAIT_V(8); PG8_WAIT_L(0); PG8_BAR; PG8_MMA(0, 0, At, B0); PG8_MMA(0, 1, At, B1); PG8_BAR; PG8_SCHED;
;             PG8_LDA(At, 0, 1); PG8_STAGE(PG8_SB(0, 0), b2, voffB); PG8_STAGE(PG8_SB(0, 1), b2 + hstepB, voffB); PG8_STAGE(PG8_SA(0, 0), a2, voffA);
.LBB0_690:
	s_add_u32 s4, s0, 0x100
	s_addc_u32 s5, s1, 0
	s_add_i32 s28, 0, 0x10000
	s_cmp_eq_u32 s34, 4
	s_cselect_b32 s23, s49, s5
	s_cselect_b32 s22, s48, s4
	s_cselect_b32 s21, s14, s19
	s_cselect_b32 s20, s15, s18
	s_add_i32 s29, 0, 0x14000
	v_add_u32_e32 v140, s28, v211
	v_add_u32_e32 v156, s29, v211
	ds_read_b128 v[128:131], v140
	ds_read_b128 v[132:135], v140 offset:1024
	ds_read_b128 v[136:139], v140 offset:2048
	ds_read_b128 v[140:143], v140 offset:3072
	ds_read_b128 v[144:147], v156
	ds_read_b128 v[148:151], v156 offset:1024
	ds_read_b128 v[152:155], v156 offset:2048
	ds_read_b128 v[156:159], v156 offset:3072
	v_lshl_add_u64 v[202:203], s[0:1], 0, v[198:199]
	s_add_i32 m0, s53, 0xc000
	ds_read_b128 v[160:163], v231
	ds_read_b128 v[164:167], v231 offset:1024
	ds_read_b128 v[168:171], v231 offset:2048
	ds_read_b128 v[172:175], v231 offset:3072
	ds_read_b128 v[176:179], v231 offset:4096
	ds_read_b128 v[180:183], v231 offset:5120
	ds_read_b128 v[184:187], v231 offset:6144
	ds_read_b128 v[188:191], v231 offset:7168
	global_load_lds_dwordx4 v[202:203], off
	v_lshl_add_u64 v[202:203], s[0:1], 0, v[200:201]
	s_add_i32 m0, s53, 0xe000
	s_nop 0
	global_load_lds_dwordx4 v[202:203], off
	s_waitcnt vmcnt(8)
	s_waitcnt lgkmcnt(0)
	s_barrier
	s_waitcnt lgkmcnt(0)
	v_mfma_f32_16x16x32_bf16 v[124:127], v[128:131], v[160:163], v[124:127]
	v_mfma_f32_16x16x32_bf16 v[120:123], v[136:139], v[160:163], v[120:123]
	v_mfma_f32_16x16x32_bf16 v[112:115], v[128:131], v[168:171], v[112:115]
	v_mfma_f32_16x16x32_bf16 v[104:107], v[136:139], v[168:171], v[104:107]
	v_mfma_f32_16x16x32_bf16 v[96:99], v[128:131], v[176:179], v[96:99]
	v_mfma_f32_16x16x32_bf16 v[88:91], v[136:139], v[176:179], v[88:91]
	v_mfma_f32_16x16x32_bf16 v[80:83], v[128:131], v[184:187], v[80:83]
	v_mfma_f32_16x16x32_bf16 v[72:75], v[136:139], v[184:187], v[72:75]
	v_mfma_f32_16x16x32_bf16 v[124:127], v[132:135], v[164:167], v[124:127]
	v_mfma_f32_16x16x32_bf16 v[120:123], v[140:143], v[164:167], v[120:123]
	v_mfma_f32_16x16x32_bf16 v[112:115], v[132:135], v[172:175], v[112:115]
	v_mfma_f32_16x16x32_bf16 v[104:107], v[140:143], v[172:175], v[104:107]
	v_mfma_f32_16x16x32_bf16 v[96:99], v[132:135], v[180:183], v[96:99]
	v_mfma_f32_16x16x32_bf16 v[88:91], v[140:143], v[180:183], v[88:91]
	v_mfma_f32_16x16x32_bf16 v[80:83], v[132:135], v[188:191], v[80:83]
	v_mfma_f32_16x16x32_bf16 v[72:75], v[140:143], v[188:191], v[72:75]
	v_mfma_f32_16x16x32_bf16 v[116:119], v[144:147], v[160:163], v[116:119]
	v_mfma_f32_16x16x32_bf16 v[108:111], v[152:155], v[160:163], v[108:111]
	v_mfma_f32_16x16x32_bf16 v[100:103], v[144:147], v[168:171], v[100:103]
	v_mfma_f32_16x16x32_bf16 v[92:95], v[152:155], v[168:171], v[92:95]
	v_mfma_f32_16x16x32_bf16 v[84:87], v[144:147], v[176:179], v[84:87]
	v_mfma_f32_16x16x32_bf16 v[76:79], v[152:155], v[176:179], v[76:79]
	v_mfma_f32_16x16x32_bf16 v[68:71], v[144:147], v[184:187], v[68:71]
	v_mfma_f32_16x16x32_bf16 v[64:67], v[152:155], v[184:187], v[64:67]
	v_mfma_f32_16x16x32_bf16 v[116:119], v[148:151], v[164:167], v[116:119]
	v_mfma_f32_16x16x32_bf16 v[108:111], v[156:159], v[164:167], v[108:111]
	v_mfma_f32_16x16x32_bf16 v[100:103], v[148:151], v[172:175], v[100:103]
	v_mfma_f32_16x16x32_bf16 v[92:95], v[156:159], v[172:175], v[92:95]
	v_mfma_f32_16x16x32_bf16 v[84:87], v[148:151], v[180:183], v[84:87]
	v_mfma_f32_16x16x32_bf16 v[76:79], v[156:159], v[180:183], v[76:79]
	v_mfma_f32_16x16x32_bf16 v[68:71], v[148:151], v[188:191], v[68:71]
	v_mfma_f32_16x16x32_bf16 v[64:67], v[156:159], v[188:191], v[64:67]
	s_barrier
	s_add_i32 s0, s28, s56
	v_lshl_add_u64 v[202:203], s[20:21], 0, v[208:209]
	s_mov_b32 m0, s0
	ds_read_b128 v[160:163], v231 offset:16384
	ds_read_b128 v[164:167], v231 offset:17408
	ds_read_b128 v[168:171], v231 offset:18432
	ds_read_b128 v[172:175], v231 offset:19456
	ds_read_b128 v[176:179], v231 offset:20480
	ds_read_b128 v[180:183], v231 offset:21504
	ds_read_b128 v[184:187], v231 offset:22528
	ds_read_b128 v[188:191], v231 offset:23552
	global_load_lds_dwordx4 v[202:203], off
	s_add_i32 m0, s0, 0x2000
	s_add_u32 s0, s20, 0x20000
	v_lshl_add_u64 v[204:205], s[20:21], 0, v[196:197]
	s_addc_u32 s1, s21, 0
	s_add_i32 s28, s29, s56
	global_load_lds_dwordx4 v[204:205], off
	v_lshl_add_u64 v[206:207], s[0:1], 0, v[208:209]
	s_mov_b32 m0, s28
	v_lshl_add_u64 v[212:213], s[22:23], 0, v[194:195]
	global_load_lds_dwordx4 v[206:207], off
	v_lshl_add_u64 v[206:207], s[0:1], 0, v[196:197]
	s_add_i32 m0, s28, 0x2000
	s_nop 0
	global_load_lds_dwordx4 v[206:207], off
	v_lshl_add_u64 v[206:207], s[22:23], 0, v[192:193]
	s_mov_b32 m0, s53
	s_nop 0
	global_load_lds_dwordx4 v[206:207], off
	s_mov_b32 m0, s57
	s_nop 0
	global_load_lds_dwordx4 v[212:213], off
	s_waitcnt vmcnt(8)
	s_waitcnt lgkmcnt(0)
	s_barrier
; #define PG8_STAGE(bufoff, gbase, voff) do { _Pragma("unroll") for (int _i = 0; _i < 2; ++_i) \
;         __builtin_amdgcn_global_load_lds((const unsigned*)((const char*)(gbase) + (voff)[_i]), (PG8_LAS unsigned*)(lds + (bufoff) + ldsw + _i * 8192), 16, 0, 0); } while (0)
; #define PG8_LDA(dst, b, h) do { _Pragma("unroll") for (int m = 0; m < 4; ++m) _Pragma("unroll") for (int k = 0; k < 2; ++k) dst[m][k] = *(const PG8_LAS bf16x8*)(lds + PG8_SA(b, h) + aoff + m * 2048 + k * 1024); } while (0)
; #define PG8_LDB(dst, b, h) do { _Pragma("unroll") for (int n = 0; n < 2; ++n) _Pragma("unroll") for (int k = 0; k < 2; ++k) dst[n][k] = *(const PG8_LAS bf16x8*)(lds + PG8_SB(b, h) + boff + n * 2048 + k * 1024); } while (0)
; #define PG8_MMA(ai, bj, At, Bt) do { __builtin_amdgcn_s_setprio(1); _Pragma("unroll") for (int m = 0; m < 4; ++m) _Pragma("unroll") for (int n = 0; n < 2; ++n) _Pragma("unroll") for (int k = 0; k < 2; ++k) \
;         acc[ai][bj][m][n] = __builtin_amdgcn_mfma_f32_16x16x32_bf16(Bt[n][k], At[m][k], acc[ai][bj][m][n], 0, 0, 0); __builtin_amdgcn_s_setprio(0); } while (0)
; #define PG8_WAIT_V(n) asm volatile("s_waitcnt vmcnt(" #n ")" ::: "memory")
; #define PG8_WAIT_L(n) asm volatile("s_waitcnt lgkmcnt(" #n ")" ::: "memory")
; #define PG8_BAR __builtin_amdgcn_s_barrier()
; #define PG8_SCHED __builtin_amdgcn_sched_barrier(0)
; template <class Epi, class Sched, bool ALIGN_EPI = false, bool SP2 = false>
; __device__ __forceinline__ void gemm_phase(PG8_LAS unsigned char* lds, const Gemm g, const Sched& S, const Epi& E) {
;     ...
;             PG8_WAIT_V(8); PG8_WAIT_L(0); PG8_BAR; PG8_MMA(1, 0, At, B0); PG8_MMA(1, 1, At, B1); PG8_BAR; PG8_SCHED;
;             PG8_LDB(B0, 1, 0); PG8_LDB(B1, 1, 1); PG8_SCHED; PG8_LDA(At, 1, 0); PG8_STAGE(PG8_SA(0, 1), a2 + hstepA, voffA);
;             PG8_WAIT_V(8); PG8_WAIT_L(0); PG8_BAR; PG8_MMA(0, 0, At, B0); PG8_MMA(0, 1, At, B1); PG8_BAR; PG8_SCHED;
	s_waitcnt lgkmcnt(0)
	v_mfma_f32_16x16x32_bf16 v[60:63], v[128:131], v[160:163], v[60:63]
	v_mfma_f32_16x16x32_bf16 v[56:59], v[136:139], v[160:163], v[56:59]
	v_mfma_f32_16x16x32_bf16 v[48:51], v[128:131], v[168:171], v[48:51]
	v_mfma_f32_16x16x32_bf16 v[40:43], v[136:139], v[168:171], v[40:43]
	v_mfma_f32_16x16x32_bf16 v[32:35], v[128:131], v[176:179], v[32:35]
	v_mfma_f32_16x16x32_bf16 v[24:27], v[136:139], v[176:179], v[24:27]
	v_mfma_f32_16x16x32_bf16 v[16:19], v[128:131], v[184:187], v[16:19]
	v_mfma_f32_16x16x32_bf16 v[8:11], v[136:139], v[184:187], v[8:11]
	v_mfma_f32_16x16x32_bf16 v[60:63], v[132:135], v[164:167], v[60:63]
	v_mfma_f32_16x16x32_bf16 v[56:59], v[140:143], v[164:167], v[56:59]
	v_mfma_f32_16x16x32_bf16 v[48:51], v[132:135], v[172:175], v[48:51]
	v_mfma_f32_16x16x32_bf16 v[40:43], v[140:143], v[172:175], v[40:43]
	v_mfma_f32_16x16x32_bf16 v[32:35], v[132:135], v[180:183], v[32:35]
	v_mfma_f32_16x16x32_bf16 v[24:27], v[140:143], v[180:183], v[24:27]
	v_mfma_f32_16x16x32_bf16 v[16:19], v[132:135], v[188:191], v[16:19]
	v_mfma_f32_16x16x32_bf16 v[8:11], v[140:143], v[188:191], v[8:11]
	v_mfma_f32_16x16x32_bf16 v[52:55], v[144:147], v[160:163], v[52:55]
	v_mfma_f32_16x16x32_bf16 v[44:47], v[152:155], v[160:163], v[44:47]
	v_mfma_f32_16x16x32_bf16 v[36:39], v[144:147], v[168:171], v[36:39]
	v_mfma_f32_16x16x32_bf16 v[28:31], v[152:155], v[168:171], v[28:31]
	v_mfma_f32_16x16x32_bf16 v[20:23], v[144:147], v[176:179], v[20:23]
	v_mfma_f32_16x16x32_bf16 v[12:15], v[152:155], v[176:179], v[12:15]
	v_mfma_f32_16x16x32_bf16 v[4:7], v[144:147], v[184:187], v[4:7]
	v_mfma_f32_16x16x32_bf16 v[0:3], v[152:155], v[184:187], v[0:3]
	v_mfma_f32_16x16x32_bf16 v[52:55], v[148:151], v[164:167], v[52:55]
	v_mfma_f32_16x16x32_bf16 v[44:47], v[156:159], v[164:167], v[44:47]
	v_mfma_f32_16x16x32_bf16 v[36:39], v[148:151], v[172:175], v[36:39]
	v_mfma_f32_16x16x32_bf16 v[28:31], v[156:159], v[172:175], v[28:31]
	v_mfma_f32_16x16x32_bf16 v[20:23], v[148:151], v[180:183], v[20:23]
	v_mfma_f32_16x16x32_bf16 v[12:15], v[156:159], v[180:183], v[12:15]
	v_mfma_f32_16x16x32_bf16 v[4:7], v[148:151], v[188:191], v[4:7]
	v_mfma_f32_16x16x32_bf16 v[0:3], v[156:159], v[188:191], v[0:3]
	s_barrier
	s_add_i32 s28, 0, 0x18000
	s_add_i32 s29, 0, 0x1c000
	v_add_u32_e32 v140, s28, v211
	v_add_u32_e32 v156, s29, v211
	ds_read_b128 v[128:131], v140
	ds_read_b128 v[132:135], v140 offset:1024
	ds_read_b128 v[136:139], v140 offset:2048
	ds_read_b128 v[140:143], v140 offset:3072
	ds_read_b128 v[144:147], v156
	ds_read_b128 v[148:151], v156 offset:1024
	ds_read_b128 v[152:155], v156 offset:2048
	ds_read_b128 v[156:159], v156 offset:3072
	s_add_u32 s0, s22, 0x60000
	s_addc_u32 s1, s23, 0
	s_mov_b32 m0, s58
	v_lshl_add_u64 v[222:223], s[0:1], 0, v[192:193]
	ds_read_b128 v[160:163], v231 offset:32768
	ds_read_b128 v[164:167], v231 offset:33792
	ds_read_b128 v[168:171], v231 offset:34816
	ds_read_b128 v[172:175], v231 offset:35840
	ds_read_b128 v[176:179], v231 offset:36864
	ds_read_b128 v[180:183], v231 offset:37888
	ds_read_b128 v[184:187], v231 offset:38912
	ds_read_b128 v[188:191], v231 offset:39936
	global_load_lds_dwordx4 v[222:223], off
	v_lshl_add_u64 v[222:223], s[0:1], 0, v[194:195]
	s_mov_b32 m0, s59
	s_nop 0
	global_load_lds_dwordx4 v[222:223], off
	s_waitcnt vmcnt(8)
	s_waitcnt lgkmcnt(0)
	s_barrier
	s_waitcnt lgkmcnt(0)
	v_mfma_f32_16x16x32_bf16 v[124:127], v[128:131], v[160:163], v[124:127]
	v_mfma_f32_16x16x32_bf16 v[120:123], v[136:139], v[160:163], v[120:123]
	v_mfma_f32_16x16x32_bf16 v[112:115], v[128:131], v[168:171], v[112:115]
	v_mfma_f32_16x16x32_bf16 v[104:107], v[136:139], v[168:171], v[104:107]
	v_mfma_f32_16x16x32_bf16 v[96:99], v[128:131], v[176:179], v[96:99]
	v_mfma_f32_16x16x32_bf16 v[88:91], v[136:139], v[176:179], v[88:91]
	v_mfma_f32_16x16x32_bf16 v[80:83], v[128:131], v[184:187], v[80:83]
	v_mfma_f32_16x16x32_bf16 v[72:75], v[136:139], v[184:187], v[72:75]
	v_mfma_f32_16x16x32_bf16 v[124:127], v[132:135], v[164:167], v[124:127]
	v_mfma_f32_16x16x32_bf16 v[120:123], v[140:143], v[164:167], v[120:123]
	v_mfma_f32_16x16x32_bf16 v[112:115], v[132:135], v[172:175], v[112:115]
	v_mfma_f32_16x16x32_bf16 v[104:107], v[140:143], v[172:175], v[104:107]
	v_mfma_f32_16x16x32_bf16 v[96:99], v[132:135], v[180:183], v[96:99]
	v_mfma_f32_16x16x32_bf16 v[88:91], v[140:143], v[180:183], v[88:91]
	v_mfma_f32_16x16x32_bf16 v[80:83], v[132:135], v[188:191], v[80:83]
	v_mfma_f32_16x16x32_bf16 v[72:75], v[140:143], v[188:191], v[72:75]
	v_mfma_f32_16x16x32_bf16 v[116:119], v[144:147], v[160:163], v[116:119]
	v_mfma_f32_16x16x32_bf16 v[108:111], v[152:155], v[160:163], v[108:111]
	v_mfma_f32_16x16x32_bf16 v[100:103], v[144:147], v[168:171], v[100:103]
	v_mfma_f32_16x16x32_bf16 v[92:95], v[152:155], v[168:171], v[92:95]
	v_mfma_f32_16x16x32_bf16 v[84:87], v[144:147], v[176:179], v[84:87]
	v_mfma_f32_16x16x32_bf16 v[76:79], v[152:155], v[176:179], v[76:79]
	v_mfma_f32_16x16x32_bf16 v[68:71], v[144:147], v[184:187], v[68:71]
	v_mfma_f32_16x16x32_bf16 v[64:67], v[152:155], v[184:187], v[64:67]
	v_mfma_f32_16x16x32_bf16 v[116:119], v[148:151], v[164:167], v[116:119]
	v_mfma_f32_16x16x32_bf16 v[108:111], v[156:159], v[164:167], v[108:111]
	v_mfma_f32_16x16x32_bf16 v[100:103], v[148:151], v[172:175], v[100:103]
	v_mfma_f32_16x16x32_bf16 v[92:95], v[156:159], v[172:175], v[92:95]
	v_mfma_f32_16x16x32_bf16 v[84:87], v[148:151], v[180:183], v[84:87]
	v_mfma_f32_16x16x32_bf16 v[76:79], v[156:159], v[180:183], v[76:79]
	v_mfma_f32_16x16x32_bf16 v[68:71], v[148:151], v[188:191], v[68:71]
	v_mfma_f32_16x16x32_bf16 v[64:67], v[156:159], v[188:191], v[64:67]
	s_barrier
; #define PG8_STAGE(bufoff, gbase, voff) do { _Pragma("unroll") for (int _i = 0; _i < 2; ++_i) \
;         __builtin_amdgcn_global_load_lds((const unsigned*)((const char*)(gbase) + (voff)[_i]), (PG8_LAS unsigned*)(lds + (bufoff) + ldsw + _i * 8192), 16, 0, 0); } while (0)
; #define PG8_LDA(dst, b, h) do { _Pragma("unroll") for (int m = 0; m < 4; ++m) _Pragma("unroll") for (int k = 0; k < 2; ++k) dst[m][k] = *(const PG8_LAS bf16x8*)(lds + PG8_SA(b, h) + aoff + m * 2048 + k * 1024); } while (0)
; #define PG8_MMA(ai, bj, At, Bt) do { __builtin_amdgcn_s_setprio(1); _Pragma("unroll") for (int m = 0; m < 4; ++m) _Pragma("unroll") for (int n = 0; n < 2; ++n) _Pragma("unroll") for (int k = 0; k < 2; ++k) \
;         acc[ai][bj][m][n] = __builtin_amdgcn_mfma_f32_16x16x32_bf16(Bt[n][k], At[m][k], acc[ai][bj][m][n], 0, 0, 0); __builtin_amdgcn_s_setprio(0); } while (0)
; #define PG8_WAIT_V(n) asm volatile("s_waitcnt vmcnt(" #n ")" ::: "memory")
; #define PG8_WAIT_L(n) asm volatile("s_waitcnt lgkmcnt(" #n ")" ::: "memory")
; #define PG8_BAR __builtin_amdgcn_s_barrier()
; #define PG8_SCHED __builtin_amdgcn_sched_barrier(0)
; template <class Epi, class Sched, bool ALIGN_EPI = false, bool SP2 = false>
; __device__ __forceinline__ void gemm_phase(PG8_LAS unsigned char* lds, const Gemm g, const Sched& S, const Epi& E) {
;     ...
;             PG8_LDA(At, 1, 1); PG8_STAGE(PG8_SB(1, 0), b3, voffB); PG8_STAGE(PG8_SB(1, 1), b3 + hstepB, voffB); PG8_STAGE(PG8_SA(1, 0), a3, voffA);
;             PG8_WAIT_V(8); PG8_WAIT_L(0); PG8_BAR; PG8_MMA(1, 0, At, B0); PG8_MMA(1, 1, At, B1); PG8_BAR; PG8_SCHED;
;     ...
;         }
;         if constexpr (ALIGN_EPI) { if (wr == 0) PG8_BAR; }
	s_add_i32 s0, s28, s56
	v_lshl_add_u64 v[202:203], v[202:203], 0, s[10:11]
	s_mov_b32 m0, s0
	ds_read_b128 v[160:163], v231 offset:49152
	ds_read_b128 v[164:167], v231 offset:50176
	ds_read_b128 v[168:171], v231 offset:51200
	ds_read_b128 v[172:175], v231 offset:52224
	ds_read_b128 v[176:179], v231 offset:53248
	ds_read_b128 v[180:183], v231 offset:54272
	ds_read_b128 v[184:187], v231 offset:55296
	ds_read_b128 v[188:191], v231 offset:56320
	global_load_lds_dwordx4 v[202:203], off
	s_add_i32 m0, s0, 0x2000
	s_add_u32 s0, s20, 0x20080
	v_lshl_add_u64 v[202:203], v[204:205], 0, s[10:11]
	s_addc_u32 s1, s21, 0
	s_add_i32 s20, s29, s56
	global_load_lds_dwordx4 v[202:203], off
	v_lshl_add_u64 v[202:203], s[0:1], 0, v[208:209]
	s_mov_b32 m0, s20
	s_nop 0
	global_load_lds_dwordx4 v[202:203], off
	v_lshl_add_u64 v[202:203], s[0:1], 0, v[196:197]
	s_add_i32 m0, s20, 0x2000
	s_nop 0
	global_load_lds_dwordx4 v[202:203], off
	v_lshl_add_u64 v[202:203], v[206:207], 0, s[10:11]
	s_mov_b32 m0, s61
	s_nop 0
	global_load_lds_dwordx4 v[202:203], off
	v_lshl_add_u64 v[202:203], v[212:213], 0, s[10:11]
	s_mov_b32 m0, s62
	s_nop 0
	global_load_lds_dwordx4 v[202:203], off
	s_waitcnt vmcnt(8)
	s_waitcnt lgkmcnt(0)
	s_barrier
	s_waitcnt lgkmcnt(0)
	v_mfma_f32_16x16x32_bf16 v[60:63], v[128:131], v[160:163], v[60:63]
	v_mfma_f32_16x16x32_bf16 v[56:59], v[136:139], v[160:163], v[56:59]
	v_mfma_f32_16x16x32_bf16 v[48:51], v[128:131], v[168:171], v[48:51]
	v_mfma_f32_16x16x32_bf16 v[40:43], v[136:139], v[168:171], v[40:43]
	v_mfma_f32_16x16x32_bf16 v[32:35], v[128:131], v[176:179], v[32:35]
	v_mfma_f32_16x16x32_bf16 v[24:27], v[136:139], v[176:179], v[24:27]
	v_mfma_f32_16x16x32_bf16 v[16:19], v[128:131], v[184:187], v[16:19]
	v_mfma_f32_16x16x32_bf16 v[8:11], v[136:139], v[184:187], v[8:11]
	v_mfma_f32_16x16x32_bf16 v[60:63], v[132:135], v[164:167], v[60:63]
	v_mfma_f32_16x16x32_bf16 v[56:59], v[140:143], v[164:167], v[56:59]
	v_mfma_f32_16x16x32_bf16 v[48:51], v[132:135], v[172:175], v[48:51]
	v_mfma_f32_16x16x32_bf16 v[40:43], v[140:143], v[172:175], v[40:43]
	v_mfma_f32_16x16x32_bf16 v[32:35], v[132:135], v[180:183], v[32:35]
	v_mfma_f32_16x16x32_bf16 v[24:27], v[140:143], v[180:183], v[24:27]
	v_mfma_f32_16x16x32_bf16 v[16:19], v[132:135], v[188:191], v[16:19]
	v_mfma_f32_16x16x32_bf16 v[8:11], v[140:143], v[188:191], v[8:11]
	v_mfma_f32_16x16x32_bf16 v[52:55], v[144:147], v[160:163], v[52:55]
	v_mfma_f32_16x16x32_bf16 v[44:47], v[152:155], v[160:163], v[44:47]
	v_mfma_f32_16x16x32_bf16 v[36:39], v[144:147], v[168:171], v[36:39]
	v_mfma_f32_16x16x32_bf16 v[28:31], v[152:155], v[168:171], v[28:31]
	v_mfma_f32_16x16x32_bf16 v[20:23], v[144:147], v[176:179], v[20:23]
	v_mfma_f32_16x16x32_bf16 v[12:15], v[152:155], v[176:179], v[12:15]
	v_mfma_f32_16x16x32_bf16 v[4:7], v[144:147], v[184:187], v[4:7]
	v_mfma_f32_16x16x32_bf16 v[0:3], v[152:155], v[184:187], v[0:3]
	v_mfma_f32_16x16x32_bf16 v[52:55], v[148:151], v[164:167], v[52:55]
	v_mfma_f32_16x16x32_bf16 v[44:47], v[156:159], v[164:167], v[44:47]
	v_mfma_f32_16x16x32_bf16 v[36:39], v[148:151], v[172:175], v[36:39]
	v_mfma_f32_16x16x32_bf16 v[28:31], v[156:159], v[172:175], v[28:31]
	v_mfma_f32_16x16x32_bf16 v[20:23], v[148:151], v[180:183], v[20:23]
	v_mfma_f32_16x16x32_bf16 v[12:15], v[156:159], v[180:183], v[12:15]
	v_mfma_f32_16x16x32_bf16 v[4:7], v[148:151], v[188:191], v[4:7]
	v_mfma_f32_16x16x32_bf16 v[0:3], v[156:159], v[188:191], v[0:3]
	s_barrier
	s_add_i32 s34, s34, 2
	s_add_u32 s18, s18, 0x100
	s_addc_u32 s19, s19, 0
	s_cmp_gt_u32 s34, 5
	s_mov_b64 s[0:1], s[4:5]
	s_cbranch_scc0 .LBB0_690
	s_and_b64 vcc, exec, s[44:45]
	s_cbranch_vccz .LBB0_693
	s_barrier

; #define PG8_STAGE(bufoff, gbase, voff) do { _Pragma("unroll") for (int _i = 0; _i < 2; ++_i) \
;         __builtin_amdgcn_global_load_lds((const unsigned*)((const char*)(gbase) + (voff)[_i]), (PG8_LAS unsigned*)(lds + (bufoff) + ldsw + _i * 8192), 16, 0, 0); } while (0)
; #define PG8_LDA(dst, b, h) do { _Pragma("unroll") for (int m = 0; m < 4; ++m) _Pragma("unroll") for (int k = 0; k < 2; ++k) dst[m][k] = *(const PG8_LAS bf16x8*)(lds + PG8_SA(b, h) + aoff + m * 2048 + k * 1024); } while (0)
; #define PG8_LDB(dst, b, h) do { _Pragma("unroll") for (int n = 0; n < 2; ++n) _Pragma("unroll") for (int k = 0; k < 2; ++k) dst[n][k] = *(const PG8_LAS bf16x8*)(lds + PG8_SB(b, h) + boff + n * 2048 + k * 1024); } while (0)
; #define PG8_MMA(ai, bj, At, Bt) do { __builtin_amdgcn_s_setprio(1); _Pragma("unroll") for (int m = 0; m < 4; ++m) _Pragma("unroll") for (int n = 0; n < 2; ++n) _Pragma("unroll") for (int k = 0; k < 2; ++k) \
;         acc[ai][bj][m][n] = __builtin_amdgcn_mfma_f32_16x16x32_bf16(Bt[n][k], At[m][k], acc[ai][bj][m][n], 0, 0, 0); __builtin_amdgcn_s_setprio(0); } while (0)
; #define PG8_WAIT_V(n) asm volatile("s_waitcnt vmcnt(" #n ")" ::: "memory")
; #define PG8_WAIT_L(n) asm volatile("s_waitcnt lgkmcnt(" #n ")" ::: "memory")
; #define PG8_BAR __builtin_amdgcn_s_barrier()
; #define PG8_SCHED __builtin_amdgcn_sched_barrier(0)
; template <class Epi, class Sched, bool ALIGN_EPI = false, bool SP2 = false>
; __device__ __forceinline__ void gemm_phase(PG8_LAS unsigned char* lds, const Gemm g, const Sched& S, const Epi& E) {
;     ...
;             const bool last = (t == nt - 2);
;             const char* a1 = cA + (size_t)(t + 1) * kstep;
;             const char* a2 = last ? nA : cA + (size_t)(t + 2) * kstep; const char* b2 = last ? nB : cB + (size_t)(t + 2) * kstep;
;             const char* a3 = a2 + kstep; const char* b3 = b2 + kstep;
;             if (last && has_next) S.a_ready(nxt);
;             if constexpr (SP2) {
;             PG8_LDB(B0, 0, 0); PG8_LDB(B1, 0, 1); PG8_SCHED; PG8_LDA(At, 0, 0); PG8_STAGE(PG8_SA(1, 1), a1 + hstepA, voffA);
;             PG8_WAIT_V(8); PG8_WAIT_L(0); PG8_BAR; PG8_MMA(0, 0, At, B0); PG8_MMA(0, 1, At, B1); PG8_BAR; PG8_SCHED;
;             PG8_LDA(At, 0, 1); PG8_STAGE(PG8_SB(0, 0), b2, voffB); PG8_STAGE(PG8_SB(0, 1), b2 + hstepB, voffB); PG8_STAGE(PG8_SA(0, 0), a2, voffA);
.LBB0_797:
	s_add_u32 s22, s0, 0xfffc0080
	s_addc_u32 s23, s1, -1
	s_add_i32 s28, 0, 0x10000
	s_cmp_eq_u32 s51, 12
	s_cselect_b32 s25, s14, s23
	s_cselect_b32 s24, s15, s22
	v_add_u32_e32 v138, s28, v141
	s_cselect_b32 s23, s9, s50
	s_cselect_b32 s22, s38, s43
	s_add_i32 s30, 0, 0x14000
	ds_read_b128 v[134:137], v138
	ds_read_b128 v[144:147], v138 offset:1024
	ds_read_b128 v[148:151], v138 offset:2048
	ds_read_b128 v[152:155], v138 offset:3072
	v_add_u32_e32 v138, s30, v141
	ds_read_b128 v[156:159], v138
	ds_read_b128 v[160:163], v138 offset:1024
	ds_read_b128 v[164:167], v138 offset:2048
	ds_read_b128 v[168:171], v138 offset:3072
	v_lshl_add_u64 v[138:139], s[0:1], 0, v[130:131]
	s_add_i32 m0, s21, 0xc000
	ds_read_b128 v[172:175], v143
	ds_read_b128 v[176:179], v143 offset:1024
	ds_read_b128 v[180:183], v143 offset:2048
	ds_read_b128 v[184:187], v143 offset:3072
	ds_read_b128 v[188:191], v143 offset:4096
	ds_read_b128 v[192:195], v143 offset:5120
	ds_read_b128 v[196:199], v143 offset:6144
	ds_read_b128 v[200:203], v143 offset:7168
	global_load_lds_dwordx4 v[138:139], off
	v_lshl_add_u64 v[138:139], s[0:1], 0, v[132:133]
	s_add_i32 m0, s21, 0xe000
	s_nop 0
	global_load_lds_dwordx4 v[138:139], off
	s_waitcnt vmcnt(8)
	s_waitcnt lgkmcnt(0)
	s_barrier
	s_waitcnt lgkmcnt(0)
	v_mfma_f32_16x16x32_bf16 v[124:127], v[134:137], v[172:175], v[124:127]
	v_mfma_f32_16x16x32_bf16 v[120:123], v[148:151], v[172:175], v[120:123]
	v_mfma_f32_16x16x32_bf16 v[116:119], v[134:137], v[180:183], v[116:119]
	v_mfma_f32_16x16x32_bf16 v[112:115], v[148:151], v[180:183], v[112:115]
	v_mfma_f32_16x16x32_bf16 v[108:111], v[134:137], v[188:191], v[108:111]
	v_mfma_f32_16x16x32_bf16 v[100:103], v[148:151], v[188:191], v[100:103]
	v_mfma_f32_16x16x32_bf16 v[92:95], v[134:137], v[196:199], v[92:95]
	v_mfma_f32_16x16x32_bf16 v[80:83], v[148:151], v[196:199], v[80:83]
	v_mfma_f32_16x16x32_bf16 v[124:127], v[144:147], v[176:179], v[124:127]
	v_mfma_f32_16x16x32_bf16 v[120:123], v[152:155], v[176:179], v[120:123]
	v_mfma_f32_16x16x32_bf16 v[116:119], v[144:147], v[184:187], v[116:119]
	v_mfma_f32_16x16x32_bf16 v[112:115], v[152:155], v[184:187], v[112:115]
	v_mfma_f32_16x16x32_bf16 v[108:111], v[144:147], v[192:195], v[108:111]
	v_mfma_f32_16x16x32_bf16 v[100:103], v[152:155], v[192:195], v[100:103]
	v_mfma_f32_16x16x32_bf16 v[92:95], v[144:147], v[200:203], v[92:95]
	v_mfma_f32_16x16x32_bf16 v[80:83], v[152:155], v[200:203], v[80:83]
	v_mfma_f32_16x16x32_bf16 v[104:107], v[156:159], v[172:175], v[104:107]
	v_mfma_f32_16x16x32_bf16 v[96:99], v[164:167], v[172:175], v[96:99]
	v_mfma_f32_16x16x32_bf16 v[88:91], v[156:159], v[180:183], v[88:91]
	v_mfma_f32_16x16x32_bf16 v[84:87], v[164:167], v[180:183], v[84:87]
	v_mfma_f32_16x16x32_bf16 v[76:79], v[156:159], v[188:191], v[76:79]
	v_mfma_f32_16x16x32_bf16 v[72:75], v[164:167], v[188:191], v[72:75]
	v_mfma_f32_16x16x32_bf16 v[68:71], v[156:159], v[196:199], v[68:71]
	v_mfma_f32_16x16x32_bf16 v[64:67], v[164:167], v[196:199], v[64:67]
	v_mfma_f32_16x16x32_bf16 v[104:107], v[160:163], v[176:179], v[104:107]
	v_mfma_f32_16x16x32_bf16 v[96:99], v[168:171], v[176:179], v[96:99]
	v_mfma_f32_16x16x32_bf16 v[88:91], v[160:163], v[184:187], v[88:91]
	v_mfma_f32_16x16x32_bf16 v[84:87], v[168:171], v[184:187], v[84:87]
	v_mfma_f32_16x16x32_bf16 v[76:79], v[160:163], v[192:195], v[76:79]
	v_mfma_f32_16x16x32_bf16 v[72:75], v[168:171], v[192:195], v[72:75]
	v_mfma_f32_16x16x32_bf16 v[68:71], v[160:163], v[200:203], v[68:71]
	v_mfma_f32_16x16x32_bf16 v[64:67], v[168:171], v[200:203], v[64:67]
	s_barrier
	s_add_i32 s28, s28, s19
	v_lshl_add_u64 v[138:139], s[22:23], 0, v[208:209]
	s_mov_b32 m0, s28
	ds_read_b128 v[172:175], v143 offset:16384
	ds_read_b128 v[176:179], v143 offset:17408
	ds_read_b128 v[180:183], v143 offset:18432
	ds_read_b128 v[184:187], v143 offset:19456
	ds_read_b128 v[188:191], v143 offset:20480
	ds_read_b128 v[192:195], v143 offset:21504
	ds_read_b128 v[196:199], v143 offset:22528
	ds_read_b128 v[200:203], v143 offset:23552
	global_load_lds_dwordx4 v[138:139], off
	s_add_i32 m0, s28, 0x2000
	s_add_u32 s28, s22, 0x40000
	v_lshl_add_u64 v[204:205], s[22:23], 0, v[128:129]
	s_addc_u32 s29, s23, 0
	s_add_i32 s30, s30, s19
	global_load_lds_dwordx4 v[204:205], off
	v_lshl_add_u64 v[206:207], s[28:29], 0, v[208:209]
	s_mov_b32 m0, s30
	v_lshl_add_u64 v[210:211], s[24:25], 0, v[128:129]
	global_load_lds_dwordx4 v[206:207], off
	v_lshl_add_u64 v[206:207], s[28:29], 0, v[128:129]
	s_add_i32 m0, s30, 0x2000
	s_nop 0
	global_load_lds_dwordx4 v[206:207], off
	v_lshl_add_u64 v[206:207], s[24:25], 0, v[208:209]
	s_mov_b32 m0, s21
	s_nop 0
	global_load_lds_dwordx4 v[206:207], off
	s_mov_b32 m0, s26
	s_nop 0
	global_load_lds_dwordx4 v[210:211], off
	s_waitcnt vmcnt(8)
	s_waitcnt lgkmcnt(0)
	s_barrier
; #define PG8_STAGE(bufoff, gbase, voff) do { _Pragma("unroll") for (int _i = 0; _i < 2; ++_i) \
;         __builtin_amdgcn_global_load_lds((const unsigned*)((const char*)(gbase) + (voff)[_i]), (PG8_LAS unsigned*)(lds + (bufoff) + ldsw + _i * 8192), 16, 0, 0); } while (0)
; #define PG8_LDA(dst, b, h) do { _Pragma("unroll") for (int m = 0; m < 4; ++m) _Pragma("unroll") for (int k = 0; k < 2; ++k) dst[m][k] = *(const PG8_LAS bf16x8*)(lds + PG8_SA(b, h) + aoff + m * 2048 + k * 1024); } while (0)
; #define PG8_LDB(dst, b, h) do { _Pragma("unroll") for (int n = 0; n < 2; ++n) _Pragma("unroll") for (int k = 0; k < 2; ++k) dst[n][k] = *(const PG8_LAS bf16x8*)(lds + PG8_SB(b, h) + boff + n * 2048 + k * 1024); } while (0)
; #define PG8_MMA(ai, bj, At, Bt) do { __builtin_amdgcn_s_setprio(1); _Pragma("unroll") for (int m = 0; m < 4; ++m) _Pragma("unroll") for (int n = 0; n < 2; ++n) _Pragma("unroll") for (int k = 0; k < 2; ++k) \
;         acc[ai][bj][m][n] = __builtin_amdgcn_mfma_f32_16x16x32_bf16(Bt[n][k], At[m][k], acc[ai][bj][m][n], 0, 0, 0); __builtin_amdgcn_s_setprio(0); } while (0)
; #define PG8_WAIT_V(n) asm volatile("s_waitcnt vmcnt(" #n ")" ::: "memory")
; #define PG8_WAIT_L(n) asm volatile("s_waitcnt lgkmcnt(" #n ")" ::: "memory")
; #define PG8_BAR __builtin_amdgcn_s_barrier()
; #define PG8_SCHED __builtin_amdgcn_sched_barrier(0)
; template <class Epi, class Sched, bool ALIGN_EPI = false, bool SP2 = false>
; __device__ __forceinline__ void gemm_phase(PG8_LAS unsigned char* lds, const Gemm g, const Sched& S, const Epi& E) {
;     ...
;             PG8_WAIT_V(8); PG8_WAIT_L(0); PG8_BAR; PG8_MMA(1, 0, At, B0); PG8_MMA(1, 1, At, B1); PG8_BAR; PG8_SCHED;
;             PG8_LDB(B0, 1, 0); PG8_LDB(B1, 1, 1); PG8_SCHED; PG8_LDA(At, 1, 0); PG8_STAGE(PG8_SA(0, 1), a2 + hstepA, voffA);
;             PG8_WAIT_V(8); PG8_WAIT_L(0); PG8_BAR; PG8_MMA(0, 0, At, B0); PG8_MMA(0, 1, At, B1); PG8_BAR; PG8_SCHED;
	s_waitcnt lgkmcnt(0)
	v_mfma_f32_16x16x32_bf16 v[60:63], v[134:137], v[172:175], v[60:63]
	v_mfma_f32_16x16x32_bf16 v[56:59], v[148:151], v[172:175], v[56:59]
	v_mfma_f32_16x16x32_bf16 v[52:55], v[134:137], v[180:183], v[52:55]
	v_mfma_f32_16x16x32_bf16 v[48:51], v[148:151], v[180:183], v[48:51]
	v_mfma_f32_16x16x32_bf16 v[44:47], v[134:137], v[188:191], v[44:47]
	v_mfma_f32_16x16x32_bf16 v[32:35], v[148:151], v[188:191], v[32:35]
	v_mfma_f32_16x16x32_bf16 v[16:19], v[134:137], v[196:199], v[16:19]
	v_mfma_f32_16x16x32_bf16 v[8:11], v[148:151], v[196:199], v[8:11]
	v_mfma_f32_16x16x32_bf16 v[60:63], v[144:147], v[176:179], v[60:63]
	v_mfma_f32_16x16x32_bf16 v[56:59], v[152:155], v[176:179], v[56:59]
	v_mfma_f32_16x16x32_bf16 v[52:55], v[144:147], v[184:187], v[52:55]
	v_mfma_f32_16x16x32_bf16 v[48:51], v[152:155], v[184:187], v[48:51]
	v_mfma_f32_16x16x32_bf16 v[44:47], v[144:147], v[192:195], v[44:47]
	v_mfma_f32_16x16x32_bf16 v[32:35], v[152:155], v[192:195], v[32:35]
	v_mfma_f32_16x16x32_bf16 v[16:19], v[144:147], v[200:203], v[16:19]
	v_mfma_f32_16x16x32_bf16 v[8:11], v[152:155], v[200:203], v[8:11]
	v_mfma_f32_16x16x32_bf16 v[40:43], v[156:159], v[172:175], v[40:43]
	v_mfma_f32_16x16x32_bf16 v[36:39], v[164:167], v[172:175], v[36:39]
	v_mfma_f32_16x16x32_bf16 v[28:31], v[156:159], v[180:183], v[28:31]
	v_mfma_f32_16x16x32_bf16 v[24:27], v[164:167], v[180:183], v[24:27]
	v_mfma_f32_16x16x32_bf16 v[20:23], v[156:159], v[188:191], v[20:23]
	v_mfma_f32_16x16x32_bf16 v[12:15], v[164:167], v[188:191], v[12:15]
	v_mfma_f32_16x16x32_bf16 v[4:7], v[156:159], v[196:199], v[4:7]
	v_mfma_f32_16x16x32_bf16 v[0:3], v[164:167], v[196:199], v[0:3]
	v_mfma_f32_16x16x32_bf16 v[40:43], v[160:163], v[176:179], v[40:43]
	v_mfma_f32_16x16x32_bf16 v[36:39], v[168:171], v[176:179], v[36:39]
	v_mfma_f32_16x16x32_bf16 v[28:31], v[160:163], v[184:187], v[28:31]
	v_mfma_f32_16x16x32_bf16 v[24:27], v[168:171], v[184:187], v[24:27]
	v_mfma_f32_16x16x32_bf16 v[20:23], v[160:163], v[192:195], v[20:23]
	v_mfma_f32_16x16x32_bf16 v[12:15], v[168:171], v[192:195], v[12:15]
	v_mfma_f32_16x16x32_bf16 v[4:7], v[160:163], v[200:203], v[4:7]
	v_mfma_f32_16x16x32_bf16 v[0:3], v[168:171], v[200:203], v[0:3]
	s_barrier
	s_add_i32 s28, 0, 0x18000
	s_add_i32 s29, 0, 0x1c000
	v_add_u32_e32 v152, s28, v141
	v_add_u32_e32 v168, s29, v141
	ds_read_b128 v[134:137], v152
	ds_read_b128 v[144:147], v152 offset:1024
	ds_read_b128 v[148:151], v152 offset:2048
	ds_read_b128 v[152:155], v152 offset:3072
	ds_read_b128 v[156:159], v168
	ds_read_b128 v[160:163], v168 offset:1024
	ds_read_b128 v[164:167], v168 offset:2048
	ds_read_b128 v[168:171], v168 offset:3072
	s_add_u32 s24, s24, 0x40000
	s_addc_u32 s25, s25, 0
	s_mov_b32 m0, s34
	v_lshl_add_u64 v[212:213], s[24:25], 0, v[208:209]
	ds_read_b128 v[172:175], v143 offset:32768
	ds_read_b128 v[176:179], v143 offset:33792
	ds_read_b128 v[180:183], v143 offset:34816
	ds_read_b128 v[184:187], v143 offset:35840
	ds_read_b128 v[188:191], v143 offset:36864
	ds_read_b128 v[192:195], v143 offset:37888
	ds_read_b128 v[196:199], v143 offset:38912
	ds_read_b128 v[200:203], v143 offset:39936
	global_load_lds_dwordx4 v[212:213], off
	v_lshl_add_u64 v[212:213], s[24:25], 0, v[128:129]
	s_mov_b32 m0, s35
	s_nop 0
	global_load_lds_dwordx4 v[212:213], off
	s_waitcnt vmcnt(8)
	s_waitcnt lgkmcnt(0)
	s_barrier
	s_waitcnt lgkmcnt(0)
	v_mfma_f32_16x16x32_bf16 v[124:127], v[134:137], v[172:175], v[124:127]
	v_mfma_f32_16x16x32_bf16 v[120:123], v[148:151], v[172:175], v[120:123]
	v_mfma_f32_16x16x32_bf16 v[116:119], v[134:137], v[180:183], v[116:119]
	v_mfma_f32_16x16x32_bf16 v[112:115], v[148:151], v[180:183], v[112:115]
	v_mfma_f32_16x16x32_bf16 v[108:111], v[134:137], v[188:191], v[108:111]
	v_mfma_f32_16x16x32_bf16 v[100:103], v[148:151], v[188:191], v[100:103]
	v_mfma_f32_16x16x32_bf16 v[92:95], v[134:137], v[196:199], v[92:95]
	v_mfma_f32_16x16x32_bf16 v[80:83], v[148:151], v[196:199], v[80:83]
	v_mfma_f32_16x16x32_bf16 v[124:127], v[144:147], v[176:179], v[124:127]
	v_mfma_f32_16x16x32_bf16 v[120:123], v[152:155], v[176:179], v[120:123]
	v_mfma_f32_16x16x32_bf16 v[116:119], v[144:147], v[184:187], v[116:119]
	v_mfma_f32_16x16x32_bf16 v[112:115], v[152:155], v[184:187], v[112:115]
	v_mfma_f32_16x16x32_bf16 v[108:111], v[144:147], v[192:195], v[108:111]
	v_mfma_f32_16x16x32_bf16 v[100:103], v[152:155], v[192:195], v[100:103]
	v_mfma_f32_16x16x32_bf16 v[92:95], v[144:147], v[200:203], v[92:95]
	v_mfma_f32_16x16x32_bf16 v[80:83], v[152:155], v[200:203], v[80:83]
	v_mfma_f32_16x16x32_bf16 v[104:107], v[156:159], v[172:175], v[104:107]
	v_mfma_f32_16x16x32_bf16 v[96:99], v[164:167], v[172:175], v[96:99]
	v_mfma_f32_16x16x32_bf16 v[88:91], v[156:159], v[180:183], v[88:91]
	v_mfma_f32_16x16x32_bf16 v[84:87], v[164:167], v[180:183], v[84:87]
	v_mfma_f32_16x16x32_bf16 v[76:79], v[156:159], v[188:191], v[76:79]
	v_mfma_f32_16x16x32_bf16 v[72:75], v[164:167], v[188:191], v[72:75]
	v_mfma_f32_16x16x32_bf16 v[68:71], v[156:159], v[196:199], v[68:71]
	v_mfma_f32_16x16x32_bf16 v[64:67], v[164:167], v[196:199], v[64:67]
	v_mfma_f32_16x16x32_bf16 v[104:107], v[160:163], v[176:179], v[104:107]
	v_mfma_f32_16x16x32_bf16 v[96:99], v[168:171], v[176:179], v[96:99]
	v_mfma_f32_16x16x32_bf16 v[88:91], v[160:163], v[184:187], v[88:91]
	v_mfma_f32_16x16x32_bf16 v[84:87], v[168:171], v[184:187], v[84:87]
	v_mfma_f32_16x16x32_bf16 v[76:79], v[160:163], v[192:195], v[76:79]
	v_mfma_f32_16x16x32_bf16 v[72:75], v[168:171], v[192:195], v[72:75]
	v_mfma_f32_16x16x32_bf16 v[68:71], v[160:163], v[200:203], v[68:71]
	v_mfma_f32_16x16x32_bf16 v[64:67], v[168:171], v[200:203], v[64:67]
	s_barrier
; #define PG8_STAGE(bufoff, gbase, voff) do { _Pragma("unroll") for (int _i = 0; _i < 2; ++_i) \
;         __builtin_amdgcn_global_load_lds((const unsigned*)((const char*)(gbase) + (voff)[_i]), (PG8_LAS unsigned*)(lds + (bufoff) + ldsw + _i * 8192), 16, 0, 0); } while (0)
; #define PG8_LDA(dst, b, h) do { _Pragma("unroll") for (int m = 0; m < 4; ++m) _Pragma("unroll") for (int k = 0; k < 2; ++k) dst[m][k] = *(const PG8_LAS bf16x8*)(lds + PG8_SA(b, h) + aoff + m * 2048 + k * 1024); } while (0)
; #define PG8_MMA(ai, bj, At, Bt) do { __builtin_amdgcn_s_setprio(1); _Pragma("unroll") for (int m = 0; m < 4; ++m) _Pragma("unroll") for (int n = 0; n < 2; ++n) _Pragma("unroll") for (int k = 0; k < 2; ++k) \
;         acc[ai][bj][m][n] = __builtin_amdgcn_mfma_f32_16x16x32_bf16(Bt[n][k], At[m][k], acc[ai][bj][m][n], 0, 0, 0); __builtin_amdgcn_s_setprio(0); } while (0)
; #define PG8_WAIT_V(n) asm volatile("s_waitcnt vmcnt(" #n ")" ::: "memory")
; #define PG8_WAIT_L(n) asm volatile("s_waitcnt lgkmcnt(" #n ")" ::: "memory")
; #define PG8_BAR __builtin_amdgcn_s_barrier()
; #define PG8_SCHED __builtin_amdgcn_sched_barrier(0)
; template <class Epi, class Sched, bool ALIGN_EPI = false, bool SP2 = false>
; __device__ __forceinline__ void gemm_phase(PG8_LAS unsigned char* lds, const Gemm g, const Sched& S, const Epi& E) {
;     ...
;             PG8_LDA(At, 1, 1); PG8_STAGE(PG8_SB(1, 0), b3, voffB); PG8_STAGE(PG8_SB(1, 1), b3 + hstepB, voffB); PG8_STAGE(PG8_SA(1, 0), a3, voffA);
;             PG8_WAIT_V(8); PG8_WAIT_L(0); PG8_BAR; PG8_MMA(1, 0, At, B0); PG8_MMA(1, 1, At, B1); PG8_BAR; PG8_SCHED;
;     ...
;         }
;         if constexpr (ALIGN_EPI) { if (wr == 0) PG8_BAR; }
	s_add_i32 s24, s28, s19
	v_lshl_add_u64 v[138:139], v[138:139], 0, s[10:11]
	s_mov_b32 m0, s24
	ds_read_b128 v[172:175], v143 offset:49152
	ds_read_b128 v[176:179], v143 offset:50176
	ds_read_b128 v[180:183], v143 offset:51200
	ds_read_b128 v[184:187], v143 offset:52224
	ds_read_b128 v[188:191], v143 offset:53248
	ds_read_b128 v[192:195], v143 offset:54272
	ds_read_b128 v[196:199], v143 offset:55296
	ds_read_b128 v[200:203], v143 offset:56320
	global_load_lds_dwordx4 v[138:139], off
	s_add_i32 m0, s24, 0x2000
	s_add_u32 s22, s22, 0x40080
	v_lshl_add_u64 v[138:139], v[204:205], 0, s[10:11]
	s_addc_u32 s23, s23, 0
	s_add_i32 s24, s29, s19
	global_load_lds_dwordx4 v[138:139], off
	v_lshl_add_u64 v[138:139], s[22:23], 0, v[208:209]
	s_mov_b32 m0, s24
	s_nop 0
	global_load_lds_dwordx4 v[138:139], off
	v_lshl_add_u64 v[138:139], s[22:23], 0, v[128:129]
	s_add_i32 m0, s24, 0x2000
	s_nop 0
	global_load_lds_dwordx4 v[138:139], off
	v_lshl_add_u64 v[138:139], v[206:207], 0, s[10:11]
	s_mov_b32 m0, s39
	s_nop 0
	global_load_lds_dwordx4 v[138:139], off
	v_lshl_add_u64 v[138:139], v[210:211], 0, s[10:11]
	s_mov_b32 m0, s48
	s_nop 0
	global_load_lds_dwordx4 v[138:139], off
	s_waitcnt vmcnt(8)
	s_waitcnt lgkmcnt(0)
	s_barrier
	s_waitcnt lgkmcnt(0)
	v_mfma_f32_16x16x32_bf16 v[60:63], v[134:137], v[172:175], v[60:63]
	v_mfma_f32_16x16x32_bf16 v[56:59], v[148:151], v[172:175], v[56:59]
	v_mfma_f32_16x16x32_bf16 v[52:55], v[134:137], v[180:183], v[52:55]
	v_mfma_f32_16x16x32_bf16 v[48:51], v[148:151], v[180:183], v[48:51]
	v_mfma_f32_16x16x32_bf16 v[44:47], v[134:137], v[188:191], v[44:47]
	v_mfma_f32_16x16x32_bf16 v[32:35], v[148:151], v[188:191], v[32:35]
	v_mfma_f32_16x16x32_bf16 v[16:19], v[134:137], v[196:199], v[16:19]
	v_mfma_f32_16x16x32_bf16 v[8:11], v[148:151], v[196:199], v[8:11]
	v_mfma_f32_16x16x32_bf16 v[60:63], v[144:147], v[176:179], v[60:63]
	v_mfma_f32_16x16x32_bf16 v[56:59], v[152:155], v[176:179], v[56:59]
	v_mfma_f32_16x16x32_bf16 v[52:55], v[144:147], v[184:187], v[52:55]
	v_mfma_f32_16x16x32_bf16 v[48:51], v[152:155], v[184:187], v[48:51]
	v_mfma_f32_16x16x32_bf16 v[44:47], v[144:147], v[192:195], v[44:47]
	v_mfma_f32_16x16x32_bf16 v[32:35], v[152:155], v[192:195], v[32:35]
	v_mfma_f32_16x16x32_bf16 v[16:19], v[144:147], v[200:203], v[16:19]
	v_mfma_f32_16x16x32_bf16 v[8:11], v[152:155], v[200:203], v[8:11]
	v_mfma_f32_16x16x32_bf16 v[40:43], v[156:159], v[172:175], v[40:43]
	v_mfma_f32_16x16x32_bf16 v[36:39], v[164:167], v[172:175], v[36:39]
	v_mfma_f32_16x16x32_bf16 v[28:31], v[156:159], v[180:183], v[28:31]
	v_mfma_f32_16x16x32_bf16 v[24:27], v[164:167], v[180:183], v[24:27]
	v_mfma_f32_16x16x32_bf16 v[20:23], v[156:159], v[188:191], v[20:23]
	v_mfma_f32_16x16x32_bf16 v[12:15], v[164:167], v[188:191], v[12:15]
	v_mfma_f32_16x16x32_bf16 v[4:7], v[156:159], v[196:199], v[4:7]
	v_mfma_f32_16x16x32_bf16 v[0:3], v[164:167], v[196:199], v[0:3]
	v_mfma_f32_16x16x32_bf16 v[40:43], v[160:163], v[176:179], v[40:43]
	v_mfma_f32_16x16x32_bf16 v[36:39], v[168:171], v[176:179], v[36:39]
	v_mfma_f32_16x16x32_bf16 v[28:31], v[160:163], v[184:187], v[28:31]
	v_mfma_f32_16x16x32_bf16 v[24:27], v[168:171], v[184:187], v[24:27]
	v_mfma_f32_16x16x32_bf16 v[20:23], v[160:163], v[192:195], v[20:23]
	v_mfma_f32_16x16x32_bf16 v[12:15], v[168:171], v[192:195], v[12:15]
	v_mfma_f32_16x16x32_bf16 v[4:7], v[160:163], v[200:203], v[4:7]
	v_mfma_f32_16x16x32_bf16 v[0:3], v[168:171], v[200:203], v[0:3]
	s_barrier
	s_add_i32 s51, s51, 2
	s_add_u32 s0, s0, 0x100
	s_addc_u32 s1, s1, 0
	s_add_u32 s43, s43, 0x100
	s_addc_u32 s50, s50, 0
	s_cmp_gt_u32 s51, 13
	s_cbranch_scc0 .LBB0_797
	s_and_b64 vcc, exec, s[6:7]
	s_cbranch_vccz .LBB0_800
	s_barrier

; #define PG8_STAGE(bufoff, gbase, voff) do { _Pragma("unroll") for (int _i = 0; _i < 2; ++_i) \
;         __builtin_amdgcn_global_load_lds((const unsigned*)((const char*)(gbase) + (voff)[_i]), (PG8_LAS unsigned*)(lds + (bufoff) + ldsw + _i * 8192), 16, 0, 0); } while (0)
; #define PG8_LDA(dst, b, h) do { _Pragma("unroll") for (int m = 0; m < 4; ++m) _Pragma("unroll") for (int k = 0; k < 2; ++k) dst[m][k] = *(const PG8_LAS bf16x8*)(lds + PG8_SA(b, h) + aoff + m * 2048 + k * 1024); } while (0)
; #define PG8_LDB(dst, b, h) do { _Pragma("unroll") for (int n = 0; n < 2; ++n) _Pragma("unroll") for (int k = 0; k < 2; ++k) dst[n][k] = *(const PG8_LAS bf16x8*)(lds + PG8_SB(b, h) + boff + n * 2048 + k * 1024); } while (0)
; #define PG8_MMA(ai, bj, At, Bt) do { __builtin_amdgcn_s_setprio(1); _Pragma("unroll") for (int m = 0; m < 4; ++m) _Pragma("unroll") for (int n = 0; n < 2; ++n) _Pragma("unroll") for (int k = 0; k < 2; ++k) \
;         acc[ai][bj][m][n] = __builtin_amdgcn_mfma_f32_16x16x32_bf16(Bt[n][k], At[m][k], acc[ai][bj][m][n], 0, 0, 0); __builtin_amdgcn_s_setprio(0); } while (0)
; #define PG8_WAIT_V(n) asm volatile("s_waitcnt vmcnt(" #n ")" ::: "memory")
; #define PG8_WAIT_L(n) asm volatile("s_waitcnt lgkmcnt(" #n ")" ::: "memory")
; #define PG8_BAR __builtin_amdgcn_s_barrier()
; #define PG8_SCHED __builtin_amdgcn_sched_barrier(0)
; template <class Epi, class Sched, bool ALIGN_EPI = false, bool SP2 = false>
; __device__ __forceinline__ void gemm_phase(PG8_LAS unsigned char* lds, const Gemm g, const Sched& S, const Epi& E) {
;     ...
;             const bool last = (t == nt - 2);
;             const char* a1 = cA + (size_t)(t + 1) * kstep;
;             const char* a2 = last ? nA : cA + (size_t)(t + 2) * kstep; const char* b2 = last ? nB : cB + (size_t)(t + 2) * kstep;
;             const char* a3 = a2 + kstep; const char* b3 = b2 + kstep;
;             if (last && has_next) S.a_ready(nxt);
;             if constexpr (SP2) {
;             PG8_LDB(B0, 0, 0); PG8_LDB(B1, 0, 1); PG8_SCHED; PG8_LDA(At, 0, 0); PG8_STAGE(PG8_SA(1, 1), a1 + hstepA, voffA);
;             PG8_WAIT_V(8); PG8_WAIT_L(0); PG8_BAR; PG8_MMA(0, 0, At, B0); PG8_MMA(0, 1, At, B1); PG8_BAR; PG8_SCHED;
;             PG8_LDA(At, 0, 1); PG8_STAGE(PG8_SB(0, 0), b2, voffB); PG8_STAGE(PG8_SB(0, 1), b2 + hstepB, voffB); PG8_STAGE(PG8_SA(0, 0), a2, voffA);
.LBB0_920:
	s_add_u32 s22, s0, 0xfffc0080
	s_addc_u32 s23, s1, -1
	s_add_i32 s28, 0, 0x10000
	s_cmp_eq_u32 s51, 12
	s_cselect_b32 s25, s14, s23
	s_cselect_b32 s24, s15, s22
	v_add_u32_e32 v138, s28, v141
	s_cselect_b32 s23, s9, s50
	s_cselect_b32 s22, s38, s43
	s_add_i32 s30, 0, 0x14000
	ds_read_b128 v[144:147], v138
	ds_read_b128 v[148:151], v138 offset:1024
	ds_read_b128 v[152:155], v138 offset:2048
	ds_read_b128 v[156:159], v138 offset:3072
	v_add_u32_e32 v138, s30, v141
	ds_read_b128 v[160:163], v138
	ds_read_b128 v[164:167], v138 offset:1024
	ds_read_b128 v[168:171], v138 offset:2048
	ds_read_b128 v[172:175], v138 offset:3072
	v_lshl_add_u64 v[138:139], s[0:1], 0, v[134:135]
	s_add_i32 m0, s21, 0xc000
	ds_read_b128 v[176:179], v143
	ds_read_b128 v[180:183], v143 offset:1024
	ds_read_b128 v[184:187], v143 offset:2048
	ds_read_b128 v[188:191], v143 offset:3072
	ds_read_b128 v[192:195], v143 offset:4096
	ds_read_b128 v[196:199], v143 offset:5120
	ds_read_b128 v[200:203], v143 offset:6144
	ds_read_b128 v[204:207], v143 offset:7168
	global_load_lds_dwordx4 v[138:139], off
	v_lshl_add_u64 v[138:139], s[0:1], 0, v[136:137]
	s_add_i32 m0, s21, 0xe000
	s_nop 0
	global_load_lds_dwordx4 v[138:139], off
	s_waitcnt vmcnt(8)
	s_waitcnt lgkmcnt(0)
	s_barrier
	s_waitcnt lgkmcnt(0)
	v_mfma_f32_16x16x32_bf16 v[124:127], v[144:147], v[176:179], v[124:127]
	v_mfma_f32_16x16x32_bf16 v[120:123], v[152:155], v[176:179], v[120:123]
	v_mfma_f32_16x16x32_bf16 v[108:111], v[144:147], v[184:187], v[108:111]
	v_mfma_f32_16x16x32_bf16 v[104:107], v[152:155], v[184:187], v[104:107]
	v_mfma_f32_16x16x32_bf16 v[92:95], v[144:147], v[192:195], v[92:95]
	v_mfma_f32_16x16x32_bf16 v[88:91], v[152:155], v[192:195], v[88:91]
	v_mfma_f32_16x16x32_bf16 v[76:79], v[144:147], v[200:203], v[76:79]
	v_mfma_f32_16x16x32_bf16 v[72:75], v[152:155], v[200:203], v[72:75]
	v_mfma_f32_16x16x32_bf16 v[124:127], v[148:151], v[180:183], v[124:127]
	v_mfma_f32_16x16x32_bf16 v[120:123], v[156:159], v[180:183], v[120:123]
	v_mfma_f32_16x16x32_bf16 v[108:111], v[148:151], v[188:191], v[108:111]
	v_mfma_f32_16x16x32_bf16 v[104:107], v[156:159], v[188:191], v[104:107]
	v_mfma_f32_16x16x32_bf16 v[92:95], v[148:151], v[196:199], v[92:95]
	v_mfma_f32_16x16x32_bf16 v[88:91], v[156:159], v[196:199], v[88:91]
	v_mfma_f32_16x16x32_bf16 v[76:79], v[148:151], v[204:207], v[76:79]
	v_mfma_f32_16x16x32_bf16 v[72:75], v[156:159], v[204:207], v[72:75]
	v_mfma_f32_16x16x32_bf16 v[116:119], v[160:163], v[176:179], v[116:119]
	v_mfma_f32_16x16x32_bf16 v[112:115], v[168:171], v[176:179], v[112:115]
	v_mfma_f32_16x16x32_bf16 v[100:103], v[160:163], v[184:187], v[100:103]
	v_mfma_f32_16x16x32_bf16 v[96:99], v[168:171], v[184:187], v[96:99]
	v_mfma_f32_16x16x32_bf16 v[84:87], v[160:163], v[192:195], v[84:87]
	v_mfma_f32_16x16x32_bf16 v[80:83], v[168:171], v[192:195], v[80:83]
	v_mfma_f32_16x16x32_bf16 v[68:71], v[160:163], v[200:203], v[68:71]
	v_mfma_f32_16x16x32_bf16 v[64:67], v[168:171], v[200:203], v[64:67]
	v_mfma_f32_16x16x32_bf16 v[116:119], v[164:167], v[180:183], v[116:119]
	v_mfma_f32_16x16x32_bf16 v[112:115], v[172:175], v[180:183], v[112:115]
	v_mfma_f32_16x16x32_bf16 v[100:103], v[164:167], v[188:191], v[100:103]
	v_mfma_f32_16x16x32_bf16 v[96:99], v[172:175], v[188:191], v[96:99]
	v_mfma_f32_16x16x32_bf16 v[84:87], v[164:167], v[196:199], v[84:87]
	v_mfma_f32_16x16x32_bf16 v[80:83], v[172:175], v[196:199], v[80:83]
	v_mfma_f32_16x16x32_bf16 v[68:71], v[164:167], v[204:207], v[68:71]
	v_mfma_f32_16x16x32_bf16 v[64:67], v[172:175], v[204:207], v[64:67]
	s_barrier
	s_add_i32 s28, s28, s18
	v_lshl_add_u64 v[138:139], s[22:23], 0, v[208:209]
	s_mov_b32 m0, s28
	ds_read_b128 v[176:179], v143 offset:16384
	ds_read_b128 v[180:183], v143 offset:17408
	ds_read_b128 v[184:187], v143 offset:18432
	ds_read_b128 v[188:191], v143 offset:19456
	ds_read_b128 v[192:195], v143 offset:20480
	ds_read_b128 v[196:199], v143 offset:21504
	ds_read_b128 v[200:203], v143 offset:22528
	ds_read_b128 v[204:207], v143 offset:23552
	global_load_lds_dwordx4 v[138:139], off
	s_add_i32 m0, s28, 0x2000
	s_add_u32 s28, s22, 0x40000
	v_lshl_add_u64 v[210:211], s[22:23], 0, v[128:129]
	s_addc_u32 s29, s23, 0
	s_add_i32 s30, s30, s18
	global_load_lds_dwordx4 v[210:211], off
	v_lshl_add_u64 v[212:213], s[28:29], 0, v[208:209]
	s_mov_b32 m0, s30
	v_lshl_add_u64 v[222:223], s[24:25], 0, v[130:131]
	global_load_lds_dwordx4 v[212:213], off
	v_lshl_add_u64 v[212:213], s[28:29], 0, v[128:129]
	s_add_i32 m0, s30, 0x2000
	s_nop 0
	global_load_lds_dwordx4 v[212:213], off
	v_lshl_add_u64 v[212:213], s[24:25], 0, v[132:133]
	s_mov_b32 m0, s21
	s_nop 0
	global_load_lds_dwordx4 v[212:213], off
	s_mov_b32 m0, s26
	s_nop 0
	global_load_lds_dwordx4 v[222:223], off
	s_waitcnt vmcnt(8)
	s_waitcnt lgkmcnt(0)
	s_barrier
; #define PG8_STAGE(bufoff, gbase, voff) do { _Pragma("unroll") for (int _i = 0; _i < 2; ++_i) \
;         __builtin_amdgcn_global_load_lds((const unsigned*)((const char*)(gbase) + (voff)[_i]), (PG8_LAS unsigned*)(lds + (bufoff) + ldsw + _i * 8192), 16, 0, 0); } while (0)
; #define PG8_LDA(dst, b, h) do { _Pragma("unroll") for (int m = 0; m < 4; ++m) _Pragma("unroll") for (int k = 0; k < 2; ++k) dst[m][k] = *(const PG8_LAS bf16x8*)(lds + PG8_SA(b, h) + aoff + m * 2048 + k * 1024); } while (0)
; #define PG8_LDB(dst, b, h) do { _Pragma("unroll") for (int n = 0; n < 2; ++n) _Pragma("unroll") for (int k = 0; k < 2; ++k) dst[n][k] = *(const PG8_LAS bf16x8*)(lds + PG8_SB(b, h) + boff + n * 2048 + k * 1024); } while (0)
; #define PG8_MMA(ai, bj, At, Bt) do { __builtin_amdgcn_s_setprio(1); _Pragma("unroll") for (int m = 0; m < 4; ++m) _Pragma("unroll") for (int n = 0; n < 2; ++n) _Pragma("unroll") for (int k = 0; k < 2; ++k) \
;         acc[ai][bj][m][n] = __builtin_amdgcn_mfma_f32_16x16x32_bf16(Bt[n][k], At[m][k], acc[ai][bj][m][n], 0, 0, 0); __builtin_amdgcn_s_setprio(0); } while (0)
; #define PG8_WAIT_V(n) asm volatile("s_waitcnt vmcnt(" #n ")" ::: "memory")
; #define PG8_WAIT_L(n) asm volatile("s_waitcnt lgkmcnt(" #n ")" ::: "memory")
; #define PG8_BAR __builtin_amdgcn_s_barrier()
; #define PG8_SCHED __builtin_amdgcn_sched_barrier(0)
; template <class Epi, class Sched, bool ALIGN_EPI = false, bool SP2 = false>
; __device__ __forceinline__ void gemm_phase(PG8_LAS unsigned char* lds, const Gemm g, const Sched& S, const Epi& E) {
;     ...
;             PG8_WAIT_V(8); PG8_WAIT_L(0); PG8_BAR; PG8_MMA(1, 0, At, B0); PG8_MMA(1, 1, At, B1); PG8_BAR; PG8_SCHED;
;             PG8_LDB(B0, 1, 0); PG8_LDB(B1, 1, 1); PG8_SCHED; PG8_LDA(At, 1, 0); PG8_STAGE(PG8_SA(0, 1), a2 + hstepA, voffA);
;             PG8_WAIT_V(8); PG8_WAIT_L(0); PG8_BAR; PG8_MMA(0, 0, At, B0); PG8_MMA(0, 1, At, B1); PG8_BAR; PG8_SCHED;
	s_waitcnt lgkmcnt(0)
	v_mfma_f32_16x16x32_bf16 v[60:63], v[144:147], v[176:179], v[60:63]
	v_mfma_f32_16x16x32_bf16 v[56:59], v[152:155], v[176:179], v[56:59]
	v_mfma_f32_16x16x32_bf16 v[44:47], v[144:147], v[184:187], v[44:47]
	v_mfma_f32_16x16x32_bf16 v[40:43], v[152:155], v[184:187], v[40:43]
	v_mfma_f32_16x16x32_bf16 v[28:31], v[144:147], v[192:195], v[28:31]
	v_mfma_f32_16x16x32_bf16 v[24:27], v[152:155], v[192:195], v[24:27]
	v_mfma_f32_16x16x32_bf16 v[12:15], v[144:147], v[200:203], v[12:15]
	v_mfma_f32_16x16x32_bf16 v[8:11], v[152:155], v[200:203], v[8:11]
	v_mfma_f32_16x16x32_bf16 v[60:63], v[148:151], v[180:183], v[60:63]
	v_mfma_f32_16x16x32_bf16 v[56:59], v[156:159], v[180:183], v[56:59]
	v_mfma_f32_16x16x32_bf16 v[44:47], v[148:151], v[188:191], v[44:47]
	v_mfma_f32_16x16x32_bf16 v[40:43], v[156:159], v[188:191], v[40:43]
	v_mfma_f32_16x16x32_bf16 v[28:31], v[148:151], v[196:199], v[28:31]
	v_mfma_f32_16x16x32_bf16 v[24:27], v[156:159], v[196:199], v[24:27]
	v_mfma_f32_16x16x32_bf16 v[12:15], v[148:151], v[204:207], v[12:15]
	v_mfma_f32_16x16x32_bf16 v[8:11], v[156:159], v[204:207], v[8:11]
	v_mfma_f32_16x16x32_bf16 v[52:55], v[160:163], v[176:179], v[52:55]
	v_mfma_f32_16x16x32_bf16 v[48:51], v[168:171], v[176:179], v[48:51]
	v_mfma_f32_16x16x32_bf16 v[36:39], v[160:163], v[184:187], v[36:39]
	v_mfma_f32_16x16x32_bf16 v[32:35], v[168:171], v[184:187], v[32:35]
	v_mfma_f32_16x16x32_bf16 v[20:23], v[160:163], v[192:195], v[20:23]
	v_mfma_f32_16x16x32_bf16 v[16:19], v[168:171], v[192:195], v[16:19]
	v_mfma_f32_16x16x32_bf16 v[4:7], v[160:163], v[200:203], v[4:7]
	v_mfma_f32_16x16x32_bf16 v[0:3], v[168:171], v[200:203], v[0:3]
	v_mfma_f32_16x16x32_bf16 v[52:55], v[164:167], v[180:183], v[52:55]
	v_mfma_f32_16x16x32_bf16 v[48:51], v[172:175], v[180:183], v[48:51]
	v_mfma_f32_16x16x32_bf16 v[36:39], v[164:167], v[188:191], v[36:39]
	v_mfma_f32_16x16x32_bf16 v[32:35], v[172:175], v[188:191], v[32:35]
	v_mfma_f32_16x16x32_bf16 v[20:23], v[164:167], v[196:199], v[20:23]
	v_mfma_f32_16x16x32_bf16 v[16:19], v[172:175], v[196:199], v[16:19]
	v_mfma_f32_16x16x32_bf16 v[4:7], v[164:167], v[204:207], v[4:7]
	v_mfma_f32_16x16x32_bf16 v[0:3], v[172:175], v[204:207], v[0:3]
	s_barrier
	s_add_i32 s28, 0, 0x18000
	s_add_i32 s29, 0, 0x1c000
	v_add_u32_e32 v156, s28, v141
	v_add_u32_e32 v172, s29, v141
	ds_read_b128 v[144:147], v156
	ds_read_b128 v[148:151], v156 offset:1024
	ds_read_b128 v[152:155], v156 offset:2048
	ds_read_b128 v[156:159], v156 offset:3072
	ds_read_b128 v[160:163], v172
	ds_read_b128 v[164:167], v172 offset:1024
	ds_read_b128 v[168:171], v172 offset:2048
	ds_read_b128 v[172:175], v172 offset:3072
	s_add_u32 s24, s24, 0x40000
	s_addc_u32 s25, s25, 0
	s_mov_b32 m0, s34
	v_lshl_add_u64 v[224:225], s[24:25], 0, v[132:133]
	ds_read_b128 v[176:179], v143 offset:32768
	ds_read_b128 v[180:183], v143 offset:33792
	ds_read_b128 v[184:187], v143 offset:34816
	ds_read_b128 v[188:191], v143 offset:35840
	ds_read_b128 v[192:195], v143 offset:36864
	ds_read_b128 v[196:199], v143 offset:37888
	ds_read_b128 v[200:203], v143 offset:38912
	ds_read_b128 v[204:207], v143 offset:39936
	global_load_lds_dwordx4 v[224:225], off
	v_lshl_add_u64 v[224:225], s[24:25], 0, v[130:131]
	s_mov_b32 m0, s35
	s_nop 0
	global_load_lds_dwordx4 v[224:225], off
	s_waitcnt vmcnt(8)
	s_waitcnt lgkmcnt(0)
	s_barrier
	s_waitcnt lgkmcnt(0)
	v_mfma_f32_16x16x32_bf16 v[124:127], v[144:147], v[176:179], v[124:127]
	v_mfma_f32_16x16x32_bf16 v[120:123], v[152:155], v[176:179], v[120:123]
	v_mfma_f32_16x16x32_bf16 v[108:111], v[144:147], v[184:187], v[108:111]
	v_mfma_f32_16x16x32_bf16 v[104:107], v[152:155], v[184:187], v[104:107]
	v_mfma_f32_16x16x32_bf16 v[92:95], v[144:147], v[192:195], v[92:95]
	v_mfma_f32_16x16x32_bf16 v[88:91], v[152:155], v[192:195], v[88:91]
	v_mfma_f32_16x16x32_bf16 v[76:79], v[144:147], v[200:203], v[76:79]
	v_mfma_f32_16x16x32_bf16 v[72:75], v[152:155], v[200:203], v[72:75]
	v_mfma_f32_16x16x32_bf16 v[124:127], v[148:151], v[180:183], v[124:127]
	v_mfma_f32_16x16x32_bf16 v[120:123], v[156:159], v[180:183], v[120:123]
	v_mfma_f32_16x16x32_bf16 v[108:111], v[148:151], v[188:191], v[108:111]
	v_mfma_f32_16x16x32_bf16 v[104:107], v[156:159], v[188:191], v[104:107]
	v_mfma_f32_16x16x32_bf16 v[92:95], v[148:151], v[196:199], v[92:95]
	v_mfma_f32_16x16x32_bf16 v[88:91], v[156:159], v[196:199], v[88:91]
	v_mfma_f32_16x16x32_bf16 v[76:79], v[148:151], v[204:207], v[76:79]
	v_mfma_f32_16x16x32_bf16 v[72:75], v[156:159], v[204:207], v[72:75]
	v_mfma_f32_16x16x32_bf16 v[116:119], v[160:163], v[176:179], v[116:119]
	v_mfma_f32_16x16x32_bf16 v[112:115], v[168:171], v[176:179], v[112:115]
	v_mfma_f32_16x16x32_bf16 v[100:103], v[160:163], v[184:187], v[100:103]
	v_mfma_f32_16x16x32_bf16 v[96:99], v[168:171], v[184:187], v[96:99]
	v_mfma_f32_16x16x32_bf16 v[84:87], v[160:163], v[192:195], v[84:87]
	v_mfma_f32_16x16x32_bf16 v[80:83], v[168:171], v[192:195], v[80:83]
	v_mfma_f32_16x16x32_bf16 v[68:71], v[160:163], v[200:203], v[68:71]
	v_mfma_f32_16x16x32_bf16 v[64:67], v[168:171], v[200:203], v[64:67]
	v_mfma_f32_16x16x32_bf16 v[116:119], v[164:167], v[180:183], v[116:119]
	v_mfma_f32_16x16x32_bf16 v[112:115], v[172:175], v[180:183], v[112:115]
	v_mfma_f32_16x16x32_bf16 v[100:103], v[164:167], v[188:191], v[100:103]
	v_mfma_f32_16x16x32_bf16 v[96:99], v[172:175], v[188:191], v[96:99]
	v_mfma_f32_16x16x32_bf16 v[84:87], v[164:167], v[196:199], v[84:87]
	v_mfma_f32_16x16x32_bf16 v[80:83], v[172:175], v[196:199], v[80:83]
	v_mfma_f32_16x16x32_bf16 v[68:71], v[164:167], v[204:207], v[68:71]
	v_mfma_f32_16x16x32_bf16 v[64:67], v[172:175], v[204:207], v[64:67]
	s_barrier
; #define PG8_STAGE(bufoff, gbase, voff) do { _Pragma("unroll") for (int _i = 0; _i < 2; ++_i) \
;         __builtin_amdgcn_global_load_lds((const unsigned*)((const char*)(gbase) + (voff)[_i]), (PG8_LAS unsigned*)(lds + (bufoff) + ldsw + _i * 8192), 16, 0, 0); } while (0)
; #define PG8_LDA(dst, b, h) do { _Pragma("unroll") for (int m = 0; m < 4; ++m) _Pragma("unroll") for (int k = 0; k < 2; ++k) dst[m][k] = *(const PG8_LAS bf16x8*)(lds + PG8_SA(b, h) + aoff + m * 2048 + k * 1024); } while (0)
; #define PG8_MMA(ai, bj, At, Bt) do { __builtin_amdgcn_s_setprio(1); _Pragma("unroll") for (int m = 0; m < 4; ++m) _Pragma("unroll") for (int n = 0; n < 2; ++n) _Pragma("unroll") for (int k = 0; k < 2; ++k) \
;         acc[ai][bj][m][n] = __builtin_amdgcn_mfma_f32_16x16x32_bf16(Bt[n][k], At[m][k], acc[ai][bj][m][n], 0, 0, 0); __builtin_amdgcn_s_setprio(0); } while (0)
; #define PG8_WAIT_V(n) asm volatile("s_waitcnt vmcnt(" #n ")" ::: "memory")
; #define PG8_WAIT_L(n) asm volatile("s_waitcnt lgkmcnt(" #n ")" ::: "memory")
; #define PG8_BAR __builtin_amdgcn_s_barrier()
; #define PG8_SCHED __builtin_amdgcn_sched_barrier(0)
; template <class Epi, class Sched, bool ALIGN_EPI = false, bool SP2 = false>
; __device__ __forceinline__ void gemm_phase(PG8_LAS unsigned char* lds, const Gemm g, const Sched& S, const Epi& E) {
;     ...
;             PG8_LDA(At, 1, 1); PG8_STAGE(PG8_SB(1, 0), b3, voffB); PG8_STAGE(PG8_SB(1, 1), b3 + hstepB, voffB); PG8_STAGE(PG8_SA(1, 0), a3, voffA);
;             PG8_WAIT_V(8); PG8_WAIT_L(0); PG8_BAR; PG8_MMA(1, 0, At, B0); PG8_MMA(1, 1, At, B1); PG8_BAR; PG8_SCHED;
;     ...
;         }
;         if constexpr (ALIGN_EPI) { if (wr == 0) PG8_BAR; }
	s_add_i32 s24, s28, s18
	v_lshl_add_u64 v[138:139], v[138:139], 0, s[10:11]
	s_mov_b32 m0, s24
	ds_read_b128 v[176:179], v143 offset:49152
	ds_read_b128 v[180:183], v143 offset:50176
	ds_read_b128 v[184:187], v143 offset:51200
	ds_read_b128 v[188:191], v143 offset:52224
	ds_read_b128 v[192:195], v143 offset:53248
	ds_read_b128 v[196:199], v143 offset:54272
	ds_read_b128 v[200:203], v143 offset:55296
	ds_read_b128 v[204:207], v143 offset:56320
	global_load_lds_dwordx4 v[138:139], off
	s_add_i32 m0, s24, 0x2000
	s_add_u32 s22, s22, 0x40080
	v_lshl_add_u64 v[138:139], v[210:211], 0, s[10:11]
	s_addc_u32 s23, s23, 0
	s_add_i32 s24, s29, s18
	global_load_lds_dwordx4 v[138:139], off
	v_lshl_add_u64 v[138:139], s[22:23], 0, v[208:209]
	s_mov_b32 m0, s24
	s_nop 0
	global_load_lds_dwordx4 v[138:139], off
	v_lshl_add_u64 v[138:139], s[22:23], 0, v[128:129]
	s_add_i32 m0, s24, 0x2000
	s_nop 0
	global_load_lds_dwordx4 v[138:139], off
	v_lshl_add_u64 v[138:139], v[212:213], 0, s[10:11]
	s_mov_b32 m0, s39
	s_nop 0
	global_load_lds_dwordx4 v[138:139], off
	v_lshl_add_u64 v[138:139], v[222:223], 0, s[10:11]
	s_mov_b32 m0, s48
	s_nop 0
	global_load_lds_dwordx4 v[138:139], off
	s_waitcnt vmcnt(8)
	s_waitcnt lgkmcnt(0)
	s_barrier
	s_waitcnt lgkmcnt(0)
	v_mfma_f32_16x16x32_bf16 v[60:63], v[144:147], v[176:179], v[60:63]
	v_mfma_f32_16x16x32_bf16 v[56:59], v[152:155], v[176:179], v[56:59]
	v_mfma_f32_16x16x32_bf16 v[44:47], v[144:147], v[184:187], v[44:47]
	v_mfma_f32_16x16x32_bf16 v[40:43], v[152:155], v[184:187], v[40:43]
	v_mfma_f32_16x16x32_bf16 v[28:31], v[144:147], v[192:195], v[28:31]
	v_mfma_f32_16x16x32_bf16 v[24:27], v[152:155], v[192:195], v[24:27]
	v_mfma_f32_16x16x32_bf16 v[12:15], v[144:147], v[200:203], v[12:15]
	v_mfma_f32_16x16x32_bf16 v[8:11], v[152:155], v[200:203], v[8:11]
	v_mfma_f32_16x16x32_bf16 v[60:63], v[148:151], v[180:183], v[60:63]
	v_mfma_f32_16x16x32_bf16 v[56:59], v[156:159], v[180:183], v[56:59]
	v_mfma_f32_16x16x32_bf16 v[44:47], v[148:151], v[188:191], v[44:47]
	v_mfma_f32_16x16x32_bf16 v[40:43], v[156:159], v[188:191], v[40:43]
	v_mfma_f32_16x16x32_bf16 v[28:31], v[148:151], v[196:199], v[28:31]
	v_mfma_f32_16x16x32_bf16 v[24:27], v[156:159], v[196:199], v[24:27]
	v_mfma_f32_16x16x32_bf16 v[12:15], v[148:151], v[204:207], v[12:15]
	v_mfma_f32_16x16x32_bf16 v[8:11], v[156:159], v[204:207], v[8:11]
	v_mfma_f32_16x16x32_bf16 v[52:55], v[160:163], v[176:179], v[52:55]
	v_mfma_f32_16x16x32_bf16 v[48:51], v[168:171], v[176:179], v[48:51]
	v_mfma_f32_16x16x32_bf16 v[36:39], v[160:163], v[184:187], v[36:39]
	v_mfma_f32_16x16x32_bf16 v[32:35], v[168:171], v[184:187], v[32:35]
	v_mfma_f32_16x16x32_bf16 v[20:23], v[160:163], v[192:195], v[20:23]
	v_mfma_f32_16x16x32_bf16 v[16:19], v[168:171], v[192:195], v[16:19]
	v_mfma_f32_16x16x32_bf16 v[4:7], v[160:163], v[200:203], v[4:7]
	v_mfma_f32_16x16x32_bf16 v[0:3], v[168:171], v[200:203], v[0:3]
	v_mfma_f32_16x16x32_bf16 v[52:55], v[164:167], v[180:183], v[52:55]
	v_mfma_f32_16x16x32_bf16 v[48:51], v[172:175], v[180:183], v[48:51]
	v_mfma_f32_16x16x32_bf16 v[36:39], v[164:167], v[188:191], v[36:39]
	v_mfma_f32_16x16x32_bf16 v[32:35], v[172:175], v[188:191], v[32:35]
	v_mfma_f32_16x16x32_bf16 v[20:23], v[164:167], v[196:199], v[20:23]
	v_mfma_f32_16x16x32_bf16 v[16:19], v[172:175], v[196:199], v[16:19]
	v_mfma_f32_16x16x32_bf16 v[4:7], v[164:167], v[204:207], v[4:7]
	v_mfma_f32_16x16x32_bf16 v[0:3], v[172:175], v[204:207], v[0:3]
	s_barrier
	s_add_i32 s51, s51, 2
	s_add_u32 s0, s0, 0x100
	s_addc_u32 s1, s1, 0
	s_add_u32 s43, s43, 0x100
	s_addc_u32 s50, s50, 0
	s_cmp_gt_u32 s51, 13
	s_cbranch_scc0 .LBB0_920
	s_and_b64 vcc, exec, s[6:7]
	s_cbranch_vccz .LBB0_923
	s_barrier

; #define PG8_STAGE(bufoff, gbase, voff) do { _Pragma("unroll") for (int _i = 0; _i < 2; ++_i) \
;         __builtin_amdgcn_global_load_lds((const unsigned*)((const char*)(gbase) + (voff)[_i]), (PG8_LAS unsigned*)(lds + (bufoff) + ldsw + _i * 8192), 16, 0, 0); } while (0)
; #define PG8_LDA(dst, b, h) do { _Pragma("unroll") for (int m = 0; m < 4; ++m) _Pragma("unroll") for (int k = 0; k < 2; ++k) dst[m][k] = *(const PG8_LAS bf16x8*)(lds + PG8_SA(b, h) + aoff + m * 2048 + k * 1024); } while (0)
; #define PG8_LDB(dst, b, h) do { _Pragma("unroll") for (int n = 0; n < 2; ++n) _Pragma("unroll") for (int k = 0; k < 2; ++k) dst[n][k] = *(const PG8_LAS bf16x8*)(lds + PG8_SB(b, h) + boff + n * 2048 + k * 1024); } while (0)
; #define PG8_MMA(ai, bj, At, Bt) do { __builtin_amdgcn_s_setprio(1); _Pragma("unroll") for (int m = 0; m < 4; ++m) _Pragma("unroll") for (int n = 0; n < 2; ++n) _Pragma("unroll") for (int k = 0; k < 2; ++k) \
;         acc[ai][bj][m][n] = __builtin_amdgcn_mfma_f32_16x16x32_bf16(Bt[n][k], At[m][k], acc[ai][bj][m][n], 0, 0, 0); __builtin_amdgcn_s_setprio(0); } while (0)
; #define PG8_WAIT_V(n) asm volatile("s_waitcnt vmcnt(" #n ")" ::: "memory")
; #define PG8_WAIT_L(n) asm volatile("s_waitcnt lgkmcnt(" #n ")" ::: "memory")
; #define PG8_BAR __builtin_amdgcn_s_barrier()
; #define PG8_SCHED __builtin_amdgcn_sched_barrier(0)
; template <class Epi, class Sched, bool ALIGN_EPI = false, bool SP2 = false>
; __device__ __forceinline__ void gemm_phase(PG8_LAS unsigned char* lds, const Gemm g, const Sched& S, const Epi& E) {
;     ...
;             const bool last = (t == nt - 2);
;             const char* a1 = cA + (size_t)(t + 1) * kstep;
;             const char* a2 = last ? nA : cA + (size_t)(t + 2) * kstep; const char* b2 = last ? nB : cB + (size_t)(t + 2) * kstep;
;             const char* a3 = a2 + kstep; const char* b3 = b2 + kstep;
;             if (last && has_next) S.a_ready(nxt);
;             if constexpr (SP2) {
;             PG8_LDB(B0, 0, 0); PG8_LDB(B1, 0, 1); PG8_SCHED; PG8_LDA(At, 0, 0); PG8_STAGE(PG8_SA(1, 1), a1 + hstepA, voffA);
;             PG8_WAIT_V(8); PG8_WAIT_L(0); PG8_BAR; PG8_MMA(0, 0, At, B0); PG8_MMA(0, 1, At, B1); PG8_BAR; PG8_SCHED;
;             PG8_LDA(At, 0, 1); PG8_STAGE(PG8_SB(0, 0), b2, voffB); PG8_STAGE(PG8_SB(0, 1), b2 + hstepB, voffB); PG8_STAGE(PG8_SA(0, 0), a2, voffA);
.LBB0_1000:
	s_add_u32 s20, s0, 0x100
	s_addc_u32 s21, s1, 0
	s_add_i32 s28, 0, 0x10000
	s_cmp_eq_u32 s49, 40
	s_cselect_b32 s25, s5, s21
	s_cselect_b32 s24, s4, s20
	v_add_u32_e32 v138, s28, v141
	s_cselect_b32 s23, s43, s15
	s_cselect_b32 s22, s42, s14
	s_add_i32 s29, 0, 0x14000
	ds_read_b128 v[134:137], v138
	ds_read_b128 v[144:147], v138 offset:1024
	ds_read_b128 v[148:151], v138 offset:2048
	ds_read_b128 v[152:155], v138 offset:3072
	v_add_u32_e32 v138, s29, v141
	ds_read_b128 v[156:159], v138
	ds_read_b128 v[160:163], v138 offset:1024
	ds_read_b128 v[164:167], v138 offset:2048
	ds_read_b128 v[168:171], v138 offset:3072
	v_lshl_add_u64 v[138:139], s[0:1], 0, v[130:131]
	s_add_i32 m0, s26, 0xc000
	ds_read_b128 v[172:175], v143
	ds_read_b128 v[176:179], v143 offset:1024
	ds_read_b128 v[180:183], v143 offset:2048
	ds_read_b128 v[184:187], v143 offset:3072
	ds_read_b128 v[188:191], v143 offset:4096
	ds_read_b128 v[192:195], v143 offset:5120
	ds_read_b128 v[196:199], v143 offset:6144
	ds_read_b128 v[200:203], v143 offset:7168
	global_load_lds_dwordx4 v[138:139], off
	v_lshl_add_u64 v[138:139], s[0:1], 0, v[132:133]
	s_add_i32 m0, s26, 0xe000
	s_nop 0
	global_load_lds_dwordx4 v[138:139], off
	s_waitcnt vmcnt(8)
	s_waitcnt lgkmcnt(0)
	s_barrier
	s_waitcnt lgkmcnt(0)
	v_mfma_f32_16x16x32_bf16 v[124:127], v[134:137], v[172:175], v[124:127]
	v_mfma_f32_16x16x32_bf16 v[120:123], v[148:151], v[172:175], v[120:123]
	v_mfma_f32_16x16x32_bf16 v[116:119], v[134:137], v[180:183], v[116:119]
	v_mfma_f32_16x16x32_bf16 v[112:115], v[148:151], v[180:183], v[112:115]
	v_mfma_f32_16x16x32_bf16 v[108:111], v[134:137], v[188:191], v[108:111]
	v_mfma_f32_16x16x32_bf16 v[100:103], v[148:151], v[188:191], v[100:103]
	v_mfma_f32_16x16x32_bf16 v[92:95], v[134:137], v[196:199], v[92:95]
	v_mfma_f32_16x16x32_bf16 v[80:83], v[148:151], v[196:199], v[80:83]
	v_mfma_f32_16x16x32_bf16 v[124:127], v[144:147], v[176:179], v[124:127]
	v_mfma_f32_16x16x32_bf16 v[120:123], v[152:155], v[176:179], v[120:123]
	v_mfma_f32_16x16x32_bf16 v[116:119], v[144:147], v[184:187], v[116:119]
	v_mfma_f32_16x16x32_bf16 v[112:115], v[152:155], v[184:187], v[112:115]
	v_mfma_f32_16x16x32_bf16 v[108:111], v[144:147], v[192:195], v[108:111]
	v_mfma_f32_16x16x32_bf16 v[100:103], v[152:155], v[192:195], v[100:103]
	v_mfma_f32_16x16x32_bf16 v[92:95], v[144:147], v[200:203], v[92:95]
	v_mfma_f32_16x16x32_bf16 v[80:83], v[152:155], v[200:203], v[80:83]
	v_mfma_f32_16x16x32_bf16 v[104:107], v[156:159], v[172:175], v[104:107]
	v_mfma_f32_16x16x32_bf16 v[96:99], v[164:167], v[172:175], v[96:99]
	v_mfma_f32_16x16x32_bf16 v[88:91], v[156:159], v[180:183], v[88:91]
	v_mfma_f32_16x16x32_bf16 v[84:87], v[164:167], v[180:183], v[84:87]
	v_mfma_f32_16x16x32_bf16 v[76:79], v[156:159], v[188:191], v[76:79]
	v_mfma_f32_16x16x32_bf16 v[72:75], v[164:167], v[188:191], v[72:75]
	v_mfma_f32_16x16x32_bf16 v[68:71], v[156:159], v[196:199], v[68:71]
	v_mfma_f32_16x16x32_bf16 v[64:67], v[164:167], v[196:199], v[64:67]
	v_mfma_f32_16x16x32_bf16 v[104:107], v[160:163], v[176:179], v[104:107]
	v_mfma_f32_16x16x32_bf16 v[96:99], v[168:171], v[176:179], v[96:99]
	v_mfma_f32_16x16x32_bf16 v[88:91], v[160:163], v[184:187], v[88:91]
	v_mfma_f32_16x16x32_bf16 v[84:87], v[168:171], v[184:187], v[84:87]
	v_mfma_f32_16x16x32_bf16 v[76:79], v[160:163], v[192:195], v[76:79]
	v_mfma_f32_16x16x32_bf16 v[72:75], v[168:171], v[192:195], v[72:75]
	v_mfma_f32_16x16x32_bf16 v[68:71], v[160:163], v[200:203], v[68:71]
	v_mfma_f32_16x16x32_bf16 v[64:67], v[168:171], v[200:203], v[64:67]
	s_barrier
	s_add_i32 s0, s28, s19
	v_lshl_add_u64 v[138:139], s[22:23], 0, v[208:209]
	s_mov_b32 m0, s0
	ds_read_b128 v[172:175], v143 offset:16384
	ds_read_b128 v[176:179], v143 offset:17408
	ds_read_b128 v[180:183], v143 offset:18432
	ds_read_b128 v[184:187], v143 offset:19456
	ds_read_b128 v[188:191], v143 offset:20480
	ds_read_b128 v[192:195], v143 offset:21504
	ds_read_b128 v[196:199], v143 offset:22528
	ds_read_b128 v[200:203], v143 offset:23552
	global_load_lds_dwordx4 v[138:139], off
	s_add_i32 m0, s0, 0x2000
	s_add_u32 s0, s22, 0xb0000
	v_lshl_add_u64 v[204:205], s[22:23], 0, v[128:129]
	s_addc_u32 s1, s23, 0
	s_add_i32 s28, s29, s19
	global_load_lds_dwordx4 v[204:205], off
	v_lshl_add_u64 v[206:207], s[0:1], 0, v[208:209]
	s_mov_b32 m0, s28
	v_lshl_add_u64 v[210:211], s[24:25], 0, v[128:129]
	global_load_lds_dwordx4 v[206:207], off
	v_lshl_add_u64 v[206:207], s[0:1], 0, v[128:129]
	s_add_i32 m0, s28, 0x2000
	s_nop 0
	global_load_lds_dwordx4 v[206:207], off
	v_lshl_add_u64 v[206:207], s[24:25], 0, v[208:209]
	s_mov_b32 m0, s26
	s_nop 0
	global_load_lds_dwordx4 v[206:207], off
	s_mov_b32 m0, s34
	s_nop 0
	global_load_lds_dwordx4 v[210:211], off
	s_waitcnt vmcnt(8)
	s_waitcnt lgkmcnt(0)
	s_barrier
; #define PG8_STAGE(bufoff, gbase, voff) do { _Pragma("unroll") for (int _i = 0; _i < 2; ++_i) \
;         __builtin_amdgcn_global_load_lds((const unsigned*)((const char*)(gbase) + (voff)[_i]), (PG8_LAS unsigned*)(lds + (bufoff) + ldsw + _i * 8192), 16, 0, 0); } while (0)
; #define PG8_LDA(dst, b, h) do { _Pragma("unroll") for (int m = 0; m < 4; ++m) _Pragma("unroll") for (int k = 0; k < 2; ++k) dst[m][k] = *(const PG8_LAS bf16x8*)(lds + PG8_SA(b, h) + aoff + m * 2048 + k * 1024); } while (0)
; #define PG8_LDB(dst, b, h) do { _Pragma("unroll") for (int n = 0; n < 2; ++n) _Pragma("unroll") for (int k = 0; k < 2; ++k) dst[n][k] = *(const PG8_LAS bf16x8*)(lds + PG8_SB(b, h) + boff + n * 2048 + k * 1024); } while (0)
; #define PG8_MMA(ai, bj, At, Bt) do { __builtin_amdgcn_s_setprio(1); _Pragma("unroll") for (int m = 0; m < 4; ++m) _Pragma("unroll") for (int n = 0; n < 2; ++n) _Pragma("unroll") for (int k = 0; k < 2; ++k) \
;         acc[ai][bj][m][n] = __builtin_amdgcn_mfma_f32_16x16x32_bf16(Bt[n][k], At[m][k], acc[ai][bj][m][n], 0, 0, 0); __builtin_amdgcn_s_setprio(0); } while (0)
; #define PG8_WAIT_V(n) asm volatile("s_waitcnt vmcnt(" #n ")" ::: "memory")
; #define PG8_WAIT_L(n) asm volatile("s_waitcnt lgkmcnt(" #n ")" ::: "memory")
; #define PG8_BAR __builtin_amdgcn_s_barrier()
; #define PG8_SCHED __builtin_amdgcn_sched_barrier(0)
; template <class Epi, class Sched, bool ALIGN_EPI = false, bool SP2 = false>
; __device__ __forceinline__ void gemm_phase(PG8_LAS unsigned char* lds, const Gemm g, const Sched& S, const Epi& E) {
;     ...
;             PG8_WAIT_V(8); PG8_WAIT_L(0); PG8_BAR; PG8_MMA(1, 0, At, B0); PG8_MMA(1, 1, At, B1); PG8_BAR; PG8_SCHED;
;             PG8_LDB(B0, 1, 0); PG8_LDB(B1, 1, 1); PG8_SCHED; PG8_LDA(At, 1, 0); PG8_STAGE(PG8_SA(0, 1), a2 + hstepA, voffA);
;             PG8_WAIT_V(8); PG8_WAIT_L(0); PG8_BAR; PG8_MMA(0, 0, At, B0); PG8_MMA(0, 1, At, B1); PG8_BAR; PG8_SCHED;
	s_waitcnt lgkmcnt(0)
	v_mfma_f32_16x16x32_bf16 v[60:63], v[134:137], v[172:175], v[60:63]
	v_mfma_f32_16x16x32_bf16 v[56:59], v[148:151], v[172:175], v[56:59]
	v_mfma_f32_16x16x32_bf16 v[52:55], v[134:137], v[180:183], v[52:55]
	v_mfma_f32_16x16x32_bf16 v[48:51], v[148:151], v[180:183], v[48:51]
	v_mfma_f32_16x16x32_bf16 v[44:47], v[134:137], v[188:191], v[44:47]
	v_mfma_f32_16x16x32_bf16 v[32:35], v[148:151], v[188:191], v[32:35]
	v_mfma_f32_16x16x32_bf16 v[16:19], v[134:137], v[196:199], v[16:19]
	v_mfma_f32_16x16x32_bf16 v[8:11], v[148:151], v[196:199], v[8:11]
	v_mfma_f32_16x16x32_bf16 v[60:63], v[144:147], v[176:179], v[60:63]
	v_mfma_f32_16x16x32_bf16 v[56:59], v[152:155], v[176:179], v[56:59]
	v_mfma_f32_16x16x32_bf16 v[52:55], v[144:147], v[184:187], v[52:55]
	v_mfma_f32_16x16x32_bf16 v[48:51], v[152:155], v[184:187], v[48:51]
	v_mfma_f32_16x16x32_bf16 v[44:47], v[144:147], v[192:195], v[44:47]
	v_mfma_f32_16x16x32_bf16 v[32:35], v[152:155], v[192:195], v[32:35]
	v_mfma_f32_16x16x32_bf16 v[16:19], v[144:147], v[200:203], v[16:19]
	v_mfma_f32_16x16x32_bf16 v[8:11], v[152:155], v[200:203], v[8:11]
	v_mfma_f32_16x16x32_bf16 v[40:43], v[156:159], v[172:175], v[40:43]
	v_mfma_f32_16x16x32_bf16 v[36:39], v[164:167], v[172:175], v[36:39]
	v_mfma_f32_16x16x32_bf16 v[28:31], v[156:159], v[180:183], v[28:31]
	v_mfma_f32_16x16x32_bf16 v[24:27], v[164:167], v[180:183], v[24:27]
	v_mfma_f32_16x16x32_bf16 v[20:23], v[156:159], v[188:191], v[20:23]
	v_mfma_f32_16x16x32_bf16 v[12:15], v[164:167], v[188:191], v[12:15]
	v_mfma_f32_16x16x32_bf16 v[4:7], v[156:159], v[196:199], v[4:7]
	v_mfma_f32_16x16x32_bf16 v[0:3], v[164:167], v[196:199], v[0:3]
	v_mfma_f32_16x16x32_bf16 v[40:43], v[160:163], v[176:179], v[40:43]
	v_mfma_f32_16x16x32_bf16 v[36:39], v[168:171], v[176:179], v[36:39]
	v_mfma_f32_16x16x32_bf16 v[28:31], v[160:163], v[184:187], v[28:31]
	v_mfma_f32_16x16x32_bf16 v[24:27], v[168:171], v[184:187], v[24:27]
	v_mfma_f32_16x16x32_bf16 v[20:23], v[160:163], v[192:195], v[20:23]
	v_mfma_f32_16x16x32_bf16 v[12:15], v[168:171], v[192:195], v[12:15]
	v_mfma_f32_16x16x32_bf16 v[4:7], v[160:163], v[200:203], v[4:7]
	v_mfma_f32_16x16x32_bf16 v[0:3], v[168:171], v[200:203], v[0:3]
	s_barrier
	s_add_i32 s28, 0, 0x18000
	s_add_i32 s29, 0, 0x1c000
	v_add_u32_e32 v152, s28, v141
	v_add_u32_e32 v168, s29, v141
	ds_read_b128 v[134:137], v152
	ds_read_b128 v[144:147], v152 offset:1024
	ds_read_b128 v[148:151], v152 offset:2048
	ds_read_b128 v[152:155], v152 offset:3072
	ds_read_b128 v[156:159], v168
	ds_read_b128 v[160:163], v168 offset:1024
	ds_read_b128 v[164:167], v168 offset:2048
	ds_read_b128 v[168:171], v168 offset:3072
	s_add_u32 s0, s24, 0xb0000
	s_addc_u32 s1, s25, 0
	s_mov_b32 m0, s35
	v_lshl_add_u64 v[212:213], s[0:1], 0, v[208:209]
	ds_read_b128 v[172:175], v143 offset:32768
	ds_read_b128 v[176:179], v143 offset:33792
	ds_read_b128 v[180:183], v143 offset:34816
	ds_read_b128 v[184:187], v143 offset:35840
	ds_read_b128 v[188:191], v143 offset:36864
	ds_read_b128 v[192:195], v143 offset:37888
	ds_read_b128 v[196:199], v143 offset:38912
	ds_read_b128 v[200:203], v143 offset:39936
	global_load_lds_dwordx4 v[212:213], off
	v_lshl_add_u64 v[212:213], s[0:1], 0, v[128:129]
	s_mov_b32 m0, s39
	s_nop 0
	global_load_lds_dwordx4 v[212:213], off
	s_waitcnt vmcnt(8)
	s_waitcnt lgkmcnt(0)
	s_barrier
	s_waitcnt lgkmcnt(0)
	v_mfma_f32_16x16x32_bf16 v[124:127], v[134:137], v[172:175], v[124:127]
	v_mfma_f32_16x16x32_bf16 v[120:123], v[148:151], v[172:175], v[120:123]
	v_mfma_f32_16x16x32_bf16 v[116:119], v[134:137], v[180:183], v[116:119]
	v_mfma_f32_16x16x32_bf16 v[112:115], v[148:151], v[180:183], v[112:115]
	v_mfma_f32_16x16x32_bf16 v[108:111], v[134:137], v[188:191], v[108:111]
	v_mfma_f32_16x16x32_bf16 v[100:103], v[148:151], v[188:191], v[100:103]
	v_mfma_f32_16x16x32_bf16 v[92:95], v[134:137], v[196:199], v[92:95]
	v_mfma_f32_16x16x32_bf16 v[80:83], v[148:151], v[196:199], v[80:83]
	v_mfma_f32_16x16x32_bf16 v[124:127], v[144:147], v[176:179], v[124:127]
	v_mfma_f32_16x16x32_bf16 v[120:123], v[152:155], v[176:179], v[120:123]
	v_mfma_f32_16x16x32_bf16 v[116:119], v[144:147], v[184:187], v[116:119]
	v_mfma_f32_16x16x32_bf16 v[112:115], v[152:155], v[184:187], v[112:115]
	v_mfma_f32_16x16x32_bf16 v[108:111], v[144:147], v[192:195], v[108:111]
	v_mfma_f32_16x16x32_bf16 v[100:103], v[152:155], v[192:195], v[100:103]
	v_mfma_f32_16x16x32_bf16 v[92:95], v[144:147], v[200:203], v[92:95]
	v_mfma_f32_16x16x32_bf16 v[80:83], v[152:155], v[200:203], v[80:83]
	v_mfma_f32_16x16x32_bf16 v[104:107], v[156:159], v[172:175], v[104:107]
	v_mfma_f32_16x16x32_bf16 v[96:99], v[164:167], v[172:175], v[96:99]
	v_mfma_f32_16x16x32_bf16 v[88:91], v[156:159], v[180:183], v[88:91]
	v_mfma_f32_16x16x32_bf16 v[84:87], v[164:167], v[180:183], v[84:87]
	v_mfma_f32_16x16x32_bf16 v[76:79], v[156:159], v[188:191], v[76:79]
	v_mfma_f32_16x16x32_bf16 v[72:75], v[164:167], v[188:191], v[72:75]
	v_mfma_f32_16x16x32_bf16 v[68:71], v[156:159], v[196:199], v[68:71]
	v_mfma_f32_16x16x32_bf16 v[64:67], v[164:167], v[196:199], v[64:67]
	v_mfma_f32_16x16x32_bf16 v[104:107], v[160:163], v[176:179], v[104:107]
	v_mfma_f32_16x16x32_bf16 v[96:99], v[168:171], v[176:179], v[96:99]
	v_mfma_f32_16x16x32_bf16 v[88:91], v[160:163], v[184:187], v[88:91]
	v_mfma_f32_16x16x32_bf16 v[84:87], v[168:171], v[184:187], v[84:87]
	v_mfma_f32_16x16x32_bf16 v[76:79], v[160:163], v[192:195], v[76:79]
	v_mfma_f32_16x16x32_bf16 v[72:75], v[168:171], v[192:195], v[72:75]
	v_mfma_f32_16x16x32_bf16 v[68:71], v[160:163], v[200:203], v[68:71]
	v_mfma_f32_16x16x32_bf16 v[64:67], v[168:171], v[200:203], v[64:67]
	s_barrier
; #define PG8_STAGE(bufoff, gbase, voff) do { _Pragma("unroll") for (int _i = 0; _i < 2; ++_i) \
;         __builtin_amdgcn_global_load_lds((const unsigned*)((const char*)(gbase) + (voff)[_i]), (PG8_LAS unsigned*)(lds + (bufoff) + ldsw + _i * 8192), 16, 0, 0); } while (0)
; #define PG8_LDA(dst, b, h) do { _Pragma("unroll") for (int m = 0; m < 4; ++m) _Pragma("unroll") for (int k = 0; k < 2; ++k) dst[m][k] = *(const PG8_LAS bf16x8*)(lds + PG8_SA(b, h) + aoff + m * 2048 + k * 1024); } while (0)
; #define PG8_MMA(ai, bj, At, Bt) do { __builtin_amdgcn_s_setprio(1); _Pragma("unroll") for (int m = 0; m < 4; ++m) _Pragma("unroll") for (int n = 0; n < 2; ++n) _Pragma("unroll") for (int k = 0; k < 2; ++k) \
;         acc[ai][bj][m][n] = __builtin_amdgcn_mfma_f32_16x16x32_bf16(Bt[n][k], At[m][k], acc[ai][bj][m][n], 0, 0, 0); __builtin_amdgcn_s_setprio(0); } while (0)
; #define PG8_WAIT_V(n) asm volatile("s_waitcnt vmcnt(" #n ")" ::: "memory")
; #define PG8_WAIT_L(n) asm volatile("s_waitcnt lgkmcnt(" #n ")" ::: "memory")
; #define PG8_BAR __builtin_amdgcn_s_barrier()
; #define PG8_SCHED __builtin_amdgcn_sched_barrier(0)
; template <class Epi, class Sched, bool ALIGN_EPI = false, bool SP2 = false>
; __device__ __forceinline__ void gemm_phase(PG8_LAS unsigned char* lds, const Gemm g, const Sched& S, const Epi& E) {
;     ...
;             PG8_LDA(At, 1, 1); PG8_STAGE(PG8_SB(1, 0), b3, voffB); PG8_STAGE(PG8_SB(1, 1), b3 + hstepB, voffB); PG8_STAGE(PG8_SA(1, 0), a3, voffA);
;             PG8_WAIT_V(8); PG8_WAIT_L(0); PG8_BAR; PG8_MMA(1, 0, At, B0); PG8_MMA(1, 1, At, B1); PG8_BAR; PG8_SCHED;
;     ...
;         }
;         if constexpr (ALIGN_EPI) { if (wr == 0) PG8_BAR; }
	s_add_i32 s0, s28, s19
	v_lshl_add_u64 v[138:139], v[138:139], 0, s[10:11]
	s_mov_b32 m0, s0
	ds_read_b128 v[172:175], v143 offset:49152
	ds_read_b128 v[176:179], v143 offset:50176
	ds_read_b128 v[180:183], v143 offset:51200
	ds_read_b128 v[184:187], v143 offset:52224
	ds_read_b128 v[188:191], v143 offset:53248
	ds_read_b128 v[192:195], v143 offset:54272
	ds_read_b128 v[196:199], v143 offset:55296
	ds_read_b128 v[200:203], v143 offset:56320
	global_load_lds_dwordx4 v[138:139], off
	s_add_i32 m0, s0, 0x2000
	s_add_u32 s0, s22, 0xb0080
	v_lshl_add_u64 v[138:139], v[204:205], 0, s[10:11]
	s_addc_u32 s1, s23, 0
	s_add_i32 s22, s29, s19
	global_load_lds_dwordx4 v[138:139], off
	v_lshl_add_u64 v[138:139], s[0:1], 0, v[208:209]
	s_mov_b32 m0, s22
	s_nop 0
	global_load_lds_dwordx4 v[138:139], off
	v_lshl_add_u64 v[138:139], s[0:1], 0, v[128:129]
	s_add_i32 m0, s22, 0x2000
	s_nop 0
	global_load_lds_dwordx4 v[138:139], off
	v_lshl_add_u64 v[138:139], v[206:207], 0, s[10:11]
	s_mov_b32 m0, s44
	s_nop 0
	global_load_lds_dwordx4 v[138:139], off
	v_lshl_add_u64 v[138:139], v[210:211], 0, s[10:11]
	s_mov_b32 m0, s45
	s_nop 0
	global_load_lds_dwordx4 v[138:139], off
	s_waitcnt vmcnt(8)
	s_waitcnt lgkmcnt(0)
	s_barrier
	s_waitcnt lgkmcnt(0)
	v_mfma_f32_16x16x32_bf16 v[60:63], v[134:137], v[172:175], v[60:63]
	v_mfma_f32_16x16x32_bf16 v[56:59], v[148:151], v[172:175], v[56:59]
	v_mfma_f32_16x16x32_bf16 v[52:55], v[134:137], v[180:183], v[52:55]
	v_mfma_f32_16x16x32_bf16 v[48:51], v[148:151], v[180:183], v[48:51]
	v_mfma_f32_16x16x32_bf16 v[44:47], v[134:137], v[188:191], v[44:47]
	v_mfma_f32_16x16x32_bf16 v[32:35], v[148:151], v[188:191], v[32:35]
	v_mfma_f32_16x16x32_bf16 v[16:19], v[134:137], v[196:199], v[16:19]
	v_mfma_f32_16x16x32_bf16 v[8:11], v[148:151], v[196:199], v[8:11]
	v_mfma_f32_16x16x32_bf16 v[60:63], v[144:147], v[176:179], v[60:63]
	v_mfma_f32_16x16x32_bf16 v[56:59], v[152:155], v[176:179], v[56:59]
	v_mfma_f32_16x16x32_bf16 v[52:55], v[144:147], v[184:187], v[52:55]
	v_mfma_f32_16x16x32_bf16 v[48:51], v[152:155], v[184:187], v[48:51]
	v_mfma_f32_16x16x32_bf16 v[44:47], v[144:147], v[192:195], v[44:47]
	v_mfma_f32_16x16x32_bf16 v[32:35], v[152:155], v[192:195], v[32:35]
	v_mfma_f32_16x16x32_bf16 v[16:19], v[144:147], v[200:203], v[16:19]
	v_mfma_f32_16x16x32_bf16 v[8:11], v[152:155], v[200:203], v[8:11]
	v_mfma_f32_16x16x32_bf16 v[40:43], v[156:159], v[172:175], v[40:43]
	v_mfma_f32_16x16x32_bf16 v[36:39], v[164:167], v[172:175], v[36:39]
	v_mfma_f32_16x16x32_bf16 v[28:31], v[156:159], v[180:183], v[28:31]
	v_mfma_f32_16x16x32_bf16 v[24:27], v[164:167], v[180:183], v[24:27]
	v_mfma_f32_16x16x32_bf16 v[20:23], v[156:159], v[188:191], v[20:23]
	v_mfma_f32_16x16x32_bf16 v[12:15], v[164:167], v[188:191], v[12:15]
	v_mfma_f32_16x16x32_bf16 v[4:7], v[156:159], v[196:199], v[4:7]
	v_mfma_f32_16x16x32_bf16 v[0:3], v[164:167], v[196:199], v[0:3]
	v_mfma_f32_16x16x32_bf16 v[40:43], v[160:163], v[176:179], v[40:43]
	v_mfma_f32_16x16x32_bf16 v[36:39], v[168:171], v[176:179], v[36:39]
	v_mfma_f32_16x16x32_bf16 v[28:31], v[160:163], v[184:187], v[28:31]
	v_mfma_f32_16x16x32_bf16 v[24:27], v[168:171], v[184:187], v[24:27]
	v_mfma_f32_16x16x32_bf16 v[20:23], v[160:163], v[192:195], v[20:23]
	v_mfma_f32_16x16x32_bf16 v[12:15], v[168:171], v[192:195], v[12:15]
	v_mfma_f32_16x16x32_bf16 v[4:7], v[160:163], v[200:203], v[4:7]
	v_mfma_f32_16x16x32_bf16 v[0:3], v[168:171], v[200:203], v[0:3]
	s_barrier
	s_add_i32 s49, s49, 2
	s_add_u32 s14, s14, 0x100
	s_addc_u32 s15, s15, 0
	s_cmp_gt_u32 s49, 41
	s_mov_b64 s[0:1], s[20:21]
	s_cbranch_scc0 .LBB0_1000
	s_and_b64 vcc, exec, s[8:9]
	s_cbranch_vccz .LBB0_1003
	s_barrier
